# W_eff weight-fold prep item: all 128 column loads issued up front, LDS+FMA loop pipelined (same fma order)
# speedup vs baseline: 1.1018x; 1.0415x over previous
.Ldn_tile:
	s_and_b32 s0, s78, 3
	s_or_b32 s0, s0, s77
	s_lshr_b32 s1, s78, 2
	s_lshl_b32 s1, s1, 7
	s_lshl_b32 s2, s0, 8
	s_mul_i32 s3, s2, 0x1600
	s_add_u32 s68, s18, s3
	s_addc_u32 s69, s19, 0
	s_mul_i32 s3, s1, 0x1600
	s_add_u32 s70, s80, s3
	s_addc_u32 s71, s81, 0
	s_lshl_b32 s3, s2, 11
	s_lshl_b32 s12, s1, 1
	s_add_u32 s3, s3, s12
	s_add_u32 s74, s24, s3
	s_addc_u32 s75, s25, 0
	s_add_i32 s12, s0, -12
	s_lshr_b32 s12, s12, 2
	s_cmp_lt_u32 s0, 16
	s_cselect_b32 s12, 0, s12
	s_cselect_b32 s14, s52, s54
	s_cselect_b32 s15, s53, s55
	s_mul_i32 s13, s82, 5
	s_add_i32 s12, s12, s13
	s_mul_i32 s12, s12, 0x6000
	s_add_u32 s12, s12, 0x5000
	s_lshl_b32 s13, s1, 2
	s_add_u32 s12, s12, s13
	s_add_u32 s72, s30, s12
	s_addc_u32 s73, s31, 0
	s_and_b32 s12, s0, 15
	s_lshl_b32 s12, s12, 20
	s_add_u32 s12, s12, s13
	s_add_u32 s14, s14, s12
	s_addc_u32 s15, s15, 0
	s_add_u32 m0, s76, 0x0
	s_nop 0
	global_load_lds_dwordx4 v196, s[68:69]
	s_add_u32 m0, s76, 0x2000
	s_nop 0
	global_load_lds_dwordx4 v197, s[68:69]
	s_add_u32 m0, s76, 0x4000
	s_nop 0
	global_load_lds_dwordx4 v198, s[68:69]
	s_add_u32 m0, s76, 0x6000
	s_nop 0
	global_load_lds_dwordx4 v199, s[68:69]
	s_add_u32 m0, s76, 0x8000
	s_nop 0
	global_load_lds_dwordx4 v196, s[70:71]
	s_add_u32 m0, s76, 0xa000
	s_nop 0
	global_load_lds_dwordx4 v197, s[70:71]
	s_add_u32 s68, s68, 0x80
	s_addc_u32 s69, s69, 0
	s_add_u32 s70, s70, 0x80
	s_addc_u32 s71, s71, 0
	s_add_u32 m0, s76, 0xc000
	s_nop 0
	global_load_lds_dwordx4 v196, s[68:69]
	s_add_u32 m0, s76, 0xe000
	s_nop 0
	global_load_lds_dwordx4 v197, s[68:69]
	s_add_u32 m0, s76, 0x10000
	s_nop 0
	global_load_lds_dwordx4 v198, s[68:69]
	s_add_u32 m0, s76, 0x12000
	s_nop 0
	global_load_lds_dwordx4 v199, s[68:69]
	s_add_u32 m0, s76, 0x14000
	s_nop 0
	global_load_lds_dwordx4 v196, s[70:71]
	s_add_u32 m0, s76, 0x16000
	s_nop 0
	global_load_lds_dwordx4 v197, s[70:71]
	s_add_u32 s68, s68, 0x80
	s_addc_u32 s69, s69, 0
	s_add_u32 s70, s70, 0x80
	s_addc_u32 s71, s71, 0
	s_waitcnt vmcnt(6)
	s_waitcnt lgkmcnt(0)
	s_barrier
	v_add_u32_e32 v204, 0x0, v200
	v_add_u32_e32 v205, 0x0, v202
	ds_read_b128 v[130:133], v204 offset:0
	ds_read_b128 v[134:137], v204 offset:2048
	ds_read_b128 v[138:141], v204 offset:4096
	ds_read_b128 v[142:145], v204 offset:6144
	ds_read_b128 v[146:149], v205 offset:0
	ds_read_b128 v[150:153], v205 offset:2048
	ds_read_b128 v[154:157], v205 offset:4096
	ds_read_b128 v[158:161], v205 offset:6144
	s_add_u32 m0, s76, 0x18000
	s_nop 0
	global_load_lds_dwordx4 v196, s[68:69]
	s_add_u32 m0, s76, 0x1a000
	s_nop 0
	global_load_lds_dwordx4 v197, s[68:69]
	s_add_u32 m0, s76, 0x1c000
	s_nop 0
	global_load_lds_dwordx4 v198, s[68:69]
	s_add_u32 m0, s76, 0x1e000
	s_nop 0
	global_load_lds_dwordx4 v199, s[68:69]
	s_add_u32 m0, s76, 0x20000
	s_nop 0
	global_load_lds_dwordx4 v196, s[70:71]
	s_add_u32 m0, s76, 0x22000
	s_nop 0
	global_load_lds_dwordx4 v197, s[70:71]
	s_add_u32 s68, s68, 0x80
	s_addc_u32 s69, s69, 0
	s_add_u32 s70, s70, 0x80
	s_addc_u32 s71, s71, 0
	s_waitcnt lgkmcnt(0)
	v_add_u32_e32 v204, 0x0, v201
	v_add_u32_e32 v205, 0x0, v203
	ds_read_b128 v[212:215], v204 offset:0
	ds_read_b128 v[216:219], v204 offset:2048
	ds_read_b128 v[220:223], v204 offset:4096
	ds_read_b128 v[224:227], v204 offset:6144
	ds_read_b128 v[228:231], v205 offset:0
	ds_read_b128 v[232:235], v205 offset:2048
	ds_read_b128 v[236:239], v205 offset:4096
	ds_read_b128 v[240:243], v205 offset:6144
	v_mfma_f32_16x16x32_bf16 v[2:5], v[146:149], v[130:133], 0
	v_mfma_f32_16x16x32_bf16 v[6:9], v[150:153], v[130:133], 0
	global_load_dwordx4 v[174:177], v190, s[72:73] offset:0
	v_mfma_f32_16x16x32_bf16 v[10:13], v[154:157], v[130:133], 0
	v_mfma_f32_16x16x32_bf16 v[14:17], v[158:161], v[130:133], 0
	global_load_dwordx4 v[178:181], v190, s[72:73] offset:64
	v_mfma_f32_16x16x32_bf16 v[18:21], v[146:149], v[134:137], 0
	v_mfma_f32_16x16x32_bf16 v[22:25], v[150:153], v[134:137], 0
	global_load_dwordx4 v[182:185], v190, s[72:73] offset:128
	v_mfma_f32_16x16x32_bf16 v[26:29], v[154:157], v[134:137], 0
	v_mfma_f32_16x16x32_bf16 v[30:33], v[158:161], v[134:137], 0
	global_load_dwordx4 v[186:189], v190, s[72:73] offset:192
	v_mfma_f32_16x16x32_bf16 v[34:37], v[146:149], v[138:141], 0
	v_mfma_f32_16x16x32_bf16 v[38:41], v[150:153], v[138:141], 0
	global_load_dwordx2 v[66:67], v206, s[74:75] offset:0
	v_mfma_f32_16x16x32_bf16 v[42:45], v[154:157], v[138:141], 0
	v_mfma_f32_16x16x32_bf16 v[46:49], v[158:161], v[138:141], 0
	global_load_dwordx2 v[70:71], v206, s[74:75] offset:32
	v_mfma_f32_16x16x32_bf16 v[50:53], v[146:149], v[142:145], 0
	v_mfma_f32_16x16x32_bf16 v[54:57], v[150:153], v[142:145], 0
	global_load_dwordx2 v[74:75], v206, s[74:75] offset:64
	v_mfma_f32_16x16x32_bf16 v[58:61], v[154:157], v[142:145], 0
	v_mfma_f32_16x16x32_bf16 v[62:65], v[158:161], v[142:145], 0
	s_waitcnt vmcnt(13)
	s_waitcnt lgkmcnt(0)
	s_barrier
	v_add_u32_e32 v204, 0xc000, v200
	v_add_u32_e32 v205, 0xc000, v202
	ds_read_b128 v[130:133], v204 offset:0
	ds_read_b128 v[134:137], v204 offset:2048
	ds_read_b128 v[138:141], v204 offset:4096
	ds_read_b128 v[142:145], v204 offset:6144
	ds_read_b128 v[146:149], v205 offset:0
	ds_read_b128 v[150:153], v205 offset:2048
	ds_read_b128 v[154:157], v205 offset:4096
	ds_read_b128 v[158:161], v205 offset:6144
	v_mfma_f32_16x16x32_bf16 v[2:5], v[228:231], v[212:215], v[2:5]
	v_mfma_f32_16x16x32_bf16 v[6:9], v[232:235], v[212:215], v[6:9]
	s_add_u32 m0, s76, 0x0
	s_nop 0
	global_load_lds_dwordx4 v196, s[68:69]
	v_mfma_f32_16x16x32_bf16 v[10:13], v[236:239], v[212:215], v[10:13]
	v_mfma_f32_16x16x32_bf16 v[14:17], v[240:243], v[212:215], v[14:17]
	s_add_u32 m0, s76, 0x2000
	s_nop 0
	global_load_lds_dwordx4 v197, s[68:69]
	v_mfma_f32_16x16x32_bf16 v[18:21], v[228:231], v[216:219], v[18:21]
	v_mfma_f32_16x16x32_bf16 v[22:25], v[232:235], v[216:219], v[22:25]
	s_add_u32 m0, s76, 0x4000
	s_nop 0
	global_load_lds_dwordx4 v198, s[68:69]
	v_mfma_f32_16x16x32_bf16 v[26:29], v[236:239], v[216:219], v[26:29]
	v_mfma_f32_16x16x32_bf16 v[30:33], v[240:243], v[216:219], v[30:33]
	s_add_u32 m0, s76, 0x6000
	s_nop 0
	global_load_lds_dwordx4 v199, s[68:69]
	v_mfma_f32_16x16x32_bf16 v[34:37], v[228:231], v[220:223], v[34:37]
	v_mfma_f32_16x16x32_bf16 v[38:41], v[232:235], v[220:223], v[38:41]
	s_add_u32 m0, s76, 0x8000
	s_nop 0
	global_load_lds_dwordx4 v196, s[70:71]
	v_mfma_f32_16x16x32_bf16 v[42:45], v[236:239], v[220:223], v[42:45]
	v_mfma_f32_16x16x32_bf16 v[46:49], v[240:243], v[220:223], v[46:49]
	s_add_u32 m0, s76, 0xa000
	s_nop 0
	global_load_lds_dwordx4 v197, s[70:71]
	v_mfma_f32_16x16x32_bf16 v[50:53], v[228:231], v[224:227], v[50:53]
	v_mfma_f32_16x16x32_bf16 v[54:57], v[232:235], v[224:227], v[54:57]
	s_add_u32 s68, s68, 0x80
	s_addc_u32 s69, s69, 0
	s_add_u32 s70, s70, 0x80
	s_addc_u32 s71, s71, 0
	v_mfma_f32_16x16x32_bf16 v[58:61], v[236:239], v[224:227], v[58:61]
	v_mfma_f32_16x16x32_bf16 v[62:65], v[240:243], v[224:227], v[62:65]
	s_waitcnt lgkmcnt(0)
	v_add_u32_e32 v204, 0xc000, v201
	v_add_u32_e32 v205, 0xc000, v203
	ds_read_b128 v[212:215], v204 offset:0
	ds_read_b128 v[216:219], v204 offset:2048
	ds_read_b128 v[220:223], v204 offset:4096
	ds_read_b128 v[224:227], v204 offset:6144
	ds_read_b128 v[228:231], v205 offset:0
	ds_read_b128 v[232:235], v205 offset:2048
	ds_read_b128 v[236:239], v205 offset:4096
	ds_read_b128 v[240:243], v205 offset:6144
	v_mfma_f32_16x16x32_bf16 v[2:5], v[146:149], v[130:133], v[2:5]
	v_mfma_f32_16x16x32_bf16 v[6:9], v[150:153], v[130:133], v[6:9]
	global_load_dwordx2 v[78:79], v206, s[74:75] offset:96
	v_mfma_f32_16x16x32_bf16 v[10:13], v[154:157], v[130:133], v[10:13]
	v_mfma_f32_16x16x32_bf16 v[14:17], v[158:161], v[130:133], v[14:17]
	global_load_dwordx2 v[82:83], v207, s[74:75] offset:0
	v_mfma_f32_16x16x32_bf16 v[18:21], v[146:149], v[134:137], v[18:21]
	v_mfma_f32_16x16x32_bf16 v[22:25], v[150:153], v[134:137], v[22:25]
	global_load_dwordx2 v[86:87], v207, s[74:75] offset:32
	v_mfma_f32_16x16x32_bf16 v[26:29], v[154:157], v[134:137], v[26:29]
	v_mfma_f32_16x16x32_bf16 v[30:33], v[158:161], v[134:137], v[30:33]
	global_load_dwordx2 v[90:91], v207, s[74:75] offset:64
	v_mfma_f32_16x16x32_bf16 v[34:37], v[146:149], v[138:141], v[34:37]
	v_mfma_f32_16x16x32_bf16 v[38:41], v[150:153], v[138:141], v[38:41]
	global_load_dwordx2 v[94:95], v207, s[74:75] offset:96
	v_mfma_f32_16x16x32_bf16 v[42:45], v[154:157], v[138:141], v[42:45]
	v_mfma_f32_16x16x32_bf16 v[46:49], v[158:161], v[138:141], v[46:49]
	global_load_dwordx2 v[98:99], v208, s[74:75] offset:0
	v_mfma_f32_16x16x32_bf16 v[50:53], v[146:149], v[142:145], v[50:53]
	v_mfma_f32_16x16x32_bf16 v[54:57], v[150:153], v[142:145], v[54:57]
	global_load_dwordx2 v[102:103], v208, s[74:75] offset:32
	v_mfma_f32_16x16x32_bf16 v[58:61], v[154:157], v[142:145], v[58:61]
	v_mfma_f32_16x16x32_bf16 v[62:65], v[158:161], v[142:145], v[62:65]
	s_waitcnt vmcnt(20)
	s_waitcnt lgkmcnt(0)
	s_barrier
	v_add_u32_e32 v204, 0x18000, v200
	v_add_u32_e32 v205, 0x18000, v202
	ds_read_b128 v[130:133], v204 offset:0
	ds_read_b128 v[134:137], v204 offset:2048
	ds_read_b128 v[138:141], v204 offset:4096
	ds_read_b128 v[142:145], v204 offset:6144
	ds_read_b128 v[146:149], v205 offset:0
	ds_read_b128 v[150:153], v205 offset:2048
	ds_read_b128 v[154:157], v205 offset:4096
	ds_read_b128 v[158:161], v205 offset:6144
	v_mfma_f32_16x16x32_bf16 v[2:5], v[228:231], v[212:215], v[2:5]
	v_mfma_f32_16x16x32_bf16 v[6:9], v[232:235], v[212:215], v[6:9]
	s_add_u32 m0, s76, 0xc000
	s_nop 0
	global_load_lds_dwordx4 v196, s[68:69]
	v_mfma_f32_16x16x32_bf16 v[10:13], v[236:239], v[212:215], v[10:13]
	v_mfma_f32_16x16x32_bf16 v[14:17], v[240:243], v[212:215], v[14:17]
	s_add_u32 m0, s76, 0xe000
	s_nop 0
	global_load_lds_dwordx4 v197, s[68:69]
	v_mfma_f32_16x16x32_bf16 v[18:21], v[228:231], v[216:219], v[18:21]
	v_mfma_f32_16x16x32_bf16 v[22:25], v[232:235], v[216:219], v[22:25]
	s_add_u32 m0, s76, 0x10000
	s_nop 0
	global_load_lds_dwordx4 v198, s[68:69]
	v_mfma_f32_16x16x32_bf16 v[26:29], v[236:239], v[216:219], v[26:29]
	v_mfma_f32_16x16x32_bf16 v[30:33], v[240:243], v[216:219], v[30:33]
	s_add_u32 m0, s76, 0x12000
	s_nop 0
	global_load_lds_dwordx4 v199, s[68:69]
	v_mfma_f32_16x16x32_bf16 v[34:37], v[228:231], v[220:223], v[34:37]
	v_mfma_f32_16x16x32_bf16 v[38:41], v[232:235], v[220:223], v[38:41]
	s_add_u32 m0, s76, 0x14000
	s_nop 0
	global_load_lds_dwordx4 v196, s[70:71]
	v_mfma_f32_16x16x32_bf16 v[42:45], v[236:239], v[220:223], v[42:45]
	v_mfma_f32_16x16x32_bf16 v[46:49], v[240:243], v[220:223], v[46:49]
	s_add_u32 m0, s76, 0x16000
	s_nop 0
	global_load_lds_dwordx4 v197, s[70:71]
	v_mfma_f32_16x16x32_bf16 v[50:53], v[228:231], v[224:227], v[50:53]
	v_mfma_f32_16x16x32_bf16 v[54:57], v[232:235], v[224:227], v[54:57]
	s_add_u32 s68, s68, 0x80
	s_addc_u32 s69, s69, 0
	s_add_u32 s70, s70, 0x80
	s_addc_u32 s71, s71, 0
	v_mfma_f32_16x16x32_bf16 v[58:61], v[236:239], v[224:227], v[58:61]
	v_mfma_f32_16x16x32_bf16 v[62:65], v[240:243], v[224:227], v[62:65]
	s_waitcnt lgkmcnt(0)
	v_add_u32_e32 v204, 0x18000, v201
	v_add_u32_e32 v205, 0x18000, v203
	ds_read_b128 v[212:215], v204 offset:0
	ds_read_b128 v[216:219], v204 offset:2048
	ds_read_b128 v[220:223], v204 offset:4096
	ds_read_b128 v[224:227], v204 offset:6144
	ds_read_b128 v[228:231], v205 offset:0
	ds_read_b128 v[232:235], v205 offset:2048
	ds_read_b128 v[236:239], v205 offset:4096
	ds_read_b128 v[240:243], v205 offset:6144
	v_mfma_f32_16x16x32_bf16 v[2:5], v[146:149], v[130:133], v[2:5]
	v_mfma_f32_16x16x32_bf16 v[6:9], v[150:153], v[130:133], v[6:9]
	global_load_dwordx2 v[106:107], v208, s[74:75] offset:64
	v_mfma_f32_16x16x32_bf16 v[10:13], v[154:157], v[130:133], v[10:13]
	v_mfma_f32_16x16x32_bf16 v[14:17], v[158:161], v[130:133], v[14:17]
	global_load_dwordx2 v[110:111], v208, s[74:75] offset:96
	v_mfma_f32_16x16x32_bf16 v[18:21], v[146:149], v[134:137], v[18:21]
	v_mfma_f32_16x16x32_bf16 v[22:25], v[150:153], v[134:137], v[22:25]
	global_load_dwordx2 v[114:115], v209, s[74:75] offset:0
	v_mfma_f32_16x16x32_bf16 v[26:29], v[154:157], v[134:137], v[26:29]
	v_mfma_f32_16x16x32_bf16 v[30:33], v[158:161], v[134:137], v[30:33]
	global_load_dwordx2 v[118:119], v209, s[74:75] offset:32
	v_mfma_f32_16x16x32_bf16 v[34:37], v[146:149], v[138:141], v[34:37]
	v_mfma_f32_16x16x32_bf16 v[38:41], v[150:153], v[138:141], v[38:41]
	global_load_dwordx2 v[122:123], v209, s[74:75] offset:64
	v_mfma_f32_16x16x32_bf16 v[42:45], v[154:157], v[138:141], v[42:45]
	v_mfma_f32_16x16x32_bf16 v[46:49], v[158:161], v[138:141], v[46:49]
	global_load_dwordx2 v[126:127], v209, s[74:75] offset:96
	v_mfma_f32_16x16x32_bf16 v[50:53], v[146:149], v[142:145], v[50:53]
	v_mfma_f32_16x16x32_bf16 v[54:57], v[150:153], v[142:145], v[54:57]
	v_mfma_f32_16x16x32_bf16 v[58:61], v[154:157], v[142:145], v[58:61]
	v_mfma_f32_16x16x32_bf16 v[62:65], v[158:161], v[142:145], v[62:65]
	s_waitcnt vmcnt(19)
	s_waitcnt lgkmcnt(0)
	s_barrier
	v_add_u32_e32 v204, 0x0, v200
	v_add_u32_e32 v205, 0x0, v202
	ds_read_b128 v[130:133], v204 offset:0
	ds_read_b128 v[134:137], v204 offset:2048
	ds_read_b128 v[138:141], v204 offset:4096
	ds_read_b128 v[142:145], v204 offset:6144
	ds_read_b128 v[146:149], v205 offset:0
	ds_read_b128 v[150:153], v205 offset:2048
	ds_read_b128 v[154:157], v205 offset:4096
	ds_read_b128 v[158:161], v205 offset:6144
	v_mfma_f32_16x16x32_bf16 v[2:5], v[228:231], v[212:215], v[2:5]
	v_mfma_f32_16x16x32_bf16 v[6:9], v[232:235], v[212:215], v[6:9]
	s_add_u32 m0, s76, 0x18000
	s_nop 0
	global_load_lds_dwordx4 v196, s[68:69]
	v_mfma_f32_16x16x32_bf16 v[10:13], v[236:239], v[212:215], v[10:13]
	v_mfma_f32_16x16x32_bf16 v[14:17], v[240:243], v[212:215], v[14:17]
	s_add_u32 m0, s76, 0x1a000
	s_nop 0
	global_load_lds_dwordx4 v197, s[68:69]
	v_mfma_f32_16x16x32_bf16 v[18:21], v[228:231], v[216:219], v[18:21]
	v_mfma_f32_16x16x32_bf16 v[22:25], v[232:235], v[216:219], v[22:25]
	s_add_u32 m0, s76, 0x1c000
	s_nop 0
	global_load_lds_dwordx4 v198, s[68:69]
	v_mfma_f32_16x16x32_bf16 v[26:29], v[236:239], v[216:219], v[26:29]
	v_mfma_f32_16x16x32_bf16 v[30:33], v[240:243], v[216:219], v[30:33]
	s_add_u32 m0, s76, 0x1e000
	s_nop 0
	global_load_lds_dwordx4 v199, s[68:69]
	v_mfma_f32_16x16x32_bf16 v[34:37], v[228:231], v[220:223], v[34:37]
	v_mfma_f32_16x16x32_bf16 v[38:41], v[232:235], v[220:223], v[38:41]
	s_add_u32 m0, s76, 0x20000
	s_nop 0
	global_load_lds_dwordx4 v196, s[70:71]
	v_mfma_f32_16x16x32_bf16 v[42:45], v[236:239], v[220:223], v[42:45]
	v_mfma_f32_16x16x32_bf16 v[46:49], v[240:243], v[220:223], v[46:49]
	s_add_u32 m0, s76, 0x22000
	s_nop 0
	global_load_lds_dwordx4 v197, s[70:71]
	v_mfma_f32_16x16x32_bf16 v[50:53], v[228:231], v[224:227], v[50:53]
	v_mfma_f32_16x16x32_bf16 v[54:57], v[232:235], v[224:227], v[54:57]
	s_add_u32 s68, s68, 0x80
	s_addc_u32 s69, s69, 0
	s_add_u32 s70, s70, 0x80
	s_addc_u32 s71, s71, 0
	v_mfma_f32_16x16x32_bf16 v[58:61], v[236:239], v[224:227], v[58:61]
	v_mfma_f32_16x16x32_bf16 v[62:65], v[240:243], v[224:227], v[62:65]
	s_waitcnt lgkmcnt(0)
	v_add_u32_e32 v204, 0x0, v201
	v_add_u32_e32 v205, 0x0, v203
	ds_read_b128 v[212:215], v204 offset:0
	ds_read_b128 v[216:219], v204 offset:2048
	ds_read_b128 v[220:223], v204 offset:4096
	ds_read_b128 v[224:227], v204 offset:6144
	ds_read_b128 v[228:231], v205 offset:0
	ds_read_b128 v[232:235], v205 offset:2048
	ds_read_b128 v[236:239], v205 offset:4096
	ds_read_b128 v[240:243], v205 offset:6144
	v_mfma_f32_16x16x32_bf16 v[2:5], v[146:149], v[130:133], v[2:5]
	v_mfma_f32_16x16x32_bf16 v[6:9], v[150:153], v[130:133], v[6:9]
	v_mfma_f32_16x16x32_bf16 v[10:13], v[154:157], v[130:133], v[10:13]
	v_mfma_f32_16x16x32_bf16 v[14:17], v[158:161], v[130:133], v[14:17]
	v_mfma_f32_16x16x32_bf16 v[18:21], v[146:149], v[134:137], v[18:21]
	v_mfma_f32_16x16x32_bf16 v[22:25], v[150:153], v[134:137], v[22:25]
	v_mfma_f32_16x16x32_bf16 v[26:29], v[154:157], v[134:137], v[26:29]
	v_mfma_f32_16x16x32_bf16 v[30:33], v[158:161], v[134:137], v[30:33]
	v_mfma_f32_16x16x32_bf16 v[34:37], v[146:149], v[138:141], v[34:37]
	v_mfma_f32_16x16x32_bf16 v[38:41], v[150:153], v[138:141], v[38:41]
	v_mfma_f32_16x16x32_bf16 v[42:45], v[154:157], v[138:141], v[42:45]
	v_mfma_f32_16x16x32_bf16 v[46:49], v[158:161], v[138:141], v[46:49]
	v_mfma_f32_16x16x32_bf16 v[50:53], v[146:149], v[142:145], v[50:53]
	v_mfma_f32_16x16x32_bf16 v[54:57], v[150:153], v[142:145], v[54:57]
	v_mfma_f32_16x16x32_bf16 v[58:61], v[154:157], v[142:145], v[58:61]
	v_mfma_f32_16x16x32_bf16 v[62:65], v[158:161], v[142:145], v[62:65]
	s_waitcnt vmcnt(12)
	s_waitcnt lgkmcnt(0)
	s_barrier
	v_add_u32_e32 v204, 0xc000, v200
	v_add_u32_e32 v205, 0xc000, v202
	ds_read_b128 v[130:133], v204 offset:0
	ds_read_b128 v[134:137], v204 offset:2048
	ds_read_b128 v[138:141], v204 offset:4096
	ds_read_b128 v[142:145], v204 offset:6144
	ds_read_b128 v[146:149], v205 offset:0
	ds_read_b128 v[150:153], v205 offset:2048
	ds_read_b128 v[154:157], v205 offset:4096
	ds_read_b128 v[158:161], v205 offset:6144
	v_mfma_f32_16x16x32_bf16 v[2:5], v[228:231], v[212:215], v[2:5]
	v_mfma_f32_16x16x32_bf16 v[6:9], v[232:235], v[212:215], v[6:9]
	s_add_u32 m0, s76, 0x0
	s_nop 0
	global_load_lds_dwordx4 v196, s[68:69]
	v_mfma_f32_16x16x32_bf16 v[10:13], v[236:239], v[212:215], v[10:13]
	v_mfma_f32_16x16x32_bf16 v[14:17], v[240:243], v[212:215], v[14:17]
	s_add_u32 m0, s76, 0x2000
	s_nop 0
	global_load_lds_dwordx4 v197, s[68:69]
	v_mfma_f32_16x16x32_bf16 v[18:21], v[228:231], v[216:219], v[18:21]
	v_mfma_f32_16x16x32_bf16 v[22:25], v[232:235], v[216:219], v[22:25]
	s_add_u32 m0, s76, 0x4000
	s_nop 0
	global_load_lds_dwordx4 v198, s[68:69]
	v_mfma_f32_16x16x32_bf16 v[26:29], v[236:239], v[216:219], v[26:29]
	v_mfma_f32_16x16x32_bf16 v[30:33], v[240:243], v[216:219], v[30:33]
	s_add_u32 m0, s76, 0x6000
	s_nop 0
	global_load_lds_dwordx4 v199, s[68:69]
	v_mfma_f32_16x16x32_bf16 v[34:37], v[228:231], v[220:223], v[34:37]
	v_mfma_f32_16x16x32_bf16 v[38:41], v[232:235], v[220:223], v[38:41]
	s_add_u32 m0, s76, 0x8000
	s_nop 0
	global_load_lds_dwordx4 v196, s[70:71]
	v_mfma_f32_16x16x32_bf16 v[42:45], v[236:239], v[220:223], v[42:45]
	v_mfma_f32_16x16x32_bf16 v[46:49], v[240:243], v[220:223], v[46:49]
	s_add_u32 m0, s76, 0xa000
	s_nop 0
	global_load_lds_dwordx4 v197, s[70:71]
	v_mfma_f32_16x16x32_bf16 v[50:53], v[228:231], v[224:227], v[50:53]
	v_mfma_f32_16x16x32_bf16 v[54:57], v[232:235], v[224:227], v[54:57]
	s_add_u32 s68, s68, 0x80
	s_addc_u32 s69, s69, 0
	s_add_u32 s70, s70, 0x80
	s_addc_u32 s71, s71, 0
	v_mfma_f32_16x16x32_bf16 v[58:61], v[236:239], v[224:227], v[58:61]
	v_mfma_f32_16x16x32_bf16 v[62:65], v[240:243], v[224:227], v[62:65]
	s_waitcnt lgkmcnt(0)
	v_add_u32_e32 v204, 0xc000, v201
	v_add_u32_e32 v205, 0xc000, v203
	ds_read_b128 v[212:215], v204 offset:0
	ds_read_b128 v[216:219], v204 offset:2048
	ds_read_b128 v[220:223], v204 offset:4096
	ds_read_b128 v[224:227], v204 offset:6144
	ds_read_b128 v[228:231], v205 offset:0
	ds_read_b128 v[232:235], v205 offset:2048
	ds_read_b128 v[236:239], v205 offset:4096
	ds_read_b128 v[240:243], v205 offset:6144
	v_mfma_f32_16x16x32_bf16 v[2:5], v[146:149], v[130:133], v[2:5]
	v_mfma_f32_16x16x32_bf16 v[6:9], v[150:153], v[130:133], v[6:9]
	v_mfma_f32_16x16x32_bf16 v[10:13], v[154:157], v[130:133], v[10:13]
	v_mfma_f32_16x16x32_bf16 v[14:17], v[158:161], v[130:133], v[14:17]
	v_mfma_f32_16x16x32_bf16 v[18:21], v[146:149], v[134:137], v[18:21]
	v_mfma_f32_16x16x32_bf16 v[22:25], v[150:153], v[134:137], v[22:25]
	v_mfma_f32_16x16x32_bf16 v[26:29], v[154:157], v[134:137], v[26:29]
	v_mfma_f32_16x16x32_bf16 v[30:33], v[158:161], v[134:137], v[30:33]
	v_mfma_f32_16x16x32_bf16 v[34:37], v[146:149], v[138:141], v[34:37]
	v_mfma_f32_16x16x32_bf16 v[38:41], v[150:153], v[138:141], v[38:41]
	v_mfma_f32_16x16x32_bf16 v[42:45], v[154:157], v[138:141], v[42:45]
	v_mfma_f32_16x16x32_bf16 v[46:49], v[158:161], v[138:141], v[46:49]
	v_mfma_f32_16x16x32_bf16 v[50:53], v[146:149], v[142:145], v[50:53]
	v_mfma_f32_16x16x32_bf16 v[54:57], v[150:153], v[142:145], v[54:57]
	v_mfma_f32_16x16x32_bf16 v[58:61], v[154:157], v[142:145], v[58:61]
	v_mfma_f32_16x16x32_bf16 v[62:65], v[158:161], v[142:145], v[62:65]
	s_mov_b32 s16, 12

.Lop_tile:
	s_and_b32 s0, s78, 3
	s_or_b32 s0, s0, s77
	s_lshr_b32 s1, s78, 2
	s_lshl_b32 s1, s1, 7
	s_lshl_b32 s2, s0, 8
	s_mul_i32 s3, s2, 0x800
	s_add_u32 s68, s18, s3
	s_addc_u32 s69, s19, 0
	s_mul_i32 s3, s1, 0x800
	s_add_u32 s70, s80, s3
	s_addc_u32 s71, s81, 0
	s_lshl_b32 s3, s2, 11
	s_lshl_b32 s12, s1, 1
	s_add_u32 s3, s3, s12
	s_add_u32 s74, s24, s3
	s_addc_u32 s75, s25, 0
	s_add_i32 s12, s0, -12
	s_lshr_b32 s12, s12, 2
	s_cmp_lt_u32 s0, 16
	s_cselect_b32 s12, 0, s12
	s_cselect_b32 s14, s52, s54
	s_cselect_b32 s15, s53, s55
	s_mul_i32 s13, s82, 5
	s_add_i32 s12, s12, s13
	s_mul_i32 s12, s12, 0x6000
	s_add_u32 s12, s12, 0x2000
	s_lshl_b32 s13, s1, 2
	s_add_u32 s12, s12, s13
	s_add_u32 s72, s30, s12
	s_addc_u32 s73, s31, 0
	s_and_b32 s12, s0, 15
	s_lshl_b32 s12, s12, 20
	s_add_u32 s12, s12, s13
	s_add_u32 s14, s14, s12
	s_addc_u32 s15, s15, 0
	s_cmp_eq_u32 s82, 0
	s_cselect_b32 s14, s14, s74
	s_cselect_b32 s15, s15, s75
	s_cselect_b32 s38, 64, 32
	s_cselect_b64 vcc, -1, 0
	s_lshl_b32 s39, s38, 1
	s_add_u32 s40, s39, s38
	v_cndmask_b32_e32 v191, v206, v210, vcc
	v_cndmask_b32_e32 v192, v207, v211, vcc
	v_cndmask_b32_e32 v193, v208, v168, vcc
	v_cndmask_b32_e32 v244, v209, v169, vcc
	s_add_u32 m0, s76, 0x0
	s_nop 0
	global_load_lds_dwordx4 v196, s[68:69]
	s_add_u32 m0, s76, 0x2000
	s_nop 0
	global_load_lds_dwordx4 v197, s[68:69]
	s_add_u32 m0, s76, 0x4000
	s_nop 0
	global_load_lds_dwordx4 v198, s[68:69]
	s_add_u32 m0, s76, 0x6000
	s_nop 0
	global_load_lds_dwordx4 v199, s[68:69]
	s_add_u32 m0, s76, 0x8000
	s_nop 0
	global_load_lds_dwordx4 v196, s[70:71]
	s_add_u32 m0, s76, 0xa000
	s_nop 0
	global_load_lds_dwordx4 v197, s[70:71]
	s_add_u32 s68, s68, 0x80
	s_addc_u32 s69, s69, 0
	s_add_u32 s70, s70, 0x80
	s_addc_u32 s71, s71, 0
	s_add_u32 m0, s76, 0xc000
	s_nop 0
	global_load_lds_dwordx4 v196, s[68:69]
	s_add_u32 m0, s76, 0xe000
	s_nop 0
	global_load_lds_dwordx4 v197, s[68:69]
	s_add_u32 m0, s76, 0x10000
	s_nop 0
	global_load_lds_dwordx4 v198, s[68:69]
	s_add_u32 m0, s76, 0x12000
	s_nop 0
	global_load_lds_dwordx4 v199, s[68:69]
	s_add_u32 m0, s76, 0x14000
	s_nop 0
	global_load_lds_dwordx4 v196, s[70:71]
	s_add_u32 m0, s76, 0x16000
	s_nop 0
	global_load_lds_dwordx4 v197, s[70:71]
	s_add_u32 s68, s68, 0x80
	s_addc_u32 s69, s69, 0
	s_add_u32 s70, s70, 0x80
	s_addc_u32 s71, s71, 0
	s_waitcnt vmcnt(6)
	s_waitcnt lgkmcnt(0)
	s_barrier
	v_add_u32_e32 v204, 0x0, v200
	v_add_u32_e32 v205, 0x0, v202
	ds_read_b128 v[130:133], v204 offset:0
	ds_read_b128 v[134:137], v204 offset:2048
	ds_read_b128 v[138:141], v204 offset:4096
	ds_read_b128 v[142:145], v204 offset:6144
	ds_read_b128 v[146:149], v205 offset:0
	ds_read_b128 v[150:153], v205 offset:2048
	ds_read_b128 v[154:157], v205 offset:4096
	ds_read_b128 v[158:161], v205 offset:6144
	s_add_u32 m0, s76, 0x18000
	s_nop 0
	global_load_lds_dwordx4 v196, s[68:69]
	s_add_u32 m0, s76, 0x1a000
	s_nop 0
	global_load_lds_dwordx4 v197, s[68:69]
	s_add_u32 m0, s76, 0x1c000
	s_nop 0
	global_load_lds_dwordx4 v198, s[68:69]
	s_add_u32 m0, s76, 0x1e000
	s_nop 0
	global_load_lds_dwordx4 v199, s[68:69]
	s_add_u32 m0, s76, 0x20000
	s_nop 0
	global_load_lds_dwordx4 v196, s[70:71]
	s_add_u32 m0, s76, 0x22000
	s_nop 0
	global_load_lds_dwordx4 v197, s[70:71]
	s_add_u32 s68, s68, 0x80
	s_addc_u32 s69, s69, 0
	s_add_u32 s70, s70, 0x80
	s_addc_u32 s71, s71, 0
	s_waitcnt lgkmcnt(0)
	v_add_u32_e32 v204, 0x0, v201
	v_add_u32_e32 v205, 0x0, v203
	ds_read_b128 v[212:215], v204 offset:0
	ds_read_b128 v[216:219], v204 offset:2048
	ds_read_b128 v[220:223], v204 offset:4096
	ds_read_b128 v[224:227], v204 offset:6144
	ds_read_b128 v[228:231], v205 offset:0
	ds_read_b128 v[232:235], v205 offset:2048
	ds_read_b128 v[236:239], v205 offset:4096
	ds_read_b128 v[240:243], v205 offset:6144
	v_mfma_f32_16x16x32_bf16 v[2:5], v[146:149], v[130:133], 0
	v_mfma_f32_16x16x32_bf16 v[6:9], v[150:153], v[130:133], 0
	global_load_dwordx4 v[174:177], v190, s[72:73] offset:0
	v_mfma_f32_16x16x32_bf16 v[10:13], v[154:157], v[130:133], 0
	v_mfma_f32_16x16x32_bf16 v[14:17], v[158:161], v[130:133], 0
	global_load_dwordx4 v[178:181], v190, s[72:73] offset:64
	v_mfma_f32_16x16x32_bf16 v[18:21], v[146:149], v[134:137], 0
	v_mfma_f32_16x16x32_bf16 v[22:25], v[150:153], v[134:137], 0
	v_mfma_f32_16x16x32_bf16 v[26:29], v[154:157], v[134:137], 0
	v_mfma_f32_16x16x32_bf16 v[30:33], v[158:161], v[134:137], 0
	v_mfma_f32_16x16x32_bf16 v[34:37], v[146:149], v[138:141], 0
	v_mfma_f32_16x16x32_bf16 v[38:41], v[150:153], v[138:141], 0
	v_mfma_f32_16x16x32_bf16 v[42:45], v[154:157], v[138:141], 0
	v_mfma_f32_16x16x32_bf16 v[46:49], v[158:161], v[138:141], 0
	v_mfma_f32_16x16x32_bf16 v[50:53], v[146:149], v[142:145], 0
	v_mfma_f32_16x16x32_bf16 v[54:57], v[150:153], v[142:145], 0
	v_mfma_f32_16x16x32_bf16 v[58:61], v[154:157], v[142:145], 0
	v_mfma_f32_16x16x32_bf16 v[62:65], v[158:161], v[142:145], 0
	s_waitcnt vmcnt(8)
	s_waitcnt lgkmcnt(0)
	s_barrier
	v_add_u32_e32 v204, 0xc000, v200
	v_add_u32_e32 v205, 0xc000, v202
	ds_read_b128 v[130:133], v204 offset:0
	ds_read_b128 v[134:137], v204 offset:2048
	ds_read_b128 v[138:141], v204 offset:4096
	ds_read_b128 v[142:145], v204 offset:6144
	ds_read_b128 v[146:149], v205 offset:0
	ds_read_b128 v[150:153], v205 offset:2048
	ds_read_b128 v[154:157], v205 offset:4096
	ds_read_b128 v[158:161], v205 offset:6144
	v_mfma_f32_16x16x32_bf16 v[2:5], v[228:231], v[212:215], v[2:5]
	v_mfma_f32_16x16x32_bf16 v[6:9], v[232:235], v[212:215], v[6:9]
	s_add_u32 m0, s76, 0x0
	s_nop 0
	global_load_lds_dwordx4 v196, s[68:69]
	v_mfma_f32_16x16x32_bf16 v[10:13], v[236:239], v[212:215], v[10:13]
	v_mfma_f32_16x16x32_bf16 v[14:17], v[240:243], v[212:215], v[14:17]
	s_add_u32 m0, s76, 0x2000
	s_nop 0
	global_load_lds_dwordx4 v197, s[68:69]
	v_mfma_f32_16x16x32_bf16 v[18:21], v[228:231], v[216:219], v[18:21]
	v_mfma_f32_16x16x32_bf16 v[22:25], v[232:235], v[216:219], v[22:25]
	s_add_u32 m0, s76, 0x4000
	s_nop 0
	global_load_lds_dwordx4 v198, s[68:69]
	v_mfma_f32_16x16x32_bf16 v[26:29], v[236:239], v[216:219], v[26:29]
	v_mfma_f32_16x16x32_bf16 v[30:33], v[240:243], v[216:219], v[30:33]
	s_add_u32 m0, s76, 0x6000
	s_nop 0
	global_load_lds_dwordx4 v199, s[68:69]
	v_mfma_f32_16x16x32_bf16 v[34:37], v[228:231], v[220:223], v[34:37]
	v_mfma_f32_16x16x32_bf16 v[38:41], v[232:235], v[220:223], v[38:41]
	s_add_u32 m0, s76, 0x8000
	s_nop 0
	global_load_lds_dwordx4 v196, s[70:71]
	v_mfma_f32_16x16x32_bf16 v[42:45], v[236:239], v[220:223], v[42:45]
	v_mfma_f32_16x16x32_bf16 v[46:49], v[240:243], v[220:223], v[46:49]
	s_add_u32 m0, s76, 0xa000
	s_nop 0
	global_load_lds_dwordx4 v197, s[70:71]
	v_mfma_f32_16x16x32_bf16 v[50:53], v[228:231], v[224:227], v[50:53]
	v_mfma_f32_16x16x32_bf16 v[54:57], v[232:235], v[224:227], v[54:57]
	s_add_u32 s68, s68, 0x80
	s_addc_u32 s69, s69, 0
	s_add_u32 s70, s70, 0x80
	s_addc_u32 s71, s71, 0
	v_mfma_f32_16x16x32_bf16 v[58:61], v[236:239], v[224:227], v[58:61]
	v_mfma_f32_16x16x32_bf16 v[62:65], v[240:243], v[224:227], v[62:65]
	s_waitcnt lgkmcnt(0)
	v_add_u32_e32 v204, 0xc000, v201
	v_add_u32_e32 v205, 0xc000, v203
	ds_read_b128 v[212:215], v204 offset:0
	ds_read_b128 v[216:219], v204 offset:2048
	ds_read_b128 v[220:223], v204 offset:4096
	ds_read_b128 v[224:227], v204 offset:6144
	ds_read_b128 v[228:231], v205 offset:0
	ds_read_b128 v[232:235], v205 offset:2048
	ds_read_b128 v[236:239], v205 offset:4096
	ds_read_b128 v[240:243], v205 offset:6144
	v_mfma_f32_16x16x32_bf16 v[2:5], v[146:149], v[130:133], v[2:5]
	v_mfma_f32_16x16x32_bf16 v[6:9], v[150:153], v[130:133], v[6:9]
	global_load_dwordx4 v[182:185], v190, s[72:73] offset:128
	v_mfma_f32_16x16x32_bf16 v[10:13], v[154:157], v[130:133], v[10:13]
	v_mfma_f32_16x16x32_bf16 v[14:17], v[158:161], v[130:133], v[14:17]
	global_load_dwordx4 v[186:189], v190, s[72:73] offset:192
	v_mfma_f32_16x16x32_bf16 v[18:21], v[146:149], v[134:137], v[18:21]
	v_mfma_f32_16x16x32_bf16 v[22:25], v[150:153], v[134:137], v[22:25]
	v_mfma_f32_16x16x32_bf16 v[26:29], v[154:157], v[134:137], v[26:29]
	v_mfma_f32_16x16x32_bf16 v[30:33], v[158:161], v[134:137], v[30:33]
	v_mfma_f32_16x16x32_bf16 v[34:37], v[146:149], v[138:141], v[34:37]
	v_mfma_f32_16x16x32_bf16 v[38:41], v[150:153], v[138:141], v[38:41]
	v_mfma_f32_16x16x32_bf16 v[42:45], v[154:157], v[138:141], v[42:45]
	v_mfma_f32_16x16x32_bf16 v[46:49], v[158:161], v[138:141], v[46:49]
	v_mfma_f32_16x16x32_bf16 v[50:53], v[146:149], v[142:145], v[50:53]
	v_mfma_f32_16x16x32_bf16 v[54:57], v[150:153], v[142:145], v[54:57]
	v_mfma_f32_16x16x32_bf16 v[58:61], v[154:157], v[142:145], v[58:61]
	v_mfma_f32_16x16x32_bf16 v[62:65], v[158:161], v[142:145], v[62:65]
	s_waitcnt vmcnt(10)
	s_waitcnt lgkmcnt(0)
	s_barrier
	v_add_u32_e32 v204, 0x18000, v200
	v_add_u32_e32 v205, 0x18000, v202
	ds_read_b128 v[130:133], v204 offset:0
	ds_read_b128 v[134:137], v204 offset:2048
	ds_read_b128 v[138:141], v204 offset:4096
	ds_read_b128 v[142:145], v204 offset:6144
	ds_read_b128 v[146:149], v205 offset:0
	ds_read_b128 v[150:153], v205 offset:2048
	ds_read_b128 v[154:157], v205 offset:4096
	ds_read_b128 v[158:161], v205 offset:6144
	v_mfma_f32_16x16x32_bf16 v[2:5], v[228:231], v[212:215], v[2:5]
	v_mfma_f32_16x16x32_bf16 v[6:9], v[232:235], v[212:215], v[6:9]
	s_add_u32 m0, s76, 0xc000
	s_nop 0
	global_load_lds_dwordx4 v196, s[68:69]
	v_mfma_f32_16x16x32_bf16 v[10:13], v[236:239], v[212:215], v[10:13]
	v_mfma_f32_16x16x32_bf16 v[14:17], v[240:243], v[212:215], v[14:17]
	s_add_u32 m0, s76, 0xe000
	s_nop 0
	global_load_lds_dwordx4 v197, s[68:69]
	v_mfma_f32_16x16x32_bf16 v[18:21], v[228:231], v[216:219], v[18:21]
	v_mfma_f32_16x16x32_bf16 v[22:25], v[232:235], v[216:219], v[22:25]
	s_add_u32 m0, s76, 0x10000
	s_nop 0
	global_load_lds_dwordx4 v198, s[68:69]
	v_mfma_f32_16x16x32_bf16 v[26:29], v[236:239], v[216:219], v[26:29]
	v_mfma_f32_16x16x32_bf16 v[30:33], v[240:243], v[216:219], v[30:33]
	s_add_u32 m0, s76, 0x12000
	s_nop 0
	global_load_lds_dwordx4 v199, s[68:69]
	v_mfma_f32_16x16x32_bf16 v[34:37], v[228:231], v[220:223], v[34:37]
	v_mfma_f32_16x16x32_bf16 v[38:41], v[232:235], v[220:223], v[38:41]
	s_add_u32 m0, s76, 0x14000
	s_nop 0
	global_load_lds_dwordx4 v196, s[70:71]
	v_mfma_f32_16x16x32_bf16 v[42:45], v[236:239], v[220:223], v[42:45]
	v_mfma_f32_16x16x32_bf16 v[46:49], v[240:243], v[220:223], v[46:49]
	s_add_u32 m0, s76, 0x16000
	s_nop 0
	global_load_lds_dwordx4 v197, s[70:71]
	v_mfma_f32_16x16x32_bf16 v[50:53], v[228:231], v[224:227], v[50:53]
	v_mfma_f32_16x16x32_bf16 v[54:57], v[232:235], v[224:227], v[54:57]
	s_add_u32 s68, s68, 0x80
	s_addc_u32 s69, s69, 0
	s_add_u32 s70, s70, 0x80
	s_addc_u32 s71, s71, 0
	v_mfma_f32_16x16x32_bf16 v[58:61], v[236:239], v[224:227], v[58:61]
	v_mfma_f32_16x16x32_bf16 v[62:65], v[240:243], v[224:227], v[62:65]
	s_waitcnt lgkmcnt(0)
	v_add_u32_e32 v204, 0x18000, v201
	v_add_u32_e32 v205, 0x18000, v203
	ds_read_b128 v[212:215], v204 offset:0
	ds_read_b128 v[216:219], v204 offset:2048
	ds_read_b128 v[220:223], v204 offset:4096
	ds_read_b128 v[224:227], v204 offset:6144
	ds_read_b128 v[228:231], v205 offset:0
	ds_read_b128 v[232:235], v205 offset:2048
	ds_read_b128 v[236:239], v205 offset:4096
	ds_read_b128 v[240:243], v205 offset:6144
	v_mfma_f32_16x16x32_bf16 v[2:5], v[146:149], v[130:133], v[2:5]
	v_mfma_f32_16x16x32_bf16 v[6:9], v[150:153], v[130:133], v[6:9]
	global_load_dwordx4 v[66:69], v191, s[14:15]
	v_mfma_f32_16x16x32_bf16 v[10:13], v[154:157], v[130:133], v[10:13]
	v_mfma_f32_16x16x32_bf16 v[14:17], v[158:161], v[130:133], v[14:17]
	v_add_u32_e32 v170, s38, v191
	global_load_dwordx4 v[70:73], v170, s[14:15]
	v_mfma_f32_16x16x32_bf16 v[18:21], v[146:149], v[134:137], v[18:21]
	v_mfma_f32_16x16x32_bf16 v[22:25], v[150:153], v[134:137], v[22:25]
	v_mfma_f32_16x16x32_bf16 v[26:29], v[154:157], v[134:137], v[26:29]
	v_mfma_f32_16x16x32_bf16 v[30:33], v[158:161], v[134:137], v[30:33]
	v_mfma_f32_16x16x32_bf16 v[34:37], v[146:149], v[138:141], v[34:37]
	v_mfma_f32_16x16x32_bf16 v[38:41], v[150:153], v[138:141], v[38:41]
	v_mfma_f32_16x16x32_bf16 v[42:45], v[154:157], v[138:141], v[42:45]
	v_mfma_f32_16x16x32_bf16 v[46:49], v[158:161], v[138:141], v[46:49]
	v_mfma_f32_16x16x32_bf16 v[50:53], v[146:149], v[142:145], v[50:53]
	v_mfma_f32_16x16x32_bf16 v[54:57], v[150:153], v[142:145], v[54:57]
	v_mfma_f32_16x16x32_bf16 v[58:61], v[154:157], v[142:145], v[58:61]
	v_mfma_f32_16x16x32_bf16 v[62:65], v[158:161], v[142:145], v[62:65]
	s_waitcnt vmcnt(10)
	s_waitcnt lgkmcnt(0)
	s_barrier
	v_add_u32_e32 v204, 0x0, v200
	v_add_u32_e32 v205, 0x0, v202
	ds_read_b128 v[130:133], v204 offset:0
	ds_read_b128 v[134:137], v204 offset:2048
	ds_read_b128 v[138:141], v204 offset:4096
	ds_read_b128 v[142:145], v204 offset:6144
	ds_read_b128 v[146:149], v205 offset:0
	ds_read_b128 v[150:153], v205 offset:2048
	ds_read_b128 v[154:157], v205 offset:4096
	ds_read_b128 v[158:161], v205 offset:6144
	v_mfma_f32_16x16x32_bf16 v[2:5], v[228:231], v[212:215], v[2:5]
	v_mfma_f32_16x16x32_bf16 v[6:9], v[232:235], v[212:215], v[6:9]
	s_add_u32 m0, s76, 0x18000
	s_nop 0
	global_load_lds_dwordx4 v196, s[68:69]
	v_mfma_f32_16x16x32_bf16 v[10:13], v[236:239], v[212:215], v[10:13]
	v_mfma_f32_16x16x32_bf16 v[14:17], v[240:243], v[212:215], v[14:17]
	s_add_u32 m0, s76, 0x1a000
	s_nop 0
	global_load_lds_dwordx4 v197, s[68:69]
	v_mfma_f32_16x16x32_bf16 v[18:21], v[228:231], v[216:219], v[18:21]
	v_mfma_f32_16x16x32_bf16 v[22:25], v[232:235], v[216:219], v[22:25]
	s_add_u32 m0, s76, 0x1c000
	s_nop 0
	global_load_lds_dwordx4 v198, s[68:69]
	v_mfma_f32_16x16x32_bf16 v[26:29], v[236:239], v[216:219], v[26:29]
	v_mfma_f32_16x16x32_bf16 v[30:33], v[240:243], v[216:219], v[30:33]
	s_add_u32 m0, s76, 0x1e000
	s_nop 0
	global_load_lds_dwordx4 v199, s[68:69]
	v_mfma_f32_16x16x32_bf16 v[34:37], v[228:231], v[220:223], v[34:37]
	v_mfma_f32_16x16x32_bf16 v[38:41], v[232:235], v[220:223], v[38:41]
	s_add_u32 m0, s76, 0x20000
	s_nop 0
	global_load_lds_dwordx4 v196, s[70:71]
	v_mfma_f32_16x16x32_bf16 v[42:45], v[236:239], v[220:223], v[42:45]
	v_mfma_f32_16x16x32_bf16 v[46:49], v[240:243], v[220:223], v[46:49]
	s_add_u32 m0, s76, 0x22000
	s_nop 0
	global_load_lds_dwordx4 v197, s[70:71]
	v_mfma_f32_16x16x32_bf16 v[50:53], v[228:231], v[224:227], v[50:53]
	v_mfma_f32_16x16x32_bf16 v[54:57], v[232:235], v[224:227], v[54:57]
	s_add_u32 s68, s68, 0x80
	s_addc_u32 s69, s69, 0
	s_add_u32 s70, s70, 0x80
	s_addc_u32 s71, s71, 0
	v_mfma_f32_16x16x32_bf16 v[58:61], v[236:239], v[224:227], v[58:61]
	v_mfma_f32_16x16x32_bf16 v[62:65], v[240:243], v[224:227], v[62:65]
	s_waitcnt lgkmcnt(0)
	v_add_u32_e32 v204, 0x0, v201
	v_add_u32_e32 v205, 0x0, v203
	ds_read_b128 v[212:215], v204 offset:0
	ds_read_b128 v[216:219], v204 offset:2048
	ds_read_b128 v[220:223], v204 offset:4096
	ds_read_b128 v[224:227], v204 offset:6144
	ds_read_b128 v[228:231], v205 offset:0
	ds_read_b128 v[232:235], v205 offset:2048
	ds_read_b128 v[236:239], v205 offset:4096
	ds_read_b128 v[240:243], v205 offset:6144
	v_mfma_f32_16x16x32_bf16 v[2:5], v[146:149], v[130:133], v[2:5]
	v_mfma_f32_16x16x32_bf16 v[6:9], v[150:153], v[130:133], v[6:9]
	v_add_u32_e32 v170, s39, v191
	global_load_dwordx4 v[74:77], v170, s[14:15]
	v_mfma_f32_16x16x32_bf16 v[10:13], v[154:157], v[130:133], v[10:13]
	v_mfma_f32_16x16x32_bf16 v[14:17], v[158:161], v[130:133], v[14:17]
	v_add_u32_e32 v170, s40, v191
	global_load_dwordx4 v[78:81], v170, s[14:15]
	v_mfma_f32_16x16x32_bf16 v[18:21], v[146:149], v[134:137], v[18:21]
	v_mfma_f32_16x16x32_bf16 v[22:25], v[150:153], v[134:137], v[22:25]
	v_mfma_f32_16x16x32_bf16 v[26:29], v[154:157], v[134:137], v[26:29]
	v_mfma_f32_16x16x32_bf16 v[30:33], v[158:161], v[134:137], v[30:33]
	v_mfma_f32_16x16x32_bf16 v[34:37], v[146:149], v[138:141], v[34:37]
	v_mfma_f32_16x16x32_bf16 v[38:41], v[150:153], v[138:141], v[38:41]
	v_mfma_f32_16x16x32_bf16 v[42:45], v[154:157], v[138:141], v[42:45]
	v_mfma_f32_16x16x32_bf16 v[46:49], v[158:161], v[138:141], v[46:49]
	v_mfma_f32_16x16x32_bf16 v[50:53], v[146:149], v[142:145], v[50:53]
	v_mfma_f32_16x16x32_bf16 v[54:57], v[150:153], v[142:145], v[54:57]
	v_mfma_f32_16x16x32_bf16 v[58:61], v[154:157], v[142:145], v[58:61]
	v_mfma_f32_16x16x32_bf16 v[62:65], v[158:161], v[142:145], v[62:65]
	s_waitcnt vmcnt(10)
	s_waitcnt lgkmcnt(0)
	s_barrier
	v_add_u32_e32 v204, 0xc000, v200
	v_add_u32_e32 v205, 0xc000, v202
	ds_read_b128 v[130:133], v204 offset:0
	ds_read_b128 v[134:137], v204 offset:2048
	ds_read_b128 v[138:141], v204 offset:4096
	ds_read_b128 v[142:145], v204 offset:6144
	ds_read_b128 v[146:149], v205 offset:0
	ds_read_b128 v[150:153], v205 offset:2048
	ds_read_b128 v[154:157], v205 offset:4096
	ds_read_b128 v[158:161], v205 offset:6144
	v_mfma_f32_16x16x32_bf16 v[2:5], v[228:231], v[212:215], v[2:5]
	v_mfma_f32_16x16x32_bf16 v[6:9], v[232:235], v[212:215], v[6:9]
	s_add_u32 m0, s76, 0x0
	s_nop 0
	global_load_lds_dwordx4 v196, s[68:69]
	v_mfma_f32_16x16x32_bf16 v[10:13], v[236:239], v[212:215], v[10:13]
	v_mfma_f32_16x16x32_bf16 v[14:17], v[240:243], v[212:215], v[14:17]
	s_add_u32 m0, s76, 0x2000
	s_nop 0
	global_load_lds_dwordx4 v197, s[68:69]
	v_mfma_f32_16x16x32_bf16 v[18:21], v[228:231], v[216:219], v[18:21]
	v_mfma_f32_16x16x32_bf16 v[22:25], v[232:235], v[216:219], v[22:25]
	s_add_u32 m0, s76, 0x4000
	s_nop 0
	global_load_lds_dwordx4 v198, s[68:69]
	v_mfma_f32_16x16x32_bf16 v[26:29], v[236:239], v[216:219], v[26:29]
	v_mfma_f32_16x16x32_bf16 v[30:33], v[240:243], v[216:219], v[30:33]
	s_add_u32 m0, s76, 0x6000
	s_nop 0
	global_load_lds_dwordx4 v199, s[68:69]
	v_mfma_f32_16x16x32_bf16 v[34:37], v[228:231], v[220:223], v[34:37]
	v_mfma_f32_16x16x32_bf16 v[38:41], v[232:235], v[220:223], v[38:41]
	s_add_u32 m0, s76, 0x8000
	s_nop 0
	global_load_lds_dwordx4 v196, s[70:71]
	v_mfma_f32_16x16x32_bf16 v[42:45], v[236:239], v[220:223], v[42:45]
	v_mfma_f32_16x16x32_bf16 v[46:49], v[240:243], v[220:223], v[46:49]
	s_add_u32 m0, s76, 0xa000
	s_nop 0
	global_load_lds_dwordx4 v197, s[70:71]
	v_mfma_f32_16x16x32_bf16 v[50:53], v[228:231], v[224:227], v[50:53]
	v_mfma_f32_16x16x32_bf16 v[54:57], v[232:235], v[224:227], v[54:57]
	s_add_u32 s68, s68, 0x80
	s_addc_u32 s69, s69, 0
	s_add_u32 s70, s70, 0x80
	s_addc_u32 s71, s71, 0
	v_mfma_f32_16x16x32_bf16 v[58:61], v[236:239], v[224:227], v[58:61]
	v_mfma_f32_16x16x32_bf16 v[62:65], v[240:243], v[224:227], v[62:65]
	s_waitcnt lgkmcnt(0)
	v_add_u32_e32 v204, 0xc000, v201
	v_add_u32_e32 v205, 0xc000, v203
	ds_read_b128 v[212:215], v204 offset:0
	ds_read_b128 v[216:219], v204 offset:2048
	ds_read_b128 v[220:223], v204 offset:4096
	ds_read_b128 v[224:227], v204 offset:6144
	ds_read_b128 v[228:231], v205 offset:0
	ds_read_b128 v[232:235], v205 offset:2048
	ds_read_b128 v[236:239], v205 offset:4096
	ds_read_b128 v[240:243], v205 offset:6144
	v_mfma_f32_16x16x32_bf16 v[2:5], v[146:149], v[130:133], v[2:5]
	v_mfma_f32_16x16x32_bf16 v[6:9], v[150:153], v[130:133], v[6:9]
	global_load_dwordx4 v[82:85], v192, s[14:15]
	v_mfma_f32_16x16x32_bf16 v[10:13], v[154:157], v[130:133], v[10:13]
	v_mfma_f32_16x16x32_bf16 v[14:17], v[158:161], v[130:133], v[14:17]
	v_add_u32_e32 v170, s38, v192
	global_load_dwordx4 v[86:89], v170, s[14:15]
	v_mfma_f32_16x16x32_bf16 v[18:21], v[146:149], v[134:137], v[18:21]
	v_mfma_f32_16x16x32_bf16 v[22:25], v[150:153], v[134:137], v[22:25]
	v_mfma_f32_16x16x32_bf16 v[26:29], v[154:157], v[134:137], v[26:29]
	v_mfma_f32_16x16x32_bf16 v[30:33], v[158:161], v[134:137], v[30:33]
	v_mfma_f32_16x16x32_bf16 v[34:37], v[146:149], v[138:141], v[34:37]
	v_mfma_f32_16x16x32_bf16 v[38:41], v[150:153], v[138:141], v[38:41]
	v_mfma_f32_16x16x32_bf16 v[42:45], v[154:157], v[138:141], v[42:45]
	v_mfma_f32_16x16x32_bf16 v[46:49], v[158:161], v[138:141], v[46:49]
	v_mfma_f32_16x16x32_bf16 v[50:53], v[146:149], v[142:145], v[50:53]
	v_mfma_f32_16x16x32_bf16 v[54:57], v[150:153], v[142:145], v[54:57]
	v_mfma_f32_16x16x32_bf16 v[58:61], v[154:157], v[142:145], v[58:61]
	v_mfma_f32_16x16x32_bf16 v[62:65], v[158:161], v[142:145], v[62:65]
	s_waitcnt vmcnt(10)
	s_waitcnt lgkmcnt(0)
	s_barrier
	v_add_u32_e32 v204, 0x18000, v200
	v_add_u32_e32 v205, 0x18000, v202
	ds_read_b128 v[130:133], v204 offset:0
	ds_read_b128 v[134:137], v204 offset:2048
	ds_read_b128 v[138:141], v204 offset:4096
	ds_read_b128 v[142:145], v204 offset:6144
	ds_read_b128 v[146:149], v205 offset:0
	ds_read_b128 v[150:153], v205 offset:2048
	ds_read_b128 v[154:157], v205 offset:4096
	ds_read_b128 v[158:161], v205 offset:6144
	v_mfma_f32_16x16x32_bf16 v[2:5], v[228:231], v[212:215], v[2:5]
	v_mfma_f32_16x16x32_bf16 v[6:9], v[232:235], v[212:215], v[6:9]
	s_add_u32 m0, s76, 0xc000
	s_nop 0
	global_load_lds_dwordx4 v196, s[68:69]
	v_mfma_f32_16x16x32_bf16 v[10:13], v[236:239], v[212:215], v[10:13]
	v_mfma_f32_16x16x32_bf16 v[14:17], v[240:243], v[212:215], v[14:17]
	s_add_u32 m0, s76, 0xe000
	s_nop 0
	global_load_lds_dwordx4 v197, s[68:69]
	v_mfma_f32_16x16x32_bf16 v[18:21], v[228:231], v[216:219], v[18:21]
	v_mfma_f32_16x16x32_bf16 v[22:25], v[232:235], v[216:219], v[22:25]
	s_add_u32 m0, s76, 0x10000
	s_nop 0
	global_load_lds_dwordx4 v198, s[68:69]
	v_mfma_f32_16x16x32_bf16 v[26:29], v[236:239], v[216:219], v[26:29]
	v_mfma_f32_16x16x32_bf16 v[30:33], v[240:243], v[216:219], v[30:33]
	s_add_u32 m0, s76, 0x12000
	s_nop 0
	global_load_lds_dwordx4 v199, s[68:69]
	v_mfma_f32_16x16x32_bf16 v[34:37], v[228:231], v[220:223], v[34:37]
	v_mfma_f32_16x16x32_bf16 v[38:41], v[232:235], v[220:223], v[38:41]
	s_add_u32 m0, s76, 0x14000
	s_nop 0
	global_load_lds_dwordx4 v196, s[70:71]
	v_mfma_f32_16x16x32_bf16 v[42:45], v[236:239], v[220:223], v[42:45]
	v_mfma_f32_16x16x32_bf16 v[46:49], v[240:243], v[220:223], v[46:49]
	s_add_u32 m0, s76, 0x16000
	s_nop 0
	global_load_lds_dwordx4 v197, s[70:71]
	v_mfma_f32_16x16x32_bf16 v[50:53], v[228:231], v[224:227], v[50:53]
	v_mfma_f32_16x16x32_bf16 v[54:57], v[232:235], v[224:227], v[54:57]
	s_add_u32 s68, s68, 0x80
	s_addc_u32 s69, s69, 0
	s_add_u32 s70, s70, 0x80
	s_addc_u32 s71, s71, 0
	v_mfma_f32_16x16x32_bf16 v[58:61], v[236:239], v[224:227], v[58:61]
	v_mfma_f32_16x16x32_bf16 v[62:65], v[240:243], v[224:227], v[62:65]
	s_waitcnt lgkmcnt(0)
	v_add_u32_e32 v204, 0x18000, v201
	v_add_u32_e32 v205, 0x18000, v203
	ds_read_b128 v[212:215], v204 offset:0
	ds_read_b128 v[216:219], v204 offset:2048
	ds_read_b128 v[220:223], v204 offset:4096
	ds_read_b128 v[224:227], v204 offset:6144
	ds_read_b128 v[228:231], v205 offset:0
	ds_read_b128 v[232:235], v205 offset:2048
	ds_read_b128 v[236:239], v205 offset:4096
	ds_read_b128 v[240:243], v205 offset:6144
	v_mfma_f32_16x16x32_bf16 v[2:5], v[146:149], v[130:133], v[2:5]
	v_mfma_f32_16x16x32_bf16 v[6:9], v[150:153], v[130:133], v[6:9]
	v_add_u32_e32 v170, s39, v192
	global_load_dwordx4 v[90:93], v170, s[14:15]
	v_mfma_f32_16x16x32_bf16 v[10:13], v[154:157], v[130:133], v[10:13]
	v_mfma_f32_16x16x32_bf16 v[14:17], v[158:161], v[130:133], v[14:17]
	v_add_u32_e32 v170, s40, v192
	global_load_dwordx4 v[94:97], v170, s[14:15]
	v_mfma_f32_16x16x32_bf16 v[18:21], v[146:149], v[134:137], v[18:21]
	v_mfma_f32_16x16x32_bf16 v[22:25], v[150:153], v[134:137], v[22:25]
	v_mfma_f32_16x16x32_bf16 v[26:29], v[154:157], v[134:137], v[26:29]
	v_mfma_f32_16x16x32_bf16 v[30:33], v[158:161], v[134:137], v[30:33]
	v_mfma_f32_16x16x32_bf16 v[34:37], v[146:149], v[138:141], v[34:37]
	v_mfma_f32_16x16x32_bf16 v[38:41], v[150:153], v[138:141], v[38:41]
	v_mfma_f32_16x16x32_bf16 v[42:45], v[154:157], v[138:141], v[42:45]
	v_mfma_f32_16x16x32_bf16 v[46:49], v[158:161], v[138:141], v[46:49]
	v_mfma_f32_16x16x32_bf16 v[50:53], v[146:149], v[142:145], v[50:53]
	v_mfma_f32_16x16x32_bf16 v[54:57], v[150:153], v[142:145], v[54:57]
	v_mfma_f32_16x16x32_bf16 v[58:61], v[154:157], v[142:145], v[58:61]
	v_mfma_f32_16x16x32_bf16 v[62:65], v[158:161], v[142:145], v[62:65]
	s_waitcnt vmcnt(10)
	s_waitcnt lgkmcnt(0)
	s_barrier
	v_add_u32_e32 v204, 0x0, v200
	v_add_u32_e32 v205, 0x0, v202
	ds_read_b128 v[130:133], v204 offset:0
	ds_read_b128 v[134:137], v204 offset:2048
	ds_read_b128 v[138:141], v204 offset:4096
	ds_read_b128 v[142:145], v204 offset:6144
	ds_read_b128 v[146:149], v205 offset:0
	ds_read_b128 v[150:153], v205 offset:2048
	ds_read_b128 v[154:157], v205 offset:4096
	ds_read_b128 v[158:161], v205 offset:6144
	v_mfma_f32_16x16x32_bf16 v[2:5], v[228:231], v[212:215], v[2:5]
	v_mfma_f32_16x16x32_bf16 v[6:9], v[232:235], v[212:215], v[6:9]
	s_add_u32 m0, s76, 0x18000
	s_nop 0
	global_load_lds_dwordx4 v196, s[68:69]
	v_mfma_f32_16x16x32_bf16 v[10:13], v[236:239], v[212:215], v[10:13]
	v_mfma_f32_16x16x32_bf16 v[14:17], v[240:243], v[212:215], v[14:17]
	s_add_u32 m0, s76, 0x1a000
	s_nop 0
	global_load_lds_dwordx4 v197, s[68:69]
	v_mfma_f32_16x16x32_bf16 v[18:21], v[228:231], v[216:219], v[18:21]
	v_mfma_f32_16x16x32_bf16 v[22:25], v[232:235], v[216:219], v[22:25]
	s_add_u32 m0, s76, 0x1c000
	s_nop 0
	global_load_lds_dwordx4 v198, s[68:69]
	v_mfma_f32_16x16x32_bf16 v[26:29], v[236:239], v[216:219], v[26:29]
	v_mfma_f32_16x16x32_bf16 v[30:33], v[240:243], v[216:219], v[30:33]
	s_add_u32 m0, s76, 0x1e000
	s_nop 0
	global_load_lds_dwordx4 v199, s[68:69]
	v_mfma_f32_16x16x32_bf16 v[34:37], v[228:231], v[220:223], v[34:37]
	v_mfma_f32_16x16x32_bf16 v[38:41], v[232:235], v[220:223], v[38:41]
	s_add_u32 m0, s76, 0x20000
	s_nop 0
	global_load_lds_dwordx4 v196, s[70:71]
	v_mfma_f32_16x16x32_bf16 v[42:45], v[236:239], v[220:223], v[42:45]
	v_mfma_f32_16x16x32_bf16 v[46:49], v[240:243], v[220:223], v[46:49]
	s_add_u32 m0, s76, 0x22000
	s_nop 0
	global_load_lds_dwordx4 v197, s[70:71]
	v_mfma_f32_16x16x32_bf16 v[50:53], v[228:231], v[224:227], v[50:53]
	v_mfma_f32_16x16x32_bf16 v[54:57], v[232:235], v[224:227], v[54:57]
	s_add_u32 s68, s68, 0x80
	s_addc_u32 s69, s69, 0
	s_add_u32 s70, s70, 0x80
	s_addc_u32 s71, s71, 0
	v_mfma_f32_16x16x32_bf16 v[58:61], v[236:239], v[224:227], v[58:61]
	v_mfma_f32_16x16x32_bf16 v[62:65], v[240:243], v[224:227], v[62:65]
	s_waitcnt lgkmcnt(0)
	v_add_u32_e32 v204, 0x0, v201
	v_add_u32_e32 v205, 0x0, v203
	ds_read_b128 v[212:215], v204 offset:0
	ds_read_b128 v[216:219], v204 offset:2048
	ds_read_b128 v[220:223], v204 offset:4096
	ds_read_b128 v[224:227], v204 offset:6144
	ds_read_b128 v[228:231], v205 offset:0
	ds_read_b128 v[232:235], v205 offset:2048
	ds_read_b128 v[236:239], v205 offset:4096
	ds_read_b128 v[240:243], v205 offset:6144
	v_mfma_f32_16x16x32_bf16 v[2:5], v[146:149], v[130:133], v[2:5]
	v_mfma_f32_16x16x32_bf16 v[6:9], v[150:153], v[130:133], v[6:9]
	global_load_dwordx4 v[98:101], v193, s[14:15]
	v_mfma_f32_16x16x32_bf16 v[10:13], v[154:157], v[130:133], v[10:13]
	v_mfma_f32_16x16x32_bf16 v[14:17], v[158:161], v[130:133], v[14:17]
	v_add_u32_e32 v170, s38, v193
	global_load_dwordx4 v[102:105], v170, s[14:15]
	v_mfma_f32_16x16x32_bf16 v[18:21], v[146:149], v[134:137], v[18:21]
	v_mfma_f32_16x16x32_bf16 v[22:25], v[150:153], v[134:137], v[22:25]
	v_mfma_f32_16x16x32_bf16 v[26:29], v[154:157], v[134:137], v[26:29]
	v_mfma_f32_16x16x32_bf16 v[30:33], v[158:161], v[134:137], v[30:33]
	v_mfma_f32_16x16x32_bf16 v[34:37], v[146:149], v[138:141], v[34:37]
	v_mfma_f32_16x16x32_bf16 v[38:41], v[150:153], v[138:141], v[38:41]
	v_mfma_f32_16x16x32_bf16 v[42:45], v[154:157], v[138:141], v[42:45]
	v_mfma_f32_16x16x32_bf16 v[46:49], v[158:161], v[138:141], v[46:49]
	v_mfma_f32_16x16x32_bf16 v[50:53], v[146:149], v[142:145], v[50:53]
	v_mfma_f32_16x16x32_bf16 v[54:57], v[150:153], v[142:145], v[54:57]
	v_mfma_f32_16x16x32_bf16 v[58:61], v[154:157], v[142:145], v[58:61]
	v_mfma_f32_16x16x32_bf16 v[62:65], v[158:161], v[142:145], v[62:65]
	s_waitcnt vmcnt(10)
	s_waitcnt lgkmcnt(0)
	s_barrier
	v_add_u32_e32 v204, 0xc000, v200
	v_add_u32_e32 v205, 0xc000, v202
	ds_read_b128 v[130:133], v204 offset:0
	ds_read_b128 v[134:137], v204 offset:2048
	ds_read_b128 v[138:141], v204 offset:4096
	ds_read_b128 v[142:145], v204 offset:6144
	ds_read_b128 v[146:149], v205 offset:0
	ds_read_b128 v[150:153], v205 offset:2048
	ds_read_b128 v[154:157], v205 offset:4096
	ds_read_b128 v[158:161], v205 offset:6144
	v_mfma_f32_16x16x32_bf16 v[2:5], v[228:231], v[212:215], v[2:5]
	v_mfma_f32_16x16x32_bf16 v[6:9], v[232:235], v[212:215], v[6:9]
	s_add_u32 m0, s76, 0x0
	s_nop 0
	global_load_lds_dwordx4 v196, s[68:69]
	v_mfma_f32_16x16x32_bf16 v[10:13], v[236:239], v[212:215], v[10:13]
	v_mfma_f32_16x16x32_bf16 v[14:17], v[240:243], v[212:215], v[14:17]
	s_add_u32 m0, s76, 0x2000
	s_nop 0
	global_load_lds_dwordx4 v197, s[68:69]
	v_mfma_f32_16x16x32_bf16 v[18:21], v[228:231], v[216:219], v[18:21]
	v_mfma_f32_16x16x32_bf16 v[22:25], v[232:235], v[216:219], v[22:25]
	s_add_u32 m0, s76, 0x4000
	s_nop 0
	global_load_lds_dwordx4 v198, s[68:69]
	v_mfma_f32_16x16x32_bf16 v[26:29], v[236:239], v[216:219], v[26:29]
	v_mfma_f32_16x16x32_bf16 v[30:33], v[240:243], v[216:219], v[30:33]
	s_add_u32 m0, s76, 0x6000
	s_nop 0
	global_load_lds_dwordx4 v199, s[68:69]
	v_mfma_f32_16x16x32_bf16 v[34:37], v[228:231], v[220:223], v[34:37]
	v_mfma_f32_16x16x32_bf16 v[38:41], v[232:235], v[220:223], v[38:41]
	s_add_u32 m0, s76, 0x8000
	s_nop 0
	global_load_lds_dwordx4 v196, s[70:71]
	v_mfma_f32_16x16x32_bf16 v[42:45], v[236:239], v[220:223], v[42:45]
	v_mfma_f32_16x16x32_bf16 v[46:49], v[240:243], v[220:223], v[46:49]
	s_add_u32 m0, s76, 0xa000
	s_nop 0
	global_load_lds_dwordx4 v197, s[70:71]
	v_mfma_f32_16x16x32_bf16 v[50:53], v[228:231], v[224:227], v[50:53]
	v_mfma_f32_16x16x32_bf16 v[54:57], v[232:235], v[224:227], v[54:57]
	s_add_u32 s68, s68, 0x80
	s_addc_u32 s69, s69, 0
	s_add_u32 s70, s70, 0x80
	s_addc_u32 s71, s71, 0
	v_mfma_f32_16x16x32_bf16 v[58:61], v[236:239], v[224:227], v[58:61]
	v_mfma_f32_16x16x32_bf16 v[62:65], v[240:243], v[224:227], v[62:65]
	s_waitcnt lgkmcnt(0)
	v_add_u32_e32 v204, 0xc000, v201
	v_add_u32_e32 v205, 0xc000, v203
	ds_read_b128 v[212:215], v204 offset:0
	ds_read_b128 v[216:219], v204 offset:2048
	ds_read_b128 v[220:223], v204 offset:4096
	ds_read_b128 v[224:227], v204 offset:6144
	ds_read_b128 v[228:231], v205 offset:0
	ds_read_b128 v[232:235], v205 offset:2048
	ds_read_b128 v[236:239], v205 offset:4096
	ds_read_b128 v[240:243], v205 offset:6144
	v_mfma_f32_16x16x32_bf16 v[2:5], v[146:149], v[130:133], v[2:5]
	v_mfma_f32_16x16x32_bf16 v[6:9], v[150:153], v[130:133], v[6:9]
	v_add_u32_e32 v170, s39, v193
	global_load_dwordx4 v[106:109], v170, s[14:15]
	v_mfma_f32_16x16x32_bf16 v[10:13], v[154:157], v[130:133], v[10:13]
	v_mfma_f32_16x16x32_bf16 v[14:17], v[158:161], v[130:133], v[14:17]
	v_add_u32_e32 v170, s40, v193
	global_load_dwordx4 v[110:113], v170, s[14:15]
	v_mfma_f32_16x16x32_bf16 v[18:21], v[146:149], v[134:137], v[18:21]
	v_mfma_f32_16x16x32_bf16 v[22:25], v[150:153], v[134:137], v[22:25]
	v_mfma_f32_16x16x32_bf16 v[26:29], v[154:157], v[134:137], v[26:29]
	v_mfma_f32_16x16x32_bf16 v[30:33], v[158:161], v[134:137], v[30:33]
	v_mfma_f32_16x16x32_bf16 v[34:37], v[146:149], v[138:141], v[34:37]
	v_mfma_f32_16x16x32_bf16 v[38:41], v[150:153], v[138:141], v[38:41]
	v_mfma_f32_16x16x32_bf16 v[42:45], v[154:157], v[138:141], v[42:45]
	v_mfma_f32_16x16x32_bf16 v[46:49], v[158:161], v[138:141], v[46:49]
	v_mfma_f32_16x16x32_bf16 v[50:53], v[146:149], v[142:145], v[50:53]
	v_mfma_f32_16x16x32_bf16 v[54:57], v[150:153], v[142:145], v[54:57]
	v_mfma_f32_16x16x32_bf16 v[58:61], v[154:157], v[142:145], v[58:61]
	v_mfma_f32_16x16x32_bf16 v[62:65], v[158:161], v[142:145], v[62:65]
	s_waitcnt vmcnt(10)
	s_waitcnt lgkmcnt(0)
	s_barrier
	v_add_u32_e32 v204, 0x18000, v200
	v_add_u32_e32 v205, 0x18000, v202
	ds_read_b128 v[130:133], v204 offset:0
	ds_read_b128 v[134:137], v204 offset:2048
	ds_read_b128 v[138:141], v204 offset:4096
	ds_read_b128 v[142:145], v204 offset:6144
	ds_read_b128 v[146:149], v205 offset:0
	ds_read_b128 v[150:153], v205 offset:2048
	ds_read_b128 v[154:157], v205 offset:4096
	ds_read_b128 v[158:161], v205 offset:6144
	v_mfma_f32_16x16x32_bf16 v[2:5], v[228:231], v[212:215], v[2:5]
	v_mfma_f32_16x16x32_bf16 v[6:9], v[232:235], v[212:215], v[6:9]
	s_add_u32 m0, s76, 0xc000
	s_nop 0
	global_load_lds_dwordx4 v196, s[68:69]
	v_mfma_f32_16x16x32_bf16 v[10:13], v[236:239], v[212:215], v[10:13]
	v_mfma_f32_16x16x32_bf16 v[14:17], v[240:243], v[212:215], v[14:17]
	s_add_u32 m0, s76, 0xe000
	s_nop 0
	global_load_lds_dwordx4 v197, s[68:69]
	v_mfma_f32_16x16x32_bf16 v[18:21], v[228:231], v[216:219], v[18:21]
	v_mfma_f32_16x16x32_bf16 v[22:25], v[232:235], v[216:219], v[22:25]
	s_add_u32 m0, s76, 0x10000
	s_nop 0
	global_load_lds_dwordx4 v198, s[68:69]
	v_mfma_f32_16x16x32_bf16 v[26:29], v[236:239], v[216:219], v[26:29]
	v_mfma_f32_16x16x32_bf16 v[30:33], v[240:243], v[216:219], v[30:33]
	s_add_u32 m0, s76, 0x12000
	s_nop 0
	global_load_lds_dwordx4 v199, s[68:69]
	v_mfma_f32_16x16x32_bf16 v[34:37], v[228:231], v[220:223], v[34:37]
	v_mfma_f32_16x16x32_bf16 v[38:41], v[232:235], v[220:223], v[38:41]
	s_add_u32 m0, s76, 0x14000
	s_nop 0
	global_load_lds_dwordx4 v196, s[70:71]
	v_mfma_f32_16x16x32_bf16 v[42:45], v[236:239], v[220:223], v[42:45]
	v_mfma_f32_16x16x32_bf16 v[46:49], v[240:243], v[220:223], v[46:49]
	s_add_u32 m0, s76, 0x16000
	s_nop 0
	global_load_lds_dwordx4 v197, s[70:71]
	v_mfma_f32_16x16x32_bf16 v[50:53], v[228:231], v[224:227], v[50:53]
	v_mfma_f32_16x16x32_bf16 v[54:57], v[232:235], v[224:227], v[54:57]
	s_add_u32 s68, s68, 0x80
	s_addc_u32 s69, s69, 0
	s_add_u32 s70, s70, 0x80
	s_addc_u32 s71, s71, 0
	v_mfma_f32_16x16x32_bf16 v[58:61], v[236:239], v[224:227], v[58:61]
	v_mfma_f32_16x16x32_bf16 v[62:65], v[240:243], v[224:227], v[62:65]
	s_waitcnt lgkmcnt(0)
	v_add_u32_e32 v204, 0x18000, v201
	v_add_u32_e32 v205, 0x18000, v203
	ds_read_b128 v[212:215], v204 offset:0
	ds_read_b128 v[216:219], v204 offset:2048
	ds_read_b128 v[220:223], v204 offset:4096
	ds_read_b128 v[224:227], v204 offset:6144
	ds_read_b128 v[228:231], v205 offset:0
	ds_read_b128 v[232:235], v205 offset:2048
	ds_read_b128 v[236:239], v205 offset:4096
	ds_read_b128 v[240:243], v205 offset:6144
	v_mfma_f32_16x16x32_bf16 v[2:5], v[146:149], v[130:133], v[2:5]
	v_mfma_f32_16x16x32_bf16 v[6:9], v[150:153], v[130:133], v[6:9]
	global_load_dwordx4 v[114:117], v244, s[14:15]
	v_mfma_f32_16x16x32_bf16 v[10:13], v[154:157], v[130:133], v[10:13]
	v_mfma_f32_16x16x32_bf16 v[14:17], v[158:161], v[130:133], v[14:17]
	v_add_u32_e32 v170, s38, v244
	global_load_dwordx4 v[118:121], v170, s[14:15]
	v_mfma_f32_16x16x32_bf16 v[18:21], v[146:149], v[134:137], v[18:21]
	v_mfma_f32_16x16x32_bf16 v[22:25], v[150:153], v[134:137], v[22:25]
	v_mfma_f32_16x16x32_bf16 v[26:29], v[154:157], v[134:137], v[26:29]
	v_mfma_f32_16x16x32_bf16 v[30:33], v[158:161], v[134:137], v[30:33]
	v_mfma_f32_16x16x32_bf16 v[34:37], v[146:149], v[138:141], v[34:37]
	v_mfma_f32_16x16x32_bf16 v[38:41], v[150:153], v[138:141], v[38:41]
	v_mfma_f32_16x16x32_bf16 v[42:45], v[154:157], v[138:141], v[42:45]
	v_mfma_f32_16x16x32_bf16 v[46:49], v[158:161], v[138:141], v[46:49]
	v_mfma_f32_16x16x32_bf16 v[50:53], v[146:149], v[142:145], v[50:53]
	v_mfma_f32_16x16x32_bf16 v[54:57], v[150:153], v[142:145], v[54:57]
	v_mfma_f32_16x16x32_bf16 v[58:61], v[154:157], v[142:145], v[58:61]
	v_mfma_f32_16x16x32_bf16 v[62:65], v[158:161], v[142:145], v[62:65]
	s_waitcnt vmcnt(10)
	s_waitcnt lgkmcnt(0)
	s_barrier
	v_add_u32_e32 v204, 0x0, v200
	v_add_u32_e32 v205, 0x0, v202
	ds_read_b128 v[130:133], v204 offset:0
	ds_read_b128 v[134:137], v204 offset:2048
	ds_read_b128 v[138:141], v204 offset:4096
	ds_read_b128 v[142:145], v204 offset:6144
	ds_read_b128 v[146:149], v205 offset:0
	ds_read_b128 v[150:153], v205 offset:2048
	ds_read_b128 v[154:157], v205 offset:4096
	ds_read_b128 v[158:161], v205 offset:6144
	v_mfma_f32_16x16x32_bf16 v[2:5], v[228:231], v[212:215], v[2:5]
	v_mfma_f32_16x16x32_bf16 v[6:9], v[232:235], v[212:215], v[6:9]
	s_add_u32 m0, s76, 0x18000
	s_nop 0
	global_load_lds_dwordx4 v196, s[68:69]
	v_mfma_f32_16x16x32_bf16 v[10:13], v[236:239], v[212:215], v[10:13]
	v_mfma_f32_16x16x32_bf16 v[14:17], v[240:243], v[212:215], v[14:17]
	s_add_u32 m0, s76, 0x1a000
	s_nop 0
	global_load_lds_dwordx4 v197, s[68:69]
	v_mfma_f32_16x16x32_bf16 v[18:21], v[228:231], v[216:219], v[18:21]
	v_mfma_f32_16x16x32_bf16 v[22:25], v[232:235], v[216:219], v[22:25]
	s_add_u32 m0, s76, 0x1c000
	s_nop 0
	global_load_lds_dwordx4 v198, s[68:69]
	v_mfma_f32_16x16x32_bf16 v[26:29], v[236:239], v[216:219], v[26:29]
	v_mfma_f32_16x16x32_bf16 v[30:33], v[240:243], v[216:219], v[30:33]
	s_add_u32 m0, s76, 0x1e000
	s_nop 0
	global_load_lds_dwordx4 v199, s[68:69]
	v_mfma_f32_16x16x32_bf16 v[34:37], v[228:231], v[220:223], v[34:37]
	v_mfma_f32_16x16x32_bf16 v[38:41], v[232:235], v[220:223], v[38:41]
	s_add_u32 m0, s76, 0x20000
	s_nop 0
	global_load_lds_dwordx4 v196, s[70:71]
	v_mfma_f32_16x16x32_bf16 v[42:45], v[236:239], v[220:223], v[42:45]
	v_mfma_f32_16x16x32_bf16 v[46:49], v[240:243], v[220:223], v[46:49]
	s_add_u32 m0, s76, 0x22000
	s_nop 0
	global_load_lds_dwordx4 v197, s[70:71]
	v_mfma_f32_16x16x32_bf16 v[50:53], v[228:231], v[224:227], v[50:53]
	v_mfma_f32_16x16x32_bf16 v[54:57], v[232:235], v[224:227], v[54:57]
	s_add_u32 s68, s68, 0x80
	s_addc_u32 s69, s69, 0
	s_add_u32 s70, s70, 0x80
	s_addc_u32 s71, s71, 0
	v_mfma_f32_16x16x32_bf16 v[58:61], v[236:239], v[224:227], v[58:61]
	v_mfma_f32_16x16x32_bf16 v[62:65], v[240:243], v[224:227], v[62:65]
	s_waitcnt lgkmcnt(0)
	v_add_u32_e32 v204, 0x0, v201
	v_add_u32_e32 v205, 0x0, v203
	ds_read_b128 v[212:215], v204 offset:0
	ds_read_b128 v[216:219], v204 offset:2048
	ds_read_b128 v[220:223], v204 offset:4096
	ds_read_b128 v[224:227], v204 offset:6144
	ds_read_b128 v[228:231], v205 offset:0
	ds_read_b128 v[232:235], v205 offset:2048
	ds_read_b128 v[236:239], v205 offset:4096
	ds_read_b128 v[240:243], v205 offset:6144
	v_mfma_f32_16x16x32_bf16 v[2:5], v[146:149], v[130:133], v[2:5]
	v_mfma_f32_16x16x32_bf16 v[6:9], v[150:153], v[130:133], v[6:9]
	v_add_u32_e32 v170, s39, v244
	global_load_dwordx4 v[122:125], v170, s[14:15]
	v_mfma_f32_16x16x32_bf16 v[10:13], v[154:157], v[130:133], v[10:13]
	v_mfma_f32_16x16x32_bf16 v[14:17], v[158:161], v[130:133], v[14:17]
	v_add_u32_e32 v170, s40, v244
	global_load_dwordx4 v[126:129], v170, s[14:15]
	v_mfma_f32_16x16x32_bf16 v[18:21], v[146:149], v[134:137], v[18:21]
	v_mfma_f32_16x16x32_bf16 v[22:25], v[150:153], v[134:137], v[22:25]
	v_mfma_f32_16x16x32_bf16 v[26:29], v[154:157], v[134:137], v[26:29]
	v_mfma_f32_16x16x32_bf16 v[30:33], v[158:161], v[134:137], v[30:33]
	v_mfma_f32_16x16x32_bf16 v[34:37], v[146:149], v[138:141], v[34:37]
	v_mfma_f32_16x16x32_bf16 v[38:41], v[150:153], v[138:141], v[38:41]
	v_mfma_f32_16x16x32_bf16 v[42:45], v[154:157], v[138:141], v[42:45]
	v_mfma_f32_16x16x32_bf16 v[46:49], v[158:161], v[138:141], v[46:49]
	v_mfma_f32_16x16x32_bf16 v[50:53], v[146:149], v[142:145], v[50:53]
	v_mfma_f32_16x16x32_bf16 v[54:57], v[150:153], v[142:145], v[54:57]
	v_mfma_f32_16x16x32_bf16 v[58:61], v[154:157], v[142:145], v[58:61]
	v_mfma_f32_16x16x32_bf16 v[62:65], v[158:161], v[142:145], v[62:65]
	s_waitcnt vmcnt(10)
	s_waitcnt lgkmcnt(0)
	s_barrier
	v_add_u32_e32 v204, 0xc000, v200
	v_add_u32_e32 v205, 0xc000, v202
	ds_read_b128 v[130:133], v204 offset:0
	ds_read_b128 v[134:137], v204 offset:2048
	ds_read_b128 v[138:141], v204 offset:4096
	ds_read_b128 v[142:145], v204 offset:6144
	ds_read_b128 v[146:149], v205 offset:0
	ds_read_b128 v[150:153], v205 offset:2048
	ds_read_b128 v[154:157], v205 offset:4096
	ds_read_b128 v[158:161], v205 offset:6144
	v_mfma_f32_16x16x32_bf16 v[2:5], v[228:231], v[212:215], v[2:5]
	v_mfma_f32_16x16x32_bf16 v[6:9], v[232:235], v[212:215], v[6:9]
	s_add_u32 m0, s76, 0x0
	s_nop 0
	global_load_lds_dwordx4 v196, s[68:69]
	v_mfma_f32_16x16x32_bf16 v[10:13], v[236:239], v[212:215], v[10:13]
	v_mfma_f32_16x16x32_bf16 v[14:17], v[240:243], v[212:215], v[14:17]
	s_add_u32 m0, s76, 0x2000
	s_nop 0
	global_load_lds_dwordx4 v197, s[68:69]
	v_mfma_f32_16x16x32_bf16 v[18:21], v[228:231], v[216:219], v[18:21]
	v_mfma_f32_16x16x32_bf16 v[22:25], v[232:235], v[216:219], v[22:25]
	s_add_u32 m0, s76, 0x4000
	s_nop 0
	global_load_lds_dwordx4 v198, s[68:69]
	v_mfma_f32_16x16x32_bf16 v[26:29], v[236:239], v[216:219], v[26:29]
	v_mfma_f32_16x16x32_bf16 v[30:33], v[240:243], v[216:219], v[30:33]
	s_add_u32 m0, s76, 0x6000
	s_nop 0
	global_load_lds_dwordx4 v199, s[68:69]
	v_mfma_f32_16x16x32_bf16 v[34:37], v[228:231], v[220:223], v[34:37]
	v_mfma_f32_16x16x32_bf16 v[38:41], v[232:235], v[220:223], v[38:41]
	s_add_u32 m0, s76, 0x8000
	s_nop 0
	global_load_lds_dwordx4 v196, s[70:71]
	v_mfma_f32_16x16x32_bf16 v[42:45], v[236:239], v[220:223], v[42:45]
	v_mfma_f32_16x16x32_bf16 v[46:49], v[240:243], v[220:223], v[46:49]
	s_add_u32 m0, s76, 0xa000
	s_nop 0
	global_load_lds_dwordx4 v197, s[70:71]
	v_mfma_f32_16x16x32_bf16 v[50:53], v[228:231], v[224:227], v[50:53]
	v_mfma_f32_16x16x32_bf16 v[54:57], v[232:235], v[224:227], v[54:57]
	s_add_u32 s68, s68, 0x80
	s_addc_u32 s69, s69, 0
	s_add_u32 s70, s70, 0x80
	s_addc_u32 s71, s71, 0
	v_mfma_f32_16x16x32_bf16 v[58:61], v[236:239], v[224:227], v[58:61]
	v_mfma_f32_16x16x32_bf16 v[62:65], v[240:243], v[224:227], v[62:65]
	s_waitcnt lgkmcnt(0)
	v_add_u32_e32 v204, 0xc000, v201
	v_add_u32_e32 v205, 0xc000, v203
	ds_read_b128 v[212:215], v204 offset:0
	ds_read_b128 v[216:219], v204 offset:2048
	ds_read_b128 v[220:223], v204 offset:4096
	ds_read_b128 v[224:227], v204 offset:6144
	ds_read_b128 v[228:231], v205 offset:0
	ds_read_b128 v[232:235], v205 offset:2048
	ds_read_b128 v[236:239], v205 offset:4096
	ds_read_b128 v[240:243], v205 offset:6144
	v_mfma_f32_16x16x32_bf16 v[2:5], v[146:149], v[130:133], v[2:5]
	v_mfma_f32_16x16x32_bf16 v[6:9], v[150:153], v[130:133], v[6:9]
	v_mfma_f32_16x16x32_bf16 v[10:13], v[154:157], v[130:133], v[10:13]
	v_mfma_f32_16x16x32_bf16 v[14:17], v[158:161], v[130:133], v[14:17]
	v_mfma_f32_16x16x32_bf16 v[18:21], v[146:149], v[134:137], v[18:21]
	v_mfma_f32_16x16x32_bf16 v[22:25], v[150:153], v[134:137], v[22:25]
	v_mfma_f32_16x16x32_bf16 v[26:29], v[154:157], v[134:137], v[26:29]
	v_mfma_f32_16x16x32_bf16 v[30:33], v[158:161], v[134:137], v[30:33]
	v_mfma_f32_16x16x32_bf16 v[34:37], v[146:149], v[138:141], v[34:37]
	v_mfma_f32_16x16x32_bf16 v[38:41], v[150:153], v[138:141], v[38:41]
	v_mfma_f32_16x16x32_bf16 v[42:45], v[154:157], v[138:141], v[42:45]
	v_mfma_f32_16x16x32_bf16 v[46:49], v[158:161], v[138:141], v[46:49]
	v_mfma_f32_16x16x32_bf16 v[50:53], v[146:149], v[142:145], v[50:53]
	v_mfma_f32_16x16x32_bf16 v[54:57], v[150:153], v[142:145], v[54:57]
	v_mfma_f32_16x16x32_bf16 v[58:61], v[154:157], v[142:145], v[58:61]
	v_mfma_f32_16x16x32_bf16 v[62:65], v[158:161], v[142:145], v[62:65]
	s_waitcnt vmcnt(8)
	s_waitcnt lgkmcnt(0)
	s_barrier
	v_add_u32_e32 v204, 0x18000, v200
	v_add_u32_e32 v205, 0x18000, v202
	ds_read_b128 v[130:133], v204 offset:0
	ds_read_b128 v[134:137], v204 offset:2048
	ds_read_b128 v[138:141], v204 offset:4096
	ds_read_b128 v[142:145], v204 offset:6144
	ds_read_b128 v[146:149], v205 offset:0
	ds_read_b128 v[150:153], v205 offset:2048
	ds_read_b128 v[154:157], v205 offset:4096
	ds_read_b128 v[158:161], v205 offset:6144
	v_mfma_f32_16x16x32_bf16 v[2:5], v[228:231], v[212:215], v[2:5]
	v_mfma_f32_16x16x32_bf16 v[6:9], v[232:235], v[212:215], v[6:9]
	s_add_u32 m0, s76, 0xc000
	s_nop 0
	global_load_lds_dwordx4 v196, s[68:69]
	v_mfma_f32_16x16x32_bf16 v[10:13], v[236:239], v[212:215], v[10:13]
	v_mfma_f32_16x16x32_bf16 v[14:17], v[240:243], v[212:215], v[14:17]
	s_add_u32 m0, s76, 0xe000
	s_nop 0
	global_load_lds_dwordx4 v197, s[68:69]
	v_mfma_f32_16x16x32_bf16 v[18:21], v[228:231], v[216:219], v[18:21]
	v_mfma_f32_16x16x32_bf16 v[22:25], v[232:235], v[216:219], v[22:25]
	s_add_u32 m0, s76, 0x10000
	s_nop 0
	global_load_lds_dwordx4 v198, s[68:69]
	v_mfma_f32_16x16x32_bf16 v[26:29], v[236:239], v[216:219], v[26:29]
	v_mfma_f32_16x16x32_bf16 v[30:33], v[240:243], v[216:219], v[30:33]
	s_add_u32 m0, s76, 0x12000
	s_nop 0
	global_load_lds_dwordx4 v199, s[68:69]
	v_mfma_f32_16x16x32_bf16 v[34:37], v[228:231], v[220:223], v[34:37]
	v_mfma_f32_16x16x32_bf16 v[38:41], v[232:235], v[220:223], v[38:41]
	s_add_u32 m0, s76, 0x14000
	s_nop 0
	global_load_lds_dwordx4 v196, s[70:71]
	v_mfma_f32_16x16x32_bf16 v[42:45], v[236:239], v[220:223], v[42:45]
	v_mfma_f32_16x16x32_bf16 v[46:49], v[240:243], v[220:223], v[46:49]
	s_add_u32 m0, s76, 0x16000
	s_nop 0
	global_load_lds_dwordx4 v197, s[70:71]
	v_mfma_f32_16x16x32_bf16 v[50:53], v[228:231], v[224:227], v[50:53]
	v_mfma_f32_16x16x32_bf16 v[54:57], v[232:235], v[224:227], v[54:57]
	s_add_u32 s68, s68, 0x80
	s_addc_u32 s69, s69, 0
	s_add_u32 s70, s70, 0x80
	s_addc_u32 s71, s71, 0
	v_mfma_f32_16x16x32_bf16 v[58:61], v[236:239], v[224:227], v[58:61]
	v_mfma_f32_16x16x32_bf16 v[62:65], v[240:243], v[224:227], v[62:65]
	s_waitcnt lgkmcnt(0)
	v_add_u32_e32 v204, 0x18000, v201
	v_add_u32_e32 v205, 0x18000, v203
	ds_read_b128 v[212:215], v204 offset:0
	ds_read_b128 v[216:219], v204 offset:2048
	ds_read_b128 v[220:223], v204 offset:4096
	ds_read_b128 v[224:227], v204 offset:6144
	ds_read_b128 v[228:231], v205 offset:0
	ds_read_b128 v[232:235], v205 offset:2048
	ds_read_b128 v[236:239], v205 offset:4096
	ds_read_b128 v[240:243], v205 offset:6144
	v_mfma_f32_16x16x32_bf16 v[2:5], v[146:149], v[130:133], v[2:5]
	v_mfma_f32_16x16x32_bf16 v[6:9], v[150:153], v[130:133], v[6:9]
	v_mfma_f32_16x16x32_bf16 v[10:13], v[154:157], v[130:133], v[10:13]
	v_mfma_f32_16x16x32_bf16 v[14:17], v[158:161], v[130:133], v[14:17]
	v_mfma_f32_16x16x32_bf16 v[18:21], v[146:149], v[134:137], v[18:21]
	v_mfma_f32_16x16x32_bf16 v[22:25], v[150:153], v[134:137], v[22:25]
	v_mfma_f32_16x16x32_bf16 v[26:29], v[154:157], v[134:137], v[26:29]
	v_mfma_f32_16x16x32_bf16 v[30:33], v[158:161], v[134:137], v[30:33]
	v_mfma_f32_16x16x32_bf16 v[34:37], v[146:149], v[138:141], v[34:37]
	v_mfma_f32_16x16x32_bf16 v[38:41], v[150:153], v[138:141], v[38:41]
	v_mfma_f32_16x16x32_bf16 v[42:45], v[154:157], v[138:141], v[42:45]
	v_mfma_f32_16x16x32_bf16 v[46:49], v[158:161], v[138:141], v[46:49]
	v_mfma_f32_16x16x32_bf16 v[50:53], v[146:149], v[142:145], v[50:53]
	v_mfma_f32_16x16x32_bf16 v[54:57], v[150:153], v[142:145], v[54:57]
	v_mfma_f32_16x16x32_bf16 v[58:61], v[154:157], v[142:145], v[58:61]
	v_mfma_f32_16x16x32_bf16 v[62:65], v[158:161], v[142:145], v[62:65]
	s_waitcnt vmcnt(6)
	s_waitcnt lgkmcnt(0)
	s_barrier
	v_add_u32_e32 v204, 0x0, v200
	v_add_u32_e32 v205, 0x0, v202
	ds_read_b128 v[130:133], v204 offset:0
	ds_read_b128 v[134:137], v204 offset:2048
	ds_read_b128 v[138:141], v204 offset:4096
	ds_read_b128 v[142:145], v204 offset:6144
	ds_read_b128 v[146:149], v205 offset:0
	ds_read_b128 v[150:153], v205 offset:2048
	ds_read_b128 v[154:157], v205 offset:4096
	ds_read_b128 v[158:161], v205 offset:6144
	v_mfma_f32_16x16x32_bf16 v[2:5], v[228:231], v[212:215], v[2:5]
	v_mfma_f32_16x16x32_bf16 v[6:9], v[232:235], v[212:215], v[6:9]
	s_add_u32 m0, s76, 0x18000
	s_nop 0
	global_load_lds_dwordx4 v196, s[68:69]
	v_mfma_f32_16x16x32_bf16 v[10:13], v[236:239], v[212:215], v[10:13]
	v_mfma_f32_16x16x32_bf16 v[14:17], v[240:243], v[212:215], v[14:17]
	s_add_u32 m0, s76, 0x1a000
	s_nop 0
	global_load_lds_dwordx4 v197, s[68:69]
	v_mfma_f32_16x16x32_bf16 v[18:21], v[228:231], v[216:219], v[18:21]
	v_mfma_f32_16x16x32_bf16 v[22:25], v[232:235], v[216:219], v[22:25]
	s_add_u32 m0, s76, 0x1c000
	s_nop 0
	global_load_lds_dwordx4 v198, s[68:69]
	v_mfma_f32_16x16x32_bf16 v[26:29], v[236:239], v[216:219], v[26:29]
	v_mfma_f32_16x16x32_bf16 v[30:33], v[240:243], v[216:219], v[30:33]
	s_add_u32 m0, s76, 0x1e000
	s_nop 0
	global_load_lds_dwordx4 v199, s[68:69]
	v_mfma_f32_16x16x32_bf16 v[34:37], v[228:231], v[220:223], v[34:37]
	v_mfma_f32_16x16x32_bf16 v[38:41], v[232:235], v[220:223], v[38:41]
	s_add_u32 m0, s76, 0x20000
	s_nop 0
	global_load_lds_dwordx4 v196, s[70:71]
	v_mfma_f32_16x16x32_bf16 v[42:45], v[236:239], v[220:223], v[42:45]
	v_mfma_f32_16x16x32_bf16 v[46:49], v[240:243], v[220:223], v[46:49]
	s_add_u32 m0, s76, 0x22000
	s_nop 0
	global_load_lds_dwordx4 v197, s[70:71]
	v_mfma_f32_16x16x32_bf16 v[50:53], v[228:231], v[224:227], v[50:53]
	v_mfma_f32_16x16x32_bf16 v[54:57], v[232:235], v[224:227], v[54:57]
	s_add_u32 s68, s68, 0x80
	s_addc_u32 s69, s69, 0
	s_add_u32 s70, s70, 0x80
	s_addc_u32 s71, s71, 0
	v_mfma_f32_16x16x32_bf16 v[58:61], v[236:239], v[224:227], v[58:61]
	v_mfma_f32_16x16x32_bf16 v[62:65], v[240:243], v[224:227], v[62:65]
	s_waitcnt lgkmcnt(0)
	v_add_u32_e32 v204, 0x0, v201
	v_add_u32_e32 v205, 0x0, v203
	ds_read_b128 v[212:215], v204 offset:0
	ds_read_b128 v[216:219], v204 offset:2048
	ds_read_b128 v[220:223], v204 offset:4096
	ds_read_b128 v[224:227], v204 offset:6144
	ds_read_b128 v[228:231], v205 offset:0
	ds_read_b128 v[232:235], v205 offset:2048
	ds_read_b128 v[236:239], v205 offset:4096
	ds_read_b128 v[240:243], v205 offset:6144
	v_mfma_f32_16x16x32_bf16 v[2:5], v[146:149], v[130:133], v[2:5]
	v_mfma_f32_16x16x32_bf16 v[6:9], v[150:153], v[130:133], v[6:9]
	v_mfma_f32_16x16x32_bf16 v[10:13], v[154:157], v[130:133], v[10:13]
	v_mfma_f32_16x16x32_bf16 v[14:17], v[158:161], v[130:133], v[14:17]
	v_mfma_f32_16x16x32_bf16 v[18:21], v[146:149], v[134:137], v[18:21]
	v_mfma_f32_16x16x32_bf16 v[22:25], v[150:153], v[134:137], v[22:25]
	v_mfma_f32_16x16x32_bf16 v[26:29], v[154:157], v[134:137], v[26:29]
	v_mfma_f32_16x16x32_bf16 v[30:33], v[158:161], v[134:137], v[30:33]
	v_mfma_f32_16x16x32_bf16 v[34:37], v[146:149], v[138:141], v[34:37]
	v_mfma_f32_16x16x32_bf16 v[38:41], v[150:153], v[138:141], v[38:41]
	v_mfma_f32_16x16x32_bf16 v[42:45], v[154:157], v[138:141], v[42:45]
	v_mfma_f32_16x16x32_bf16 v[46:49], v[158:161], v[138:141], v[46:49]
	v_mfma_f32_16x16x32_bf16 v[50:53], v[146:149], v[142:145], v[50:53]
	v_mfma_f32_16x16x32_bf16 v[54:57], v[150:153], v[142:145], v[54:57]
	v_mfma_f32_16x16x32_bf16 v[58:61], v[154:157], v[142:145], v[58:61]
	v_mfma_f32_16x16x32_bf16 v[62:65], v[158:161], v[142:145], v[62:65]
	s_waitcnt vmcnt(6)
	s_waitcnt lgkmcnt(0)
	s_barrier
	v_add_u32_e32 v204, 0xc000, v200
	v_add_u32_e32 v205, 0xc000, v202
	ds_read_b128 v[130:133], v204 offset:0
	ds_read_b128 v[134:137], v204 offset:2048
	ds_read_b128 v[138:141], v204 offset:4096
	ds_read_b128 v[142:145], v204 offset:6144
	ds_read_b128 v[146:149], v205 offset:0
	ds_read_b128 v[150:153], v205 offset:2048
	ds_read_b128 v[154:157], v205 offset:4096
	ds_read_b128 v[158:161], v205 offset:6144
	v_mfma_f32_16x16x32_bf16 v[2:5], v[228:231], v[212:215], v[2:5]
	v_mfma_f32_16x16x32_bf16 v[6:9], v[232:235], v[212:215], v[6:9]
	s_add_u32 m0, s76, 0x0
	s_nop 0
	global_load_lds_dwordx4 v196, s[68:69]
	v_mfma_f32_16x16x32_bf16 v[10:13], v[236:239], v[212:215], v[10:13]
	v_mfma_f32_16x16x32_bf16 v[14:17], v[240:243], v[212:215], v[14:17]
	s_add_u32 m0, s76, 0x2000
	s_nop 0
	global_load_lds_dwordx4 v197, s[68:69]
	v_mfma_f32_16x16x32_bf16 v[18:21], v[228:231], v[216:219], v[18:21]
	v_mfma_f32_16x16x32_bf16 v[22:25], v[232:235], v[216:219], v[22:25]
	s_add_u32 m0, s76, 0x4000
	s_nop 0
	global_load_lds_dwordx4 v198, s[68:69]
	v_mfma_f32_16x16x32_bf16 v[26:29], v[236:239], v[216:219], v[26:29]
	v_mfma_f32_16x16x32_bf16 v[30:33], v[240:243], v[216:219], v[30:33]
	s_add_u32 m0, s76, 0x6000
	s_nop 0
	global_load_lds_dwordx4 v199, s[68:69]
	v_mfma_f32_16x16x32_bf16 v[34:37], v[228:231], v[220:223], v[34:37]
	v_mfma_f32_16x16x32_bf16 v[38:41], v[232:235], v[220:223], v[38:41]
	s_add_u32 m0, s76, 0x8000
	s_nop 0
	global_load_lds_dwordx4 v196, s[70:71]
	v_mfma_f32_16x16x32_bf16 v[42:45], v[236:239], v[220:223], v[42:45]
	v_mfma_f32_16x16x32_bf16 v[46:49], v[240:243], v[220:223], v[46:49]
	s_add_u32 m0, s76, 0xa000
	s_nop 0
	global_load_lds_dwordx4 v197, s[70:71]
	v_mfma_f32_16x16x32_bf16 v[50:53], v[228:231], v[224:227], v[50:53]
	v_mfma_f32_16x16x32_bf16 v[54:57], v[232:235], v[224:227], v[54:57]
	s_add_u32 s68, s68, 0x80
	s_addc_u32 s69, s69, 0
	s_add_u32 s70, s70, 0x80
	s_addc_u32 s71, s71, 0
	v_mfma_f32_16x16x32_bf16 v[58:61], v[236:239], v[224:227], v[58:61]
	v_mfma_f32_16x16x32_bf16 v[62:65], v[240:243], v[224:227], v[62:65]
	s_waitcnt lgkmcnt(0)
	v_add_u32_e32 v204, 0xc000, v201
	v_add_u32_e32 v205, 0xc000, v203
	ds_read_b128 v[212:215], v204 offset:0
	ds_read_b128 v[216:219], v204 offset:2048
	ds_read_b128 v[220:223], v204 offset:4096
	ds_read_b128 v[224:227], v204 offset:6144
	ds_read_b128 v[228:231], v205 offset:0
	ds_read_b128 v[232:235], v205 offset:2048
	ds_read_b128 v[236:239], v205 offset:4096
	ds_read_b128 v[240:243], v205 offset:6144
	v_mfma_f32_16x16x32_bf16 v[2:5], v[146:149], v[130:133], v[2:5]
	v_mfma_f32_16x16x32_bf16 v[6:9], v[150:153], v[130:133], v[6:9]
	v_mfma_f32_16x16x32_bf16 v[10:13], v[154:157], v[130:133], v[10:13]
	v_mfma_f32_16x16x32_bf16 v[14:17], v[158:161], v[130:133], v[14:17]
	v_mfma_f32_16x16x32_bf16 v[18:21], v[146:149], v[134:137], v[18:21]
	v_mfma_f32_16x16x32_bf16 v[22:25], v[150:153], v[134:137], v[22:25]
	v_mfma_f32_16x16x32_bf16 v[26:29], v[154:157], v[134:137], v[26:29]
	v_mfma_f32_16x16x32_bf16 v[30:33], v[158:161], v[134:137], v[30:33]
	v_mfma_f32_16x16x32_bf16 v[34:37], v[146:149], v[138:141], v[34:37]
	v_mfma_f32_16x16x32_bf16 v[38:41], v[150:153], v[138:141], v[38:41]
	v_mfma_f32_16x16x32_bf16 v[42:45], v[154:157], v[138:141], v[42:45]
	v_mfma_f32_16x16x32_bf16 v[46:49], v[158:161], v[138:141], v[46:49]
	v_mfma_f32_16x16x32_bf16 v[50:53], v[146:149], v[142:145], v[50:53]
	v_mfma_f32_16x16x32_bf16 v[54:57], v[150:153], v[142:145], v[54:57]
	v_mfma_f32_16x16x32_bf16 v[58:61], v[154:157], v[142:145], v[58:61]
	v_mfma_f32_16x16x32_bf16 v[62:65], v[158:161], v[142:145], v[62:65]
	s_waitcnt vmcnt(6)
	s_waitcnt lgkmcnt(0)
	s_barrier
	v_add_u32_e32 v204, 0x18000, v200
	v_add_u32_e32 v205, 0x18000, v202
	ds_read_b128 v[130:133], v204 offset:0
	ds_read_b128 v[134:137], v204 offset:2048
	ds_read_b128 v[138:141], v204 offset:4096
	ds_read_b128 v[142:145], v204 offset:6144
	ds_read_b128 v[146:149], v205 offset:0
	ds_read_b128 v[150:153], v205 offset:2048
	ds_read_b128 v[154:157], v205 offset:4096
	ds_read_b128 v[158:161], v205 offset:6144
	v_mfma_f32_16x16x32_bf16 v[2:5], v[228:231], v[212:215], v[2:5]
	v_mfma_f32_16x16x32_bf16 v[6:9], v[232:235], v[212:215], v[6:9]
	v_mfma_f32_16x16x32_bf16 v[10:13], v[236:239], v[212:215], v[10:13]
	v_mfma_f32_16x16x32_bf16 v[14:17], v[240:243], v[212:215], v[14:17]
	v_mfma_f32_16x16x32_bf16 v[18:21], v[228:231], v[216:219], v[18:21]
	v_mfma_f32_16x16x32_bf16 v[22:25], v[232:235], v[216:219], v[22:25]
	v_mfma_f32_16x16x32_bf16 v[26:29], v[236:239], v[216:219], v[26:29]
	v_mfma_f32_16x16x32_bf16 v[30:33], v[240:243], v[216:219], v[30:33]
	v_mfma_f32_16x16x32_bf16 v[34:37], v[228:231], v[220:223], v[34:37]
	v_mfma_f32_16x16x32_bf16 v[38:41], v[232:235], v[220:223], v[38:41]
	v_mfma_f32_16x16x32_bf16 v[42:45], v[236:239], v[220:223], v[42:45]
	v_mfma_f32_16x16x32_bf16 v[46:49], v[240:243], v[220:223], v[46:49]
	v_mfma_f32_16x16x32_bf16 v[50:53], v[228:231], v[224:227], v[50:53]
	v_mfma_f32_16x16x32_bf16 v[54:57], v[232:235], v[224:227], v[54:57]
	v_mfma_f32_16x16x32_bf16 v[58:61], v[236:239], v[224:227], v[58:61]
	v_mfma_f32_16x16x32_bf16 v[62:65], v[240:243], v[224:227], v[62:65]
	s_waitcnt lgkmcnt(0)
	v_add_u32_e32 v204, 0x18000, v201
	v_add_u32_e32 v205, 0x18000, v203
	ds_read_b128 v[212:215], v204 offset:0
	ds_read_b128 v[216:219], v204 offset:2048
	ds_read_b128 v[220:223], v204 offset:4096
	ds_read_b128 v[224:227], v204 offset:6144
	ds_read_b128 v[228:231], v205 offset:0
	ds_read_b128 v[232:235], v205 offset:2048
	ds_read_b128 v[236:239], v205 offset:4096
	ds_read_b128 v[240:243], v205 offset:6144
	v_mfma_f32_16x16x32_bf16 v[2:5], v[146:149], v[130:133], v[2:5]
	v_mfma_f32_16x16x32_bf16 v[6:9], v[150:153], v[130:133], v[6:9]
	v_mfma_f32_16x16x32_bf16 v[10:13], v[154:157], v[130:133], v[10:13]
	v_mfma_f32_16x16x32_bf16 v[14:17], v[158:161], v[130:133], v[14:17]
	v_mfma_f32_16x16x32_bf16 v[18:21], v[146:149], v[134:137], v[18:21]
	v_mfma_f32_16x16x32_bf16 v[22:25], v[150:153], v[134:137], v[22:25]
	v_mfma_f32_16x16x32_bf16 v[26:29], v[154:157], v[134:137], v[26:29]
	v_mfma_f32_16x16x32_bf16 v[30:33], v[158:161], v[134:137], v[30:33]
	v_mfma_f32_16x16x32_bf16 v[34:37], v[146:149], v[138:141], v[34:37]
	v_mfma_f32_16x16x32_bf16 v[38:41], v[150:153], v[138:141], v[38:41]
	v_mfma_f32_16x16x32_bf16 v[42:45], v[154:157], v[138:141], v[42:45]
	v_mfma_f32_16x16x32_bf16 v[46:49], v[158:161], v[138:141], v[46:49]
	v_mfma_f32_16x16x32_bf16 v[50:53], v[146:149], v[142:145], v[50:53]
	v_mfma_f32_16x16x32_bf16 v[54:57], v[150:153], v[142:145], v[54:57]
	v_mfma_f32_16x16x32_bf16 v[58:61], v[154:157], v[142:145], v[58:61]
	v_mfma_f32_16x16x32_bf16 v[62:65], v[158:161], v[142:145], v[62:65]
	s_waitcnt vmcnt(0)
	s_waitcnt lgkmcnt(0)
	s_barrier
	v_add_u32_e32 v204, 0x0, v200
	v_add_u32_e32 v205, 0x0, v202
	ds_read_b128 v[130:133], v204 offset:0
	ds_read_b128 v[134:137], v204 offset:2048
	ds_read_b128 v[138:141], v204 offset:4096
	ds_read_b128 v[142:145], v204 offset:6144
	ds_read_b128 v[146:149], v205 offset:0
	ds_read_b128 v[150:153], v205 offset:2048
	ds_read_b128 v[154:157], v205 offset:4096
	ds_read_b128 v[158:161], v205 offset:6144
	v_mfma_f32_16x16x32_bf16 v[2:5], v[228:231], v[212:215], v[2:5]
	v_mfma_f32_16x16x32_bf16 v[6:9], v[232:235], v[212:215], v[6:9]
	v_mfma_f32_16x16x32_bf16 v[10:13], v[236:239], v[212:215], v[10:13]
	v_mfma_f32_16x16x32_bf16 v[14:17], v[240:243], v[212:215], v[14:17]
	v_mfma_f32_16x16x32_bf16 v[18:21], v[228:231], v[216:219], v[18:21]
	v_mfma_f32_16x16x32_bf16 v[22:25], v[232:235], v[216:219], v[22:25]
	v_mfma_f32_16x16x32_bf16 v[26:29], v[236:239], v[216:219], v[26:29]
	v_mfma_f32_16x16x32_bf16 v[30:33], v[240:243], v[216:219], v[30:33]
	v_mfma_f32_16x16x32_bf16 v[34:37], v[228:231], v[220:223], v[34:37]
	v_mfma_f32_16x16x32_bf16 v[38:41], v[232:235], v[220:223], v[38:41]
	v_mfma_f32_16x16x32_bf16 v[42:45], v[236:239], v[220:223], v[42:45]
	v_mfma_f32_16x16x32_bf16 v[46:49], v[240:243], v[220:223], v[46:49]
	v_mfma_f32_16x16x32_bf16 v[50:53], v[228:231], v[224:227], v[50:53]
	v_mfma_f32_16x16x32_bf16 v[54:57], v[232:235], v[224:227], v[54:57]
	v_mfma_f32_16x16x32_bf16 v[58:61], v[236:239], v[224:227], v[58:61]
	v_mfma_f32_16x16x32_bf16 v[62:65], v[240:243], v[224:227], v[62:65]
	s_waitcnt lgkmcnt(0)
	v_add_u32_e32 v204, 0x0, v201
	v_add_u32_e32 v205, 0x0, v203
	ds_read_b128 v[212:215], v204 offset:0
	ds_read_b128 v[216:219], v204 offset:2048
	ds_read_b128 v[220:223], v204 offset:4096
	ds_read_b128 v[224:227], v204 offset:6144
	ds_read_b128 v[228:231], v205 offset:0
	ds_read_b128 v[232:235], v205 offset:2048
	ds_read_b128 v[236:239], v205 offset:4096
	ds_read_b128 v[240:243], v205 offset:6144
	v_mfma_f32_16x16x32_bf16 v[2:5], v[146:149], v[130:133], v[2:5]
	v_mfma_f32_16x16x32_bf16 v[6:9], v[150:153], v[130:133], v[6:9]
	v_mfma_f32_16x16x32_bf16 v[10:13], v[154:157], v[130:133], v[10:13]
	v_mfma_f32_16x16x32_bf16 v[14:17], v[158:161], v[130:133], v[14:17]
	v_mfma_f32_16x16x32_bf16 v[18:21], v[146:149], v[134:137], v[18:21]
	v_mfma_f32_16x16x32_bf16 v[22:25], v[150:153], v[134:137], v[22:25]
	v_mfma_f32_16x16x32_bf16 v[26:29], v[154:157], v[134:137], v[26:29]
	v_mfma_f32_16x16x32_bf16 v[30:33], v[158:161], v[134:137], v[30:33]
	v_mfma_f32_16x16x32_bf16 v[34:37], v[146:149], v[138:141], v[34:37]
	v_mfma_f32_16x16x32_bf16 v[38:41], v[150:153], v[138:141], v[38:41]
	v_mfma_f32_16x16x32_bf16 v[42:45], v[154:157], v[138:141], v[42:45]
	v_mfma_f32_16x16x32_bf16 v[46:49], v[158:161], v[138:141], v[46:49]
	v_mfma_f32_16x16x32_bf16 v[50:53], v[146:149], v[142:145], v[50:53]
	v_mfma_f32_16x16x32_bf16 v[54:57], v[150:153], v[142:145], v[54:57]
	v_mfma_f32_16x16x32_bf16 v[58:61], v[154:157], v[142:145], v[58:61]
	v_mfma_f32_16x16x32_bf16 v[62:65], v[158:161], v[142:145], v[62:65]
	s_waitcnt lgkmcnt(0)
	v_mfma_f32_16x16x32_bf16 v[2:5], v[228:231], v[212:215], v[2:5]
	v_mfma_f32_16x16x32_bf16 v[6:9], v[232:235], v[212:215], v[6:9]
	v_mfma_f32_16x16x32_bf16 v[10:13], v[236:239], v[212:215], v[10:13]
	v_mfma_f32_16x16x32_bf16 v[14:17], v[240:243], v[212:215], v[14:17]
	v_mfma_f32_16x16x32_bf16 v[18:21], v[228:231], v[216:219], v[18:21]
	v_mfma_f32_16x16x32_bf16 v[22:25], v[232:235], v[216:219], v[22:25]
	v_mfma_f32_16x16x32_bf16 v[26:29], v[236:239], v[216:219], v[26:29]
	v_mfma_f32_16x16x32_bf16 v[30:33], v[240:243], v[216:219], v[30:33]
	v_mfma_f32_16x16x32_bf16 v[34:37], v[228:231], v[220:223], v[34:37]
	v_mfma_f32_16x16x32_bf16 v[38:41], v[232:235], v[220:223], v[38:41]
	v_mfma_f32_16x16x32_bf16 v[42:45], v[236:239], v[220:223], v[42:45]
	v_mfma_f32_16x16x32_bf16 v[46:49], v[240:243], v[220:223], v[46:49]
	v_mfma_f32_16x16x32_bf16 v[50:53], v[228:231], v[224:227], v[50:53]
	v_mfma_f32_16x16x32_bf16 v[54:57], v[232:235], v[224:227], v[54:57]
	v_mfma_f32_16x16x32_bf16 v[58:61], v[236:239], v[224:227], v[58:61]
	v_mfma_f32_16x16x32_bf16 v[62:65], v[240:243], v[224:227], v[62:65]
	s_waitcnt vmcnt(0)
	s_nop 7
	s_cmp_lg_u32 s82, 0
	s_cbranch_scc1 .Lop_cvbf
	v_pk_fma_f32 v[4:5], v[4:5], v[176:177], v[68:69]
	v_pk_fma_f32 v[2:3], v[2:3], v[174:175], v[66:67]
	s_nop 0
	v_cvt_pk_bf16_f32 v2, v2, v3
	v_cvt_pk_bf16_f32 v3, v4, v5
	global_store_dwordx2 v206, v[2:3], s[74:75] offset:0
	v_pk_fma_f32 v[8:9], v[8:9], v[180:181], v[72:73]
	v_pk_fma_f32 v[6:7], v[6:7], v[178:179], v[70:71]
	s_nop 0
	v_cvt_pk_bf16_f32 v6, v6, v7
	v_cvt_pk_bf16_f32 v7, v8, v9
	global_store_dwordx2 v206, v[6:7], s[74:75] offset:32
	v_pk_fma_f32 v[12:13], v[12:13], v[184:185], v[76:77]
	v_pk_fma_f32 v[10:11], v[10:11], v[182:183], v[74:75]
	s_nop 0
	v_cvt_pk_bf16_f32 v10, v10, v11
	v_cvt_pk_bf16_f32 v11, v12, v13
	global_store_dwordx2 v206, v[10:11], s[74:75] offset:64
	v_pk_fma_f32 v[16:17], v[16:17], v[188:189], v[80:81]
	v_pk_fma_f32 v[14:15], v[14:15], v[186:187], v[78:79]
	s_nop 0
	v_cvt_pk_bf16_f32 v14, v14, v15
	v_cvt_pk_bf16_f32 v15, v16, v17
	global_store_dwordx2 v206, v[14:15], s[74:75] offset:96
	v_pk_fma_f32 v[20:21], v[20:21], v[176:177], v[84:85]
	v_pk_fma_f32 v[18:19], v[18:19], v[174:175], v[82:83]
	s_nop 0
	v_cvt_pk_bf16_f32 v18, v18, v19
	v_cvt_pk_bf16_f32 v19, v20, v21
	global_store_dwordx2 v207, v[18:19], s[74:75] offset:0
	v_pk_fma_f32 v[24:25], v[24:25], v[180:181], v[88:89]
	v_pk_fma_f32 v[22:23], v[22:23], v[178:179], v[86:87]
	s_nop 0
	v_cvt_pk_bf16_f32 v22, v22, v23
	v_cvt_pk_bf16_f32 v23, v24, v25
	global_store_dwordx2 v207, v[22:23], s[74:75] offset:32
	v_pk_fma_f32 v[28:29], v[28:29], v[184:185], v[92:93]
	v_pk_fma_f32 v[26:27], v[26:27], v[182:183], v[90:91]
	s_nop 0
	v_cvt_pk_bf16_f32 v26, v26, v27
	v_cvt_pk_bf16_f32 v27, v28, v29
	global_store_dwordx2 v207, v[26:27], s[74:75] offset:64
	v_pk_fma_f32 v[32:33], v[32:33], v[188:189], v[96:97]
	v_pk_fma_f32 v[30:31], v[30:31], v[186:187], v[94:95]
	s_nop 0
	v_cvt_pk_bf16_f32 v30, v30, v31
	v_cvt_pk_bf16_f32 v31, v32, v33
	global_store_dwordx2 v207, v[30:31], s[74:75] offset:96
	v_pk_fma_f32 v[36:37], v[36:37], v[176:177], v[100:101]
	v_pk_fma_f32 v[34:35], v[34:35], v[174:175], v[98:99]
	s_nop 0
	v_cvt_pk_bf16_f32 v34, v34, v35
	v_cvt_pk_bf16_f32 v35, v36, v37
	global_store_dwordx2 v208, v[34:35], s[74:75] offset:0
	v_pk_fma_f32 v[40:41], v[40:41], v[180:181], v[104:105]
	v_pk_fma_f32 v[38:39], v[38:39], v[178:179], v[102:103]
	s_nop 0
	v_cvt_pk_bf16_f32 v38, v38, v39
	v_cvt_pk_bf16_f32 v39, v40, v41
	global_store_dwordx2 v208, v[38:39], s[74:75] offset:32
	v_pk_fma_f32 v[44:45], v[44:45], v[184:185], v[108:109]
	v_pk_fma_f32 v[42:43], v[42:43], v[182:183], v[106:107]
	s_nop 0
	v_cvt_pk_bf16_f32 v42, v42, v43
	v_cvt_pk_bf16_f32 v43, v44, v45
	global_store_dwordx2 v208, v[42:43], s[74:75] offset:64
	v_pk_fma_f32 v[48:49], v[48:49], v[188:189], v[112:113]
	v_pk_fma_f32 v[46:47], v[46:47], v[186:187], v[110:111]
	s_nop 0
	v_cvt_pk_bf16_f32 v46, v46, v47
	v_cvt_pk_bf16_f32 v47, v48, v49
	global_store_dwordx2 v208, v[46:47], s[74:75] offset:96
	v_pk_fma_f32 v[52:53], v[52:53], v[176:177], v[116:117]
	v_pk_fma_f32 v[50:51], v[50:51], v[174:175], v[114:115]
	s_nop 0
	v_cvt_pk_bf16_f32 v50, v50, v51
	v_cvt_pk_bf16_f32 v51, v52, v53
	global_store_dwordx2 v209, v[50:51], s[74:75] offset:0
	v_pk_fma_f32 v[56:57], v[56:57], v[180:181], v[120:121]
	v_pk_fma_f32 v[54:55], v[54:55], v[178:179], v[118:119]
	s_nop 0
	v_cvt_pk_bf16_f32 v54, v54, v55
	v_cvt_pk_bf16_f32 v55, v56, v57
	global_store_dwordx2 v209, v[54:55], s[74:75] offset:32
	v_pk_fma_f32 v[60:61], v[60:61], v[184:185], v[124:125]
	v_pk_fma_f32 v[58:59], v[58:59], v[182:183], v[122:123]
	s_nop 0
	v_cvt_pk_bf16_f32 v58, v58, v59
	v_cvt_pk_bf16_f32 v59, v60, v61
	global_store_dwordx2 v209, v[58:59], s[74:75] offset:64
	v_pk_fma_f32 v[64:65], v[64:65], v[188:189], v[128:129]
	v_pk_fma_f32 v[62:63], v[62:63], v[186:187], v[126:127]
	s_nop 0
	v_cvt_pk_bf16_f32 v62, v62, v63
	v_cvt_pk_bf16_f32 v63, v64, v65
	global_store_dwordx2 v209, v[62:63], s[74:75] offset:96
	s_branch .Lop_cvdone

.LBB0_590:
	s_andn2_b64 vcc, exec, s[2:3]
	s_cbranch_vccnz .LBB0_571
	s_ashr_i32 s14, s0, 5
	v_mov_b32_e32 v2, v1
	s_lshl_b32 s2, s14, 7
	s_lshl_b32 s74, s2, 12
	s_add_u32 s74, s19, s74
	s_addc_u32 s75, s85, 0
	s_add_u32 s74, s74, 0x400000
	s_addc_u32 s75, s75, 0
	s_and_b32 s76, s0, 1
	s_lshl_b32 s76, s76, 11
	v_lshl_add_u32 v162, v1, 2, s76
	global_load_dword v34, v162, s[74:75]
	s_add_u32 s74, s74, 0x1000
	s_addc_u32 s75, s75, 0
	s_nop 1
	global_load_dword v35, v162, s[74:75]
	s_add_u32 s74, s74, 0x1000
	s_addc_u32 s75, s75, 0
	s_nop 1
	global_load_dword v36, v162, s[74:75]
	s_add_u32 s74, s74, 0x1000
	s_addc_u32 s75, s75, 0
	s_nop 1
	global_load_dword v37, v162, s[74:75]
	s_add_u32 s74, s74, 0x1000
	s_addc_u32 s75, s75, 0
	s_nop 1
	global_load_dword v38, v162, s[74:75]
	s_add_u32 s74, s74, 0x1000
	s_addc_u32 s75, s75, 0
	s_nop 1
	global_load_dword v39, v162, s[74:75]
	s_add_u32 s74, s74, 0x1000
	s_addc_u32 s75, s75, 0
	s_nop 1
	global_load_dword v40, v162, s[74:75]
	s_add_u32 s74, s74, 0x1000
	s_addc_u32 s75, s75, 0
	s_nop 1
	global_load_dword v41, v162, s[74:75]
	s_add_u32 s74, s74, 0x1000
	s_addc_u32 s75, s75, 0
	s_nop 1
	global_load_dword v42, v162, s[74:75]
	s_add_u32 s74, s74, 0x1000
	s_addc_u32 s75, s75, 0
	s_nop 1
	global_load_dword v43, v162, s[74:75]
	s_add_u32 s74, s74, 0x1000
	s_addc_u32 s75, s75, 0
	s_nop 1
	global_load_dword v44, v162, s[74:75]
	s_add_u32 s74, s74, 0x1000
	s_addc_u32 s75, s75, 0
	s_nop 1
	global_load_dword v45, v162, s[74:75]
	s_add_u32 s74, s74, 0x1000
	s_addc_u32 s75, s75, 0
	s_nop 1
	global_load_dword v46, v162, s[74:75]
	s_add_u32 s74, s74, 0x1000
	s_addc_u32 s75, s75, 0
	s_nop 1
	global_load_dword v47, v162, s[74:75]
	s_add_u32 s74, s74, 0x1000
	s_addc_u32 s75, s75, 0
	s_nop 1
	global_load_dword v48, v162, s[74:75]
	s_add_u32 s74, s74, 0x1000
	s_addc_u32 s75, s75, 0
	s_nop 1
	global_load_dword v49, v162, s[74:75]
	s_add_u32 s74, s74, 0x1000
	s_addc_u32 s75, s75, 0
	s_nop 1
	global_load_dword v50, v162, s[74:75]
	s_add_u32 s74, s74, 0x1000
	s_addc_u32 s75, s75, 0
	s_nop 1
	global_load_dword v51, v162, s[74:75]
	s_add_u32 s74, s74, 0x1000
	s_addc_u32 s75, s75, 0
	s_nop 1
	global_load_dword v52, v162, s[74:75]
	s_add_u32 s74, s74, 0x1000
	s_addc_u32 s75, s75, 0
	s_nop 1
	global_load_dword v53, v162, s[74:75]
	s_add_u32 s74, s74, 0x1000
	s_addc_u32 s75, s75, 0
	s_nop 1
	global_load_dword v54, v162, s[74:75]
	s_add_u32 s74, s74, 0x1000
	s_addc_u32 s75, s75, 0
	s_nop 1
	global_load_dword v55, v162, s[74:75]
	s_add_u32 s74, s74, 0x1000
	s_addc_u32 s75, s75, 0
	s_nop 1
	global_load_dword v56, v162, s[74:75]
	s_add_u32 s74, s74, 0x1000
	s_addc_u32 s75, s75, 0
	s_nop 1
	global_load_dword v57, v162, s[74:75]
	s_add_u32 s74, s74, 0x1000
	s_addc_u32 s75, s75, 0
	s_nop 1
	global_load_dword v58, v162, s[74:75]
	s_add_u32 s74, s74, 0x1000
	s_addc_u32 s75, s75, 0
	s_nop 1
	global_load_dword v59, v162, s[74:75]
	s_add_u32 s74, s74, 0x1000
	s_addc_u32 s75, s75, 0
	s_nop 1
	global_load_dword v60, v162, s[74:75]
	s_add_u32 s74, s74, 0x1000
	s_addc_u32 s75, s75, 0
	s_nop 1
	global_load_dword v61, v162, s[74:75]
	s_add_u32 s74, s74, 0x1000
	s_addc_u32 s75, s75, 0
	s_nop 1
	global_load_dword v62, v162, s[74:75]
	s_add_u32 s74, s74, 0x1000
	s_addc_u32 s75, s75, 0
	s_nop 1
	global_load_dword v63, v162, s[74:75]
	s_add_u32 s74, s74, 0x1000
	s_addc_u32 s75, s75, 0
	s_nop 1
	global_load_dword v64, v162, s[74:75]
	s_add_u32 s74, s74, 0x1000
	s_addc_u32 s75, s75, 0
	s_nop 1
	global_load_dword v65, v162, s[74:75]
	s_add_u32 s74, s74, 0x1000
	s_addc_u32 s75, s75, 0
	s_nop 1
	s_waitcnt vmcnt(31)
	global_load_dword v66, v162, s[74:75]
	s_add_u32 s74, s74, 0x1000
	s_addc_u32 s75, s75, 0
	s_nop 1
	global_load_dword v67, v162, s[74:75]
	s_add_u32 s74, s74, 0x1000
	s_addc_u32 s75, s75, 0
	s_nop 1
	global_load_dword v68, v162, s[74:75]
	s_add_u32 s74, s74, 0x1000
	s_addc_u32 s75, s75, 0
	s_nop 1
	global_load_dword v69, v162, s[74:75]
	s_add_u32 s74, s74, 0x1000
	s_addc_u32 s75, s75, 0
	s_nop 1
	global_load_dword v70, v162, s[74:75]
	s_add_u32 s74, s74, 0x1000
	s_addc_u32 s75, s75, 0
	s_nop 1
	global_load_dword v71, v162, s[74:75]
	s_add_u32 s74, s74, 0x1000
	s_addc_u32 s75, s75, 0
	s_nop 1
	global_load_dword v72, v162, s[74:75]
	s_add_u32 s74, s74, 0x1000
	s_addc_u32 s75, s75, 0
	s_nop 1
	global_load_dword v73, v162, s[74:75]
	s_add_u32 s74, s74, 0x1000
	s_addc_u32 s75, s75, 0
	s_nop 1
	global_load_dword v74, v162, s[74:75]
	s_add_u32 s74, s74, 0x1000
	s_addc_u32 s75, s75, 0
	s_nop 1
	global_load_dword v75, v162, s[74:75]
	s_add_u32 s74, s74, 0x1000
	s_addc_u32 s75, s75, 0
	s_nop 1
	global_load_dword v76, v162, s[74:75]
	s_add_u32 s74, s74, 0x1000
	s_addc_u32 s75, s75, 0
	s_nop 1
	global_load_dword v77, v162, s[74:75]
	s_add_u32 s74, s74, 0x1000
	s_addc_u32 s75, s75, 0
	s_nop 1
	global_load_dword v78, v162, s[74:75]
	s_add_u32 s74, s74, 0x1000
	s_addc_u32 s75, s75, 0
	s_nop 1
	global_load_dword v79, v162, s[74:75]
	s_add_u32 s74, s74, 0x1000
	s_addc_u32 s75, s75, 0
	s_nop 1
	global_load_dword v80, v162, s[74:75]
	s_add_u32 s74, s74, 0x1000
	s_addc_u32 s75, s75, 0
	s_nop 1
	global_load_dword v81, v162, s[74:75]
	s_add_u32 s74, s74, 0x1000
	s_addc_u32 s75, s75, 0
	s_nop 1
	global_load_dword v82, v162, s[74:75]
	s_add_u32 s74, s74, 0x1000
	s_addc_u32 s75, s75, 0
	s_nop 1
	global_load_dword v83, v162, s[74:75]
	s_add_u32 s74, s74, 0x1000
	s_addc_u32 s75, s75, 0
	s_nop 1
	global_load_dword v84, v162, s[74:75]
	s_add_u32 s74, s74, 0x1000
	s_addc_u32 s75, s75, 0
	s_nop 1
	global_load_dword v85, v162, s[74:75]
	s_add_u32 s74, s74, 0x1000
	s_addc_u32 s75, s75, 0
	s_nop 1
	global_load_dword v86, v162, s[74:75]
	s_add_u32 s74, s74, 0x1000
	s_addc_u32 s75, s75, 0
	s_nop 1
	global_load_dword v87, v162, s[74:75]
	s_add_u32 s74, s74, 0x1000
	s_addc_u32 s75, s75, 0
	s_nop 1
	global_load_dword v88, v162, s[74:75]
	s_add_u32 s74, s74, 0x1000
	s_addc_u32 s75, s75, 0
	s_nop 1
	global_load_dword v89, v162, s[74:75]
	s_add_u32 s74, s74, 0x1000
	s_addc_u32 s75, s75, 0
	s_nop 1
	global_load_dword v90, v162, s[74:75]
	s_add_u32 s74, s74, 0x1000
	s_addc_u32 s75, s75, 0
	s_nop 1
	global_load_dword v91, v162, s[74:75]
	s_add_u32 s74, s74, 0x1000
	s_addc_u32 s75, s75, 0
	s_nop 1
	global_load_dword v92, v162, s[74:75]
	s_add_u32 s74, s74, 0x1000
	s_addc_u32 s75, s75, 0
	s_nop 1
	global_load_dword v93, v162, s[74:75]
	s_add_u32 s74, s74, 0x1000
	s_addc_u32 s75, s75, 0
	s_nop 1
	global_load_dword v94, v162, s[74:75]
	s_add_u32 s74, s74, 0x1000
	s_addc_u32 s75, s75, 0
	s_nop 1
	global_load_dword v95, v162, s[74:75]
	s_add_u32 s74, s74, 0x1000
	s_addc_u32 s75, s75, 0
	s_nop 1
	global_load_dword v96, v162, s[74:75]
	s_add_u32 s74, s74, 0x1000
	s_addc_u32 s75, s75, 0
	s_nop 1
	global_load_dword v97, v162, s[74:75]
	s_add_u32 s74, s74, 0x1000
	s_addc_u32 s75, s75, 0
	s_nop 1
	s_waitcnt vmcnt(31)
	global_load_dword v98, v162, s[74:75]
	s_add_u32 s74, s74, 0x1000
	s_addc_u32 s75, s75, 0
	s_nop 1
	global_load_dword v99, v162, s[74:75]
	s_add_u32 s74, s74, 0x1000
	s_addc_u32 s75, s75, 0
	s_nop 1
	global_load_dword v100, v162, s[74:75]
	s_add_u32 s74, s74, 0x1000
	s_addc_u32 s75, s75, 0
	s_nop 1
	global_load_dword v101, v162, s[74:75]
	s_add_u32 s74, s74, 0x1000
	s_addc_u32 s75, s75, 0
	s_nop 1
	global_load_dword v102, v162, s[74:75]
	s_add_u32 s74, s74, 0x1000
	s_addc_u32 s75, s75, 0
	s_nop 1
	global_load_dword v103, v162, s[74:75]
	s_add_u32 s74, s74, 0x1000
	s_addc_u32 s75, s75, 0
	s_nop 1
	global_load_dword v104, v162, s[74:75]
	s_add_u32 s74, s74, 0x1000
	s_addc_u32 s75, s75, 0
	s_nop 1
	global_load_dword v105, v162, s[74:75]
	s_add_u32 s74, s74, 0x1000
	s_addc_u32 s75, s75, 0
	s_nop 1
	global_load_dword v106, v162, s[74:75]
	s_add_u32 s74, s74, 0x1000
	s_addc_u32 s75, s75, 0
	s_nop 1
	global_load_dword v107, v162, s[74:75]
	s_add_u32 s74, s74, 0x1000
	s_addc_u32 s75, s75, 0
	s_nop 1
	global_load_dword v108, v162, s[74:75]
	s_add_u32 s74, s74, 0x1000
	s_addc_u32 s75, s75, 0
	s_nop 1
	global_load_dword v109, v162, s[74:75]
	s_add_u32 s74, s74, 0x1000
	s_addc_u32 s75, s75, 0
	s_nop 1
	global_load_dword v110, v162, s[74:75]
	s_add_u32 s74, s74, 0x1000
	s_addc_u32 s75, s75, 0
	s_nop 1
	global_load_dword v111, v162, s[74:75]
	s_add_u32 s74, s74, 0x1000
	s_addc_u32 s75, s75, 0
	s_nop 1
	global_load_dword v112, v162, s[74:75]
	s_add_u32 s74, s74, 0x1000
	s_addc_u32 s75, s75, 0
	s_nop 1
	global_load_dword v113, v162, s[74:75]
	s_add_u32 s74, s74, 0x1000
	s_addc_u32 s75, s75, 0
	s_nop 1
	global_load_dword v114, v162, s[74:75]
	s_add_u32 s74, s74, 0x1000
	s_addc_u32 s75, s75, 0
	s_nop 1
	global_load_dword v115, v162, s[74:75]
	s_add_u32 s74, s74, 0x1000
	s_addc_u32 s75, s75, 0
	s_nop 1
	global_load_dword v116, v162, s[74:75]
	s_add_u32 s74, s74, 0x1000
	s_addc_u32 s75, s75, 0
	s_nop 1
	global_load_dword v117, v162, s[74:75]
	s_add_u32 s74, s74, 0x1000
	s_addc_u32 s75, s75, 0
	s_nop 1
	global_load_dword v118, v162, s[74:75]
	s_add_u32 s74, s74, 0x1000
	s_addc_u32 s75, s75, 0
	s_nop 1
	global_load_dword v119, v162, s[74:75]
	s_add_u32 s74, s74, 0x1000
	s_addc_u32 s75, s75, 0
	s_nop 1
	global_load_dword v120, v162, s[74:75]
	s_add_u32 s74, s74, 0x1000
	s_addc_u32 s75, s75, 0
	s_nop 1
	global_load_dword v121, v162, s[74:75]
	s_add_u32 s74, s74, 0x1000
	s_addc_u32 s75, s75, 0
	s_nop 1
	global_load_dword v122, v162, s[74:75]
	s_add_u32 s74, s74, 0x1000
	s_addc_u32 s75, s75, 0
	s_nop 1
	global_load_dword v123, v162, s[74:75]
	s_add_u32 s74, s74, 0x1000
	s_addc_u32 s75, s75, 0
	s_nop 1
	global_load_dword v124, v162, s[74:75]
	s_add_u32 s74, s74, 0x1000
	s_addc_u32 s75, s75, 0
	s_nop 1
	global_load_dword v125, v162, s[74:75]
	s_add_u32 s74, s74, 0x1000
	s_addc_u32 s75, s75, 0
	s_nop 1
	global_load_dword v126, v162, s[74:75]
	s_add_u32 s74, s74, 0x1000
	s_addc_u32 s75, s75, 0
	s_nop 1
	global_load_dword v127, v162, s[74:75]
	s_add_u32 s74, s74, 0x1000
	s_addc_u32 s75, s75, 0
	s_nop 1
	global_load_dword v128, v162, s[74:75]
	s_add_u32 s74, s74, 0x1000
	s_addc_u32 s75, s75, 0
	s_nop 1
	global_load_dword v129, v162, s[74:75]
	s_add_u32 s74, s74, 0x1000
	s_addc_u32 s75, s75, 0
	s_nop 1
	s_waitcnt vmcnt(31)
	global_load_dword v130, v162, s[74:75]
	s_add_u32 s74, s74, 0x1000
	s_addc_u32 s75, s75, 0
	s_nop 1
	global_load_dword v131, v162, s[74:75]
	s_add_u32 s74, s74, 0x1000
	s_addc_u32 s75, s75, 0
	s_nop 1
	global_load_dword v132, v162, s[74:75]
	s_add_u32 s74, s74, 0x1000
	s_addc_u32 s75, s75, 0
	s_nop 1
	global_load_dword v133, v162, s[74:75]
	s_add_u32 s74, s74, 0x1000
	s_addc_u32 s75, s75, 0
	s_nop 1
	global_load_dword v134, v162, s[74:75]
	s_add_u32 s74, s74, 0x1000
	s_addc_u32 s75, s75, 0
	s_nop 1
	global_load_dword v135, v162, s[74:75]
	s_add_u32 s74, s74, 0x1000
	s_addc_u32 s75, s75, 0
	s_nop 1
	global_load_dword v136, v162, s[74:75]
	s_add_u32 s74, s74, 0x1000
	s_addc_u32 s75, s75, 0
	s_nop 1
	global_load_dword v137, v162, s[74:75]
	s_add_u32 s74, s74, 0x1000
	s_addc_u32 s75, s75, 0
	s_nop 1
	global_load_dword v138, v162, s[74:75]
	s_add_u32 s74, s74, 0x1000
	s_addc_u32 s75, s75, 0
	s_nop 1
	global_load_dword v139, v162, s[74:75]
	s_add_u32 s74, s74, 0x1000
	s_addc_u32 s75, s75, 0
	s_nop 1
	global_load_dword v140, v162, s[74:75]
	s_add_u32 s74, s74, 0x1000
	s_addc_u32 s75, s75, 0
	s_nop 1
	global_load_dword v141, v162, s[74:75]
	s_add_u32 s74, s74, 0x1000
	s_addc_u32 s75, s75, 0
	s_nop 1
	global_load_dword v142, v162, s[74:75]
	s_add_u32 s74, s74, 0x1000
	s_addc_u32 s75, s75, 0
	s_nop 1
	global_load_dword v143, v162, s[74:75]
	s_add_u32 s74, s74, 0x1000
	s_addc_u32 s75, s75, 0
	s_nop 1
	global_load_dword v144, v162, s[74:75]
	s_add_u32 s74, s74, 0x1000
	s_addc_u32 s75, s75, 0
	s_nop 1
	global_load_dword v145, v162, s[74:75]
	s_add_u32 s74, s74, 0x1000
	s_addc_u32 s75, s75, 0
	s_nop 1
	global_load_dword v146, v162, s[74:75]
	s_add_u32 s74, s74, 0x1000
	s_addc_u32 s75, s75, 0
	s_nop 1
	global_load_dword v147, v162, s[74:75]
	s_add_u32 s74, s74, 0x1000
	s_addc_u32 s75, s75, 0
	s_nop 1
	global_load_dword v148, v162, s[74:75]
	s_add_u32 s74, s74, 0x1000
	s_addc_u32 s75, s75, 0
	s_nop 1
	global_load_dword v149, v162, s[74:75]
	s_add_u32 s74, s74, 0x1000
	s_addc_u32 s75, s75, 0
	s_nop 1
	global_load_dword v150, v162, s[74:75]
	s_add_u32 s74, s74, 0x1000
	s_addc_u32 s75, s75, 0
	s_nop 1
	global_load_dword v151, v162, s[74:75]
	s_add_u32 s74, s74, 0x1000
	s_addc_u32 s75, s75, 0
	s_nop 1
	global_load_dword v152, v162, s[74:75]
	s_add_u32 s74, s74, 0x1000
	s_addc_u32 s75, s75, 0
	s_nop 1
	global_load_dword v153, v162, s[74:75]
	s_add_u32 s74, s74, 0x1000
	s_addc_u32 s75, s75, 0
	s_nop 1
	global_load_dword v154, v162, s[74:75]
	s_add_u32 s74, s74, 0x1000
	s_addc_u32 s75, s75, 0
	s_nop 1
	global_load_dword v155, v162, s[74:75]
	s_add_u32 s74, s74, 0x1000
	s_addc_u32 s75, s75, 0
	s_nop 1
	global_load_dword v156, v162, s[74:75]
	s_add_u32 s74, s74, 0x1000
	s_addc_u32 s75, s75, 0
	s_nop 1
	global_load_dword v157, v162, s[74:75]
	s_add_u32 s74, s74, 0x1000
	s_addc_u32 s75, s75, 0
	s_nop 1
	global_load_dword v158, v162, s[74:75]
	s_add_u32 s74, s74, 0x1000
	s_addc_u32 s75, s75, 0
	s_nop 1
	global_load_dword v159, v162, s[74:75]
	s_add_u32 s74, s74, 0x1000
	s_addc_u32 s75, s75, 0
	s_nop 1
	global_load_dword v160, v162, s[74:75]
	s_add_u32 s74, s74, 0x1000
	s_addc_u32 s75, s75, 0
	s_nop 1
	global_load_dword v161, v162, s[74:75]
	s_add_u32 s74, s74, 0x1000
	s_addc_u32 s75, s75, 0
	s_nop 1
	s_movk_i32 s12, 0x400
	s_bfe_u32 s48, s0, 0x40001
	s_ashr_i32 s3, s2, 31
	v_cmp_gt_i32_e32 vcc, s12, v2
	s_and_saveexec_b64 s[12:13], vcc
	s_movk_i32 vcc_lo, 0x1ff
	s_cbranch_execz .LBB0_599
	s_add_i32 s14, s14, s81
	s_ashr_i32 s15, s14, 31
	s_lshl_b64 s[14:15], s[14:15], 7
	s_lshl_b32 s30, s48, 3
	s_or_b32 s14, s14, s30
	v_max_i32_e32 v3, 0x200, v2
	v_and_or_b32 v4, v2, 7, s14
	v_mov_b32_e32 v5, s15
	v_sub_u32_e32 v3, v3, v2
	v_lshlrev_b64 v[4:5], 9, v[4:5]
	v_add_u32_e32 v6, 0x1ff, v3
	s_add_i32 s86, s2, s84
	v_lshl_add_u64 v[4:5], s[40:41], 0, v[4:5]
	v_cmp_lt_u32_e32 vcc, vcc_lo, v6
	s_mov_b64 s[30:31], -1
	v_mov_b32_e32 v3, v2
	s_and_saveexec_b64 s[14:15], vcc
	s_cbranch_execz .LBB0_596
	v_lshrrev_b32_e32 v3, 9, v6
	v_add_u32_e32 v8, 1, v3
	v_and_b32_e32 v9, 0xfffffe, v8
	v_add_u32_e32 v3, 0x200, v2
	s_mov_b32 s87, s86
	v_lshl_add_u32 v10, v2, 2, 0
	s_mov_b64 s[30:31], 0
	v_mov_b32_e32 v11, v9
	v_mov_b64_e32 v[6:7], v[2:3]

.LBB0_599:
	s_or_b64 exec, exec, s[12:13]
	s_lshl_b32 s0, s0, 9
	s_and_b32 s0, s0, 0x200
	s_lshl_b64 s[12:13], s[2:3], 12
	v_add_u32_e32 v2, s0, v2
	s_add_u32 s12, s19, s12
	v_ashrrev_i32_e32 v3, 31, v2
	s_addc_u32 s13, s85, s13
	v_mov_b32_e32 v6, 0
	v_lshl_add_u64 v[4:5], v[2:3], 2, s[12:13]
	s_mov_b64 s[12:13], 0
	s_mov_b32 s0, 0
	v_mov_b32_e32 v7, v6
	v_mov_b32_e32 v8, v6
	v_mov_b32_e32 v9, v6
	v_mov_b32_e32 v10, v6
	v_mov_b32_e32 v11, v6
	v_mov_b32_e32 v12, v6
	v_mov_b32_e32 v13, v6
	s_mov_b32 s14, 0x402000
	s_mov_b32 s15, 0x404000
	s_mov_b32 s30, 0x406000
	s_mov_b32 s31, 0x408000
	s_mov_b32 s86, 0x40a000
	s_mov_b32 s74, 0x40c000
	s_mov_b32 s75, 0x40e000
	s_mov_b32 s76, 0x40f000
	s_waitcnt lgkmcnt(0)
	s_barrier
	s_waitcnt vmcnt(0)
	v_mov_b32_e32 v3, 0
	ds_read_b128 v[14:17], v3 offset:0
	ds_read_b128 v[18:21], v3 offset:16
	ds_read_b128 v[22:25], v3 offset:32
	ds_read_b128 v[26:29], v3 offset:48
	ds_read_b128 v[174:177], v3 offset:64
	ds_read_b128 v[178:181], v3 offset:80
	s_waitcnt lgkmcnt(4)
	v_pk_fma_f32 v[8:9], v[34:35], v[14:15], v[8:9] op_sel_hi:[0,1,1]
	v_pk_fma_f32 v[10:11], v[34:35], v[16:17], v[10:11] op_sel_hi:[0,1,1]
	v_pk_fma_f32 v[12:13], v[34:35], v[18:19], v[12:13] op_sel_hi:[0,1,1]
	v_pk_fma_f32 v[6:7], v[34:35], v[20:21], v[6:7] op_sel_hi:[0,1,1]
	ds_read_b128 v[182:185], v3 offset:96
	ds_read_b128 v[186:189], v3 offset:112
	s_waitcnt lgkmcnt(4)
	v_mov_b32_e32 v30, v35
	v_pk_fma_f32 v[8:9], v[30:31], v[22:23], v[8:9] op_sel_hi:[0,1,1]
	v_pk_fma_f32 v[10:11], v[30:31], v[24:25], v[10:11] op_sel_hi:[0,1,1]
	v_pk_fma_f32 v[12:13], v[30:31], v[26:27], v[12:13] op_sel_hi:[0,1,1]
	v_pk_fma_f32 v[6:7], v[30:31], v[28:29], v[6:7] op_sel_hi:[0,1,1]
	ds_read_b128 v[14:17], v3 offset:128
	ds_read_b128 v[18:21], v3 offset:144
	s_waitcnt lgkmcnt(4)
	v_pk_fma_f32 v[8:9], v[36:37], v[174:175], v[8:9] op_sel_hi:[0,1,1]
	v_pk_fma_f32 v[10:11], v[36:37], v[176:177], v[10:11] op_sel_hi:[0,1,1]
	v_pk_fma_f32 v[12:13], v[36:37], v[178:179], v[12:13] op_sel_hi:[0,1,1]
	v_pk_fma_f32 v[6:7], v[36:37], v[180:181], v[6:7] op_sel_hi:[0,1,1]
	ds_read_b128 v[22:25], v3 offset:160
	ds_read_b128 v[26:29], v3 offset:176
	s_waitcnt lgkmcnt(4)
	v_mov_b32_e32 v32, v37
	v_pk_fma_f32 v[8:9], v[32:33], v[182:183], v[8:9] op_sel_hi:[0,1,1]
	v_pk_fma_f32 v[10:11], v[32:33], v[184:185], v[10:11] op_sel_hi:[0,1,1]
	v_pk_fma_f32 v[12:13], v[32:33], v[186:187], v[12:13] op_sel_hi:[0,1,1]
	v_pk_fma_f32 v[6:7], v[32:33], v[188:189], v[6:7] op_sel_hi:[0,1,1]
	ds_read_b128 v[174:177], v3 offset:192
	ds_read_b128 v[178:181], v3 offset:208
	s_waitcnt lgkmcnt(4)
	v_pk_fma_f32 v[8:9], v[38:39], v[14:15], v[8:9] op_sel_hi:[0,1,1]
	v_pk_fma_f32 v[10:11], v[38:39], v[16:17], v[10:11] op_sel_hi:[0,1,1]
	v_pk_fma_f32 v[12:13], v[38:39], v[18:19], v[12:13] op_sel_hi:[0,1,1]
	v_pk_fma_f32 v[6:7], v[38:39], v[20:21], v[6:7] op_sel_hi:[0,1,1]
	ds_read_b128 v[182:185], v3 offset:224
	ds_read_b128 v[186:189], v3 offset:240
	s_waitcnt lgkmcnt(4)
	v_mov_b32_e32 v30, v39
	v_pk_fma_f32 v[8:9], v[30:31], v[22:23], v[8:9] op_sel_hi:[0,1,1]
	v_pk_fma_f32 v[10:11], v[30:31], v[24:25], v[10:11] op_sel_hi:[0,1,1]
	v_pk_fma_f32 v[12:13], v[30:31], v[26:27], v[12:13] op_sel_hi:[0,1,1]
	v_pk_fma_f32 v[6:7], v[30:31], v[28:29], v[6:7] op_sel_hi:[0,1,1]
	ds_read_b128 v[14:17], v3 offset:256
	ds_read_b128 v[18:21], v3 offset:272
	s_waitcnt lgkmcnt(4)
	v_pk_fma_f32 v[8:9], v[40:41], v[174:175], v[8:9] op_sel_hi:[0,1,1]
	v_pk_fma_f32 v[10:11], v[40:41], v[176:177], v[10:11] op_sel_hi:[0,1,1]
	v_pk_fma_f32 v[12:13], v[40:41], v[178:179], v[12:13] op_sel_hi:[0,1,1]
	v_pk_fma_f32 v[6:7], v[40:41], v[180:181], v[6:7] op_sel_hi:[0,1,1]
	ds_read_b128 v[22:25], v3 offset:288
	ds_read_b128 v[26:29], v3 offset:304
	s_waitcnt lgkmcnt(4)
	v_mov_b32_e32 v32, v41
	v_pk_fma_f32 v[8:9], v[32:33], v[182:183], v[8:9] op_sel_hi:[0,1,1]
	v_pk_fma_f32 v[10:11], v[32:33], v[184:185], v[10:11] op_sel_hi:[0,1,1]
	v_pk_fma_f32 v[12:13], v[32:33], v[186:187], v[12:13] op_sel_hi:[0,1,1]
	v_pk_fma_f32 v[6:7], v[32:33], v[188:189], v[6:7] op_sel_hi:[0,1,1]
	ds_read_b128 v[174:177], v3 offset:320
	ds_read_b128 v[178:181], v3 offset:336
	s_waitcnt lgkmcnt(4)
	v_pk_fma_f32 v[8:9], v[42:43], v[14:15], v[8:9] op_sel_hi:[0,1,1]
	v_pk_fma_f32 v[10:11], v[42:43], v[16:17], v[10:11] op_sel_hi:[0,1,1]
	v_pk_fma_f32 v[12:13], v[42:43], v[18:19], v[12:13] op_sel_hi:[0,1,1]
	v_pk_fma_f32 v[6:7], v[42:43], v[20:21], v[6:7] op_sel_hi:[0,1,1]
	ds_read_b128 v[182:185], v3 offset:352
	ds_read_b128 v[186:189], v3 offset:368
	s_waitcnt lgkmcnt(4)
	v_mov_b32_e32 v30, v43
	v_pk_fma_f32 v[8:9], v[30:31], v[22:23], v[8:9] op_sel_hi:[0,1,1]
	v_pk_fma_f32 v[10:11], v[30:31], v[24:25], v[10:11] op_sel_hi:[0,1,1]
	v_pk_fma_f32 v[12:13], v[30:31], v[26:27], v[12:13] op_sel_hi:[0,1,1]
	v_pk_fma_f32 v[6:7], v[30:31], v[28:29], v[6:7] op_sel_hi:[0,1,1]
	ds_read_b128 v[14:17], v3 offset:384
	ds_read_b128 v[18:21], v3 offset:400
	s_waitcnt lgkmcnt(4)
	v_pk_fma_f32 v[8:9], v[44:45], v[174:175], v[8:9] op_sel_hi:[0,1,1]
	v_pk_fma_f32 v[10:11], v[44:45], v[176:177], v[10:11] op_sel_hi:[0,1,1]
	v_pk_fma_f32 v[12:13], v[44:45], v[178:179], v[12:13] op_sel_hi:[0,1,1]
	v_pk_fma_f32 v[6:7], v[44:45], v[180:181], v[6:7] op_sel_hi:[0,1,1]
	ds_read_b128 v[22:25], v3 offset:416
	ds_read_b128 v[26:29], v3 offset:432
	s_waitcnt lgkmcnt(4)
	v_mov_b32_e32 v32, v45
	v_pk_fma_f32 v[8:9], v[32:33], v[182:183], v[8:9] op_sel_hi:[0,1,1]
	v_pk_fma_f32 v[10:11], v[32:33], v[184:185], v[10:11] op_sel_hi:[0,1,1]
	v_pk_fma_f32 v[12:13], v[32:33], v[186:187], v[12:13] op_sel_hi:[0,1,1]
	v_pk_fma_f32 v[6:7], v[32:33], v[188:189], v[6:7] op_sel_hi:[0,1,1]
	ds_read_b128 v[174:177], v3 offset:448
	ds_read_b128 v[178:181], v3 offset:464
	s_waitcnt lgkmcnt(4)
	v_pk_fma_f32 v[8:9], v[46:47], v[14:15], v[8:9] op_sel_hi:[0,1,1]
	v_pk_fma_f32 v[10:11], v[46:47], v[16:17], v[10:11] op_sel_hi:[0,1,1]
	v_pk_fma_f32 v[12:13], v[46:47], v[18:19], v[12:13] op_sel_hi:[0,1,1]
	v_pk_fma_f32 v[6:7], v[46:47], v[20:21], v[6:7] op_sel_hi:[0,1,1]
	ds_read_b128 v[182:185], v3 offset:480
	ds_read_b128 v[186:189], v3 offset:496
	s_waitcnt lgkmcnt(4)
	v_mov_b32_e32 v30, v47
	v_pk_fma_f32 v[8:9], v[30:31], v[22:23], v[8:9] op_sel_hi:[0,1,1]
	v_pk_fma_f32 v[10:11], v[30:31], v[24:25], v[10:11] op_sel_hi:[0,1,1]
	v_pk_fma_f32 v[12:13], v[30:31], v[26:27], v[12:13] op_sel_hi:[0,1,1]
	v_pk_fma_f32 v[6:7], v[30:31], v[28:29], v[6:7] op_sel_hi:[0,1,1]
	ds_read_b128 v[14:17], v3 offset:512
	ds_read_b128 v[18:21], v3 offset:528
	s_waitcnt lgkmcnt(4)
	v_pk_fma_f32 v[8:9], v[48:49], v[174:175], v[8:9] op_sel_hi:[0,1,1]
	v_pk_fma_f32 v[10:11], v[48:49], v[176:177], v[10:11] op_sel_hi:[0,1,1]
	v_pk_fma_f32 v[12:13], v[48:49], v[178:179], v[12:13] op_sel_hi:[0,1,1]
	v_pk_fma_f32 v[6:7], v[48:49], v[180:181], v[6:7] op_sel_hi:[0,1,1]
	ds_read_b128 v[22:25], v3 offset:544
	ds_read_b128 v[26:29], v3 offset:560
	s_waitcnt lgkmcnt(4)
	v_mov_b32_e32 v32, v49
	v_pk_fma_f32 v[8:9], v[32:33], v[182:183], v[8:9] op_sel_hi:[0,1,1]
	v_pk_fma_f32 v[10:11], v[32:33], v[184:185], v[10:11] op_sel_hi:[0,1,1]
	v_pk_fma_f32 v[12:13], v[32:33], v[186:187], v[12:13] op_sel_hi:[0,1,1]
	v_pk_fma_f32 v[6:7], v[32:33], v[188:189], v[6:7] op_sel_hi:[0,1,1]
	ds_read_b128 v[174:177], v3 offset:576
	ds_read_b128 v[178:181], v3 offset:592
	s_waitcnt lgkmcnt(4)
	v_pk_fma_f32 v[8:9], v[50:51], v[14:15], v[8:9] op_sel_hi:[0,1,1]
	v_pk_fma_f32 v[10:11], v[50:51], v[16:17], v[10:11] op_sel_hi:[0,1,1]
	v_pk_fma_f32 v[12:13], v[50:51], v[18:19], v[12:13] op_sel_hi:[0,1,1]
	v_pk_fma_f32 v[6:7], v[50:51], v[20:21], v[6:7] op_sel_hi:[0,1,1]
	ds_read_b128 v[182:185], v3 offset:608
	ds_read_b128 v[186:189], v3 offset:624
	s_waitcnt lgkmcnt(4)
	v_mov_b32_e32 v30, v51
	v_pk_fma_f32 v[8:9], v[30:31], v[22:23], v[8:9] op_sel_hi:[0,1,1]
	v_pk_fma_f32 v[10:11], v[30:31], v[24:25], v[10:11] op_sel_hi:[0,1,1]
	v_pk_fma_f32 v[12:13], v[30:31], v[26:27], v[12:13] op_sel_hi:[0,1,1]
	v_pk_fma_f32 v[6:7], v[30:31], v[28:29], v[6:7] op_sel_hi:[0,1,1]
	ds_read_b128 v[14:17], v3 offset:640
	ds_read_b128 v[18:21], v3 offset:656
	s_waitcnt lgkmcnt(4)
	v_pk_fma_f32 v[8:9], v[52:53], v[174:175], v[8:9] op_sel_hi:[0,1,1]
	v_pk_fma_f32 v[10:11], v[52:53], v[176:177], v[10:11] op_sel_hi:[0,1,1]
	v_pk_fma_f32 v[12:13], v[52:53], v[178:179], v[12:13] op_sel_hi:[0,1,1]
	v_pk_fma_f32 v[6:7], v[52:53], v[180:181], v[6:7] op_sel_hi:[0,1,1]
	ds_read_b128 v[22:25], v3 offset:672
	ds_read_b128 v[26:29], v3 offset:688
	s_waitcnt lgkmcnt(4)
	v_mov_b32_e32 v32, v53
	v_pk_fma_f32 v[8:9], v[32:33], v[182:183], v[8:9] op_sel_hi:[0,1,1]
	v_pk_fma_f32 v[10:11], v[32:33], v[184:185], v[10:11] op_sel_hi:[0,1,1]
	v_pk_fma_f32 v[12:13], v[32:33], v[186:187], v[12:13] op_sel_hi:[0,1,1]
	v_pk_fma_f32 v[6:7], v[32:33], v[188:189], v[6:7] op_sel_hi:[0,1,1]
	ds_read_b128 v[174:177], v3 offset:704
	ds_read_b128 v[178:181], v3 offset:720
	s_waitcnt lgkmcnt(4)
	v_pk_fma_f32 v[8:9], v[54:55], v[14:15], v[8:9] op_sel_hi:[0,1,1]
	v_pk_fma_f32 v[10:11], v[54:55], v[16:17], v[10:11] op_sel_hi:[0,1,1]
	v_pk_fma_f32 v[12:13], v[54:55], v[18:19], v[12:13] op_sel_hi:[0,1,1]
	v_pk_fma_f32 v[6:7], v[54:55], v[20:21], v[6:7] op_sel_hi:[0,1,1]
	ds_read_b128 v[182:185], v3 offset:736
	ds_read_b128 v[186:189], v3 offset:752
	s_waitcnt lgkmcnt(4)
	v_mov_b32_e32 v30, v55
	v_pk_fma_f32 v[8:9], v[30:31], v[22:23], v[8:9] op_sel_hi:[0,1,1]
	v_pk_fma_f32 v[10:11], v[30:31], v[24:25], v[10:11] op_sel_hi:[0,1,1]
	v_pk_fma_f32 v[12:13], v[30:31], v[26:27], v[12:13] op_sel_hi:[0,1,1]
	v_pk_fma_f32 v[6:7], v[30:31], v[28:29], v[6:7] op_sel_hi:[0,1,1]
	ds_read_b128 v[14:17], v3 offset:768
	ds_read_b128 v[18:21], v3 offset:784
	s_waitcnt lgkmcnt(4)
	v_pk_fma_f32 v[8:9], v[56:57], v[174:175], v[8:9] op_sel_hi:[0,1,1]
	v_pk_fma_f32 v[10:11], v[56:57], v[176:177], v[10:11] op_sel_hi:[0,1,1]
	v_pk_fma_f32 v[12:13], v[56:57], v[178:179], v[12:13] op_sel_hi:[0,1,1]
	v_pk_fma_f32 v[6:7], v[56:57], v[180:181], v[6:7] op_sel_hi:[0,1,1]
	ds_read_b128 v[22:25], v3 offset:800
	ds_read_b128 v[26:29], v3 offset:816
	s_waitcnt lgkmcnt(4)
	v_mov_b32_e32 v32, v57
	v_pk_fma_f32 v[8:9], v[32:33], v[182:183], v[8:9] op_sel_hi:[0,1,1]
	v_pk_fma_f32 v[10:11], v[32:33], v[184:185], v[10:11] op_sel_hi:[0,1,1]
	v_pk_fma_f32 v[12:13], v[32:33], v[186:187], v[12:13] op_sel_hi:[0,1,1]
	v_pk_fma_f32 v[6:7], v[32:33], v[188:189], v[6:7] op_sel_hi:[0,1,1]
	ds_read_b128 v[174:177], v3 offset:832
	ds_read_b128 v[178:181], v3 offset:848
	s_waitcnt lgkmcnt(4)
	v_pk_fma_f32 v[8:9], v[58:59], v[14:15], v[8:9] op_sel_hi:[0,1,1]
	v_pk_fma_f32 v[10:11], v[58:59], v[16:17], v[10:11] op_sel_hi:[0,1,1]
	v_pk_fma_f32 v[12:13], v[58:59], v[18:19], v[12:13] op_sel_hi:[0,1,1]
	v_pk_fma_f32 v[6:7], v[58:59], v[20:21], v[6:7] op_sel_hi:[0,1,1]
	ds_read_b128 v[182:185], v3 offset:864
	ds_read_b128 v[186:189], v3 offset:880
	s_waitcnt lgkmcnt(4)
	v_mov_b32_e32 v30, v59
	v_pk_fma_f32 v[8:9], v[30:31], v[22:23], v[8:9] op_sel_hi:[0,1,1]
	v_pk_fma_f32 v[10:11], v[30:31], v[24:25], v[10:11] op_sel_hi:[0,1,1]
	v_pk_fma_f32 v[12:13], v[30:31], v[26:27], v[12:13] op_sel_hi:[0,1,1]
	v_pk_fma_f32 v[6:7], v[30:31], v[28:29], v[6:7] op_sel_hi:[0,1,1]
	ds_read_b128 v[14:17], v3 offset:896
	ds_read_b128 v[18:21], v3 offset:912
	s_waitcnt lgkmcnt(4)
	v_pk_fma_f32 v[8:9], v[60:61], v[174:175], v[8:9] op_sel_hi:[0,1,1]
	v_pk_fma_f32 v[10:11], v[60:61], v[176:177], v[10:11] op_sel_hi:[0,1,1]
	v_pk_fma_f32 v[12:13], v[60:61], v[178:179], v[12:13] op_sel_hi:[0,1,1]
	v_pk_fma_f32 v[6:7], v[60:61], v[180:181], v[6:7] op_sel_hi:[0,1,1]
	ds_read_b128 v[22:25], v3 offset:928
	ds_read_b128 v[26:29], v3 offset:944
	s_waitcnt lgkmcnt(4)
	v_mov_b32_e32 v32, v61
	v_pk_fma_f32 v[8:9], v[32:33], v[182:183], v[8:9] op_sel_hi:[0,1,1]
	v_pk_fma_f32 v[10:11], v[32:33], v[184:185], v[10:11] op_sel_hi:[0,1,1]
	v_pk_fma_f32 v[12:13], v[32:33], v[186:187], v[12:13] op_sel_hi:[0,1,1]
	v_pk_fma_f32 v[6:7], v[32:33], v[188:189], v[6:7] op_sel_hi:[0,1,1]
	ds_read_b128 v[174:177], v3 offset:960
	ds_read_b128 v[178:181], v3 offset:976
	s_waitcnt lgkmcnt(4)
	v_pk_fma_f32 v[8:9], v[62:63], v[14:15], v[8:9] op_sel_hi:[0,1,1]
	v_pk_fma_f32 v[10:11], v[62:63], v[16:17], v[10:11] op_sel_hi:[0,1,1]
	v_pk_fma_f32 v[12:13], v[62:63], v[18:19], v[12:13] op_sel_hi:[0,1,1]
	v_pk_fma_f32 v[6:7], v[62:63], v[20:21], v[6:7] op_sel_hi:[0,1,1]
	ds_read_b128 v[182:185], v3 offset:992
	ds_read_b128 v[186:189], v3 offset:1008
	s_waitcnt lgkmcnt(4)
	v_mov_b32_e32 v30, v63
	v_pk_fma_f32 v[8:9], v[30:31], v[22:23], v[8:9] op_sel_hi:[0,1,1]
	v_pk_fma_f32 v[10:11], v[30:31], v[24:25], v[10:11] op_sel_hi:[0,1,1]
	v_pk_fma_f32 v[12:13], v[30:31], v[26:27], v[12:13] op_sel_hi:[0,1,1]
	v_pk_fma_f32 v[6:7], v[30:31], v[28:29], v[6:7] op_sel_hi:[0,1,1]
	ds_read_b128 v[14:17], v3 offset:1024
	ds_read_b128 v[18:21], v3 offset:1040
	s_waitcnt lgkmcnt(4)
	v_pk_fma_f32 v[8:9], v[64:65], v[174:175], v[8:9] op_sel_hi:[0,1,1]
	v_pk_fma_f32 v[10:11], v[64:65], v[176:177], v[10:11] op_sel_hi:[0,1,1]
	v_pk_fma_f32 v[12:13], v[64:65], v[178:179], v[12:13] op_sel_hi:[0,1,1]
	v_pk_fma_f32 v[6:7], v[64:65], v[180:181], v[6:7] op_sel_hi:[0,1,1]
	ds_read_b128 v[22:25], v3 offset:1056
	ds_read_b128 v[26:29], v3 offset:1072
	s_waitcnt lgkmcnt(4)
	v_mov_b32_e32 v32, v65
	v_pk_fma_f32 v[8:9], v[32:33], v[182:183], v[8:9] op_sel_hi:[0,1,1]
	v_pk_fma_f32 v[10:11], v[32:33], v[184:185], v[10:11] op_sel_hi:[0,1,1]
	v_pk_fma_f32 v[12:13], v[32:33], v[186:187], v[12:13] op_sel_hi:[0,1,1]
	v_pk_fma_f32 v[6:7], v[32:33], v[188:189], v[6:7] op_sel_hi:[0,1,1]
	ds_read_b128 v[174:177], v3 offset:1088
	ds_read_b128 v[178:181], v3 offset:1104
	s_waitcnt lgkmcnt(4)
	v_pk_fma_f32 v[8:9], v[66:67], v[14:15], v[8:9] op_sel_hi:[0,1,1]
	v_pk_fma_f32 v[10:11], v[66:67], v[16:17], v[10:11] op_sel_hi:[0,1,1]
	v_pk_fma_f32 v[12:13], v[66:67], v[18:19], v[12:13] op_sel_hi:[0,1,1]
	v_pk_fma_f32 v[6:7], v[66:67], v[20:21], v[6:7] op_sel_hi:[0,1,1]
	ds_read_b128 v[182:185], v3 offset:1120
	ds_read_b128 v[186:189], v3 offset:1136
	s_waitcnt lgkmcnt(4)
	v_mov_b32_e32 v30, v67
	v_pk_fma_f32 v[8:9], v[30:31], v[22:23], v[8:9] op_sel_hi:[0,1,1]
	v_pk_fma_f32 v[10:11], v[30:31], v[24:25], v[10:11] op_sel_hi:[0,1,1]
	v_pk_fma_f32 v[12:13], v[30:31], v[26:27], v[12:13] op_sel_hi:[0,1,1]
	v_pk_fma_f32 v[6:7], v[30:31], v[28:29], v[6:7] op_sel_hi:[0,1,1]
	ds_read_b128 v[14:17], v3 offset:1152
	ds_read_b128 v[18:21], v3 offset:1168
	s_waitcnt lgkmcnt(4)
	v_pk_fma_f32 v[8:9], v[68:69], v[174:175], v[8:9] op_sel_hi:[0,1,1]
	v_pk_fma_f32 v[10:11], v[68:69], v[176:177], v[10:11] op_sel_hi:[0,1,1]
	v_pk_fma_f32 v[12:13], v[68:69], v[178:179], v[12:13] op_sel_hi:[0,1,1]
	v_pk_fma_f32 v[6:7], v[68:69], v[180:181], v[6:7] op_sel_hi:[0,1,1]
	ds_read_b128 v[22:25], v3 offset:1184
	ds_read_b128 v[26:29], v3 offset:1200
	s_waitcnt lgkmcnt(4)
	v_mov_b32_e32 v32, v69
	v_pk_fma_f32 v[8:9], v[32:33], v[182:183], v[8:9] op_sel_hi:[0,1,1]
	v_pk_fma_f32 v[10:11], v[32:33], v[184:185], v[10:11] op_sel_hi:[0,1,1]
	v_pk_fma_f32 v[12:13], v[32:33], v[186:187], v[12:13] op_sel_hi:[0,1,1]
	v_pk_fma_f32 v[6:7], v[32:33], v[188:189], v[6:7] op_sel_hi:[0,1,1]
	ds_read_b128 v[174:177], v3 offset:1216
	ds_read_b128 v[178:181], v3 offset:1232
	s_waitcnt lgkmcnt(4)
	v_pk_fma_f32 v[8:9], v[70:71], v[14:15], v[8:9] op_sel_hi:[0,1,1]
	v_pk_fma_f32 v[10:11], v[70:71], v[16:17], v[10:11] op_sel_hi:[0,1,1]
	v_pk_fma_f32 v[12:13], v[70:71], v[18:19], v[12:13] op_sel_hi:[0,1,1]
	v_pk_fma_f32 v[6:7], v[70:71], v[20:21], v[6:7] op_sel_hi:[0,1,1]
	ds_read_b128 v[182:185], v3 offset:1248
	ds_read_b128 v[186:189], v3 offset:1264
	s_waitcnt lgkmcnt(4)
	v_mov_b32_e32 v30, v71
	v_pk_fma_f32 v[8:9], v[30:31], v[22:23], v[8:9] op_sel_hi:[0,1,1]
	v_pk_fma_f32 v[10:11], v[30:31], v[24:25], v[10:11] op_sel_hi:[0,1,1]
	v_pk_fma_f32 v[12:13], v[30:31], v[26:27], v[12:13] op_sel_hi:[0,1,1]
	v_pk_fma_f32 v[6:7], v[30:31], v[28:29], v[6:7] op_sel_hi:[0,1,1]
	ds_read_b128 v[14:17], v3 offset:1280
	ds_read_b128 v[18:21], v3 offset:1296
	s_waitcnt lgkmcnt(4)
	v_pk_fma_f32 v[8:9], v[72:73], v[174:175], v[8:9] op_sel_hi:[0,1,1]
	v_pk_fma_f32 v[10:11], v[72:73], v[176:177], v[10:11] op_sel_hi:[0,1,1]
	v_pk_fma_f32 v[12:13], v[72:73], v[178:179], v[12:13] op_sel_hi:[0,1,1]
	v_pk_fma_f32 v[6:7], v[72:73], v[180:181], v[6:7] op_sel_hi:[0,1,1]
	ds_read_b128 v[22:25], v3 offset:1312
	ds_read_b128 v[26:29], v3 offset:1328
	s_waitcnt lgkmcnt(4)
	v_mov_b32_e32 v32, v73
	v_pk_fma_f32 v[8:9], v[32:33], v[182:183], v[8:9] op_sel_hi:[0,1,1]
	v_pk_fma_f32 v[10:11], v[32:33], v[184:185], v[10:11] op_sel_hi:[0,1,1]
	v_pk_fma_f32 v[12:13], v[32:33], v[186:187], v[12:13] op_sel_hi:[0,1,1]
	v_pk_fma_f32 v[6:7], v[32:33], v[188:189], v[6:7] op_sel_hi:[0,1,1]
	ds_read_b128 v[174:177], v3 offset:1344
	ds_read_b128 v[178:181], v3 offset:1360
	s_waitcnt lgkmcnt(4)
	v_pk_fma_f32 v[8:9], v[74:75], v[14:15], v[8:9] op_sel_hi:[0,1,1]
	v_pk_fma_f32 v[10:11], v[74:75], v[16:17], v[10:11] op_sel_hi:[0,1,1]
	v_pk_fma_f32 v[12:13], v[74:75], v[18:19], v[12:13] op_sel_hi:[0,1,1]
	v_pk_fma_f32 v[6:7], v[74:75], v[20:21], v[6:7] op_sel_hi:[0,1,1]
	ds_read_b128 v[182:185], v3 offset:1376
	ds_read_b128 v[186:189], v3 offset:1392
	s_waitcnt lgkmcnt(4)
	v_mov_b32_e32 v30, v75
	v_pk_fma_f32 v[8:9], v[30:31], v[22:23], v[8:9] op_sel_hi:[0,1,1]
	v_pk_fma_f32 v[10:11], v[30:31], v[24:25], v[10:11] op_sel_hi:[0,1,1]
	v_pk_fma_f32 v[12:13], v[30:31], v[26:27], v[12:13] op_sel_hi:[0,1,1]
	v_pk_fma_f32 v[6:7], v[30:31], v[28:29], v[6:7] op_sel_hi:[0,1,1]
	ds_read_b128 v[14:17], v3 offset:1408
	ds_read_b128 v[18:21], v3 offset:1424
	s_waitcnt lgkmcnt(4)
	v_pk_fma_f32 v[8:9], v[76:77], v[174:175], v[8:9] op_sel_hi:[0,1,1]
	v_pk_fma_f32 v[10:11], v[76:77], v[176:177], v[10:11] op_sel_hi:[0,1,1]
	v_pk_fma_f32 v[12:13], v[76:77], v[178:179], v[12:13] op_sel_hi:[0,1,1]
	v_pk_fma_f32 v[6:7], v[76:77], v[180:181], v[6:7] op_sel_hi:[0,1,1]
	ds_read_b128 v[22:25], v3 offset:1440
	ds_read_b128 v[26:29], v3 offset:1456
	s_waitcnt lgkmcnt(4)
	v_mov_b32_e32 v32, v77
	v_pk_fma_f32 v[8:9], v[32:33], v[182:183], v[8:9] op_sel_hi:[0,1,1]
	v_pk_fma_f32 v[10:11], v[32:33], v[184:185], v[10:11] op_sel_hi:[0,1,1]
	v_pk_fma_f32 v[12:13], v[32:33], v[186:187], v[12:13] op_sel_hi:[0,1,1]
	v_pk_fma_f32 v[6:7], v[32:33], v[188:189], v[6:7] op_sel_hi:[0,1,1]
	ds_read_b128 v[174:177], v3 offset:1472
	ds_read_b128 v[178:181], v3 offset:1488
	s_waitcnt lgkmcnt(4)
	v_pk_fma_f32 v[8:9], v[78:79], v[14:15], v[8:9] op_sel_hi:[0,1,1]
	v_pk_fma_f32 v[10:11], v[78:79], v[16:17], v[10:11] op_sel_hi:[0,1,1]
	v_pk_fma_f32 v[12:13], v[78:79], v[18:19], v[12:13] op_sel_hi:[0,1,1]
	v_pk_fma_f32 v[6:7], v[78:79], v[20:21], v[6:7] op_sel_hi:[0,1,1]
	ds_read_b128 v[182:185], v3 offset:1504
	ds_read_b128 v[186:189], v3 offset:1520
	s_waitcnt lgkmcnt(4)
	v_mov_b32_e32 v30, v79
	v_pk_fma_f32 v[8:9], v[30:31], v[22:23], v[8:9] op_sel_hi:[0,1,1]
	v_pk_fma_f32 v[10:11], v[30:31], v[24:25], v[10:11] op_sel_hi:[0,1,1]
	v_pk_fma_f32 v[12:13], v[30:31], v[26:27], v[12:13] op_sel_hi:[0,1,1]
	v_pk_fma_f32 v[6:7], v[30:31], v[28:29], v[6:7] op_sel_hi:[0,1,1]
	ds_read_b128 v[14:17], v3 offset:1536
	ds_read_b128 v[18:21], v3 offset:1552
	s_waitcnt lgkmcnt(4)
	v_pk_fma_f32 v[8:9], v[80:81], v[174:175], v[8:9] op_sel_hi:[0,1,1]
	v_pk_fma_f32 v[10:11], v[80:81], v[176:177], v[10:11] op_sel_hi:[0,1,1]
	v_pk_fma_f32 v[12:13], v[80:81], v[178:179], v[12:13] op_sel_hi:[0,1,1]
	v_pk_fma_f32 v[6:7], v[80:81], v[180:181], v[6:7] op_sel_hi:[0,1,1]
	ds_read_b128 v[22:25], v3 offset:1568
	ds_read_b128 v[26:29], v3 offset:1584
	s_waitcnt lgkmcnt(4)
	v_mov_b32_e32 v32, v81
	v_pk_fma_f32 v[8:9], v[32:33], v[182:183], v[8:9] op_sel_hi:[0,1,1]
	v_pk_fma_f32 v[10:11], v[32:33], v[184:185], v[10:11] op_sel_hi:[0,1,1]
	v_pk_fma_f32 v[12:13], v[32:33], v[186:187], v[12:13] op_sel_hi:[0,1,1]
	v_pk_fma_f32 v[6:7], v[32:33], v[188:189], v[6:7] op_sel_hi:[0,1,1]
	ds_read_b128 v[174:177], v3 offset:1600
	ds_read_b128 v[178:181], v3 offset:1616
	s_waitcnt lgkmcnt(4)
	v_pk_fma_f32 v[8:9], v[82:83], v[14:15], v[8:9] op_sel_hi:[0,1,1]
	v_pk_fma_f32 v[10:11], v[82:83], v[16:17], v[10:11] op_sel_hi:[0,1,1]
	v_pk_fma_f32 v[12:13], v[82:83], v[18:19], v[12:13] op_sel_hi:[0,1,1]
	v_pk_fma_f32 v[6:7], v[82:83], v[20:21], v[6:7] op_sel_hi:[0,1,1]
	ds_read_b128 v[182:185], v3 offset:1632
	ds_read_b128 v[186:189], v3 offset:1648
	s_waitcnt lgkmcnt(4)
	v_mov_b32_e32 v30, v83
	v_pk_fma_f32 v[8:9], v[30:31], v[22:23], v[8:9] op_sel_hi:[0,1,1]
	v_pk_fma_f32 v[10:11], v[30:31], v[24:25], v[10:11] op_sel_hi:[0,1,1]
	v_pk_fma_f32 v[12:13], v[30:31], v[26:27], v[12:13] op_sel_hi:[0,1,1]
	v_pk_fma_f32 v[6:7], v[30:31], v[28:29], v[6:7] op_sel_hi:[0,1,1]
	ds_read_b128 v[14:17], v3 offset:1664
	ds_read_b128 v[18:21], v3 offset:1680
	s_waitcnt lgkmcnt(4)
	v_pk_fma_f32 v[8:9], v[84:85], v[174:175], v[8:9] op_sel_hi:[0,1,1]
	v_pk_fma_f32 v[10:11], v[84:85], v[176:177], v[10:11] op_sel_hi:[0,1,1]
	v_pk_fma_f32 v[12:13], v[84:85], v[178:179], v[12:13] op_sel_hi:[0,1,1]
	v_pk_fma_f32 v[6:7], v[84:85], v[180:181], v[6:7] op_sel_hi:[0,1,1]
	ds_read_b128 v[22:25], v3 offset:1696
	ds_read_b128 v[26:29], v3 offset:1712
	s_waitcnt lgkmcnt(4)
	v_mov_b32_e32 v32, v85
	v_pk_fma_f32 v[8:9], v[32:33], v[182:183], v[8:9] op_sel_hi:[0,1,1]
	v_pk_fma_f32 v[10:11], v[32:33], v[184:185], v[10:11] op_sel_hi:[0,1,1]
	v_pk_fma_f32 v[12:13], v[32:33], v[186:187], v[12:13] op_sel_hi:[0,1,1]
	v_pk_fma_f32 v[6:7], v[32:33], v[188:189], v[6:7] op_sel_hi:[0,1,1]
	ds_read_b128 v[174:177], v3 offset:1728
	ds_read_b128 v[178:181], v3 offset:1744
	s_waitcnt lgkmcnt(4)
	v_pk_fma_f32 v[8:9], v[86:87], v[14:15], v[8:9] op_sel_hi:[0,1,1]
	v_pk_fma_f32 v[10:11], v[86:87], v[16:17], v[10:11] op_sel_hi:[0,1,1]
	v_pk_fma_f32 v[12:13], v[86:87], v[18:19], v[12:13] op_sel_hi:[0,1,1]
	v_pk_fma_f32 v[6:7], v[86:87], v[20:21], v[6:7] op_sel_hi:[0,1,1]
	ds_read_b128 v[182:185], v3 offset:1760
	ds_read_b128 v[186:189], v3 offset:1776
	s_waitcnt lgkmcnt(4)
	v_mov_b32_e32 v30, v87
	v_pk_fma_f32 v[8:9], v[30:31], v[22:23], v[8:9] op_sel_hi:[0,1,1]
	v_pk_fma_f32 v[10:11], v[30:31], v[24:25], v[10:11] op_sel_hi:[0,1,1]
	v_pk_fma_f32 v[12:13], v[30:31], v[26:27], v[12:13] op_sel_hi:[0,1,1]
	v_pk_fma_f32 v[6:7], v[30:31], v[28:29], v[6:7] op_sel_hi:[0,1,1]
	ds_read_b128 v[14:17], v3 offset:1792
	ds_read_b128 v[18:21], v3 offset:1808
	s_waitcnt lgkmcnt(4)
	v_pk_fma_f32 v[8:9], v[88:89], v[174:175], v[8:9] op_sel_hi:[0,1,1]
	v_pk_fma_f32 v[10:11], v[88:89], v[176:177], v[10:11] op_sel_hi:[0,1,1]
	v_pk_fma_f32 v[12:13], v[88:89], v[178:179], v[12:13] op_sel_hi:[0,1,1]
	v_pk_fma_f32 v[6:7], v[88:89], v[180:181], v[6:7] op_sel_hi:[0,1,1]
	ds_read_b128 v[22:25], v3 offset:1824
	ds_read_b128 v[26:29], v3 offset:1840
	s_waitcnt lgkmcnt(4)
	v_mov_b32_e32 v32, v89
	v_pk_fma_f32 v[8:9], v[32:33], v[182:183], v[8:9] op_sel_hi:[0,1,1]
	v_pk_fma_f32 v[10:11], v[32:33], v[184:185], v[10:11] op_sel_hi:[0,1,1]
	v_pk_fma_f32 v[12:13], v[32:33], v[186:187], v[12:13] op_sel_hi:[0,1,1]
	v_pk_fma_f32 v[6:7], v[32:33], v[188:189], v[6:7] op_sel_hi:[0,1,1]
	ds_read_b128 v[174:177], v3 offset:1856
	ds_read_b128 v[178:181], v3 offset:1872
	s_waitcnt lgkmcnt(4)
	v_pk_fma_f32 v[8:9], v[90:91], v[14:15], v[8:9] op_sel_hi:[0,1,1]
	v_pk_fma_f32 v[10:11], v[90:91], v[16:17], v[10:11] op_sel_hi:[0,1,1]
	v_pk_fma_f32 v[12:13], v[90:91], v[18:19], v[12:13] op_sel_hi:[0,1,1]
	v_pk_fma_f32 v[6:7], v[90:91], v[20:21], v[6:7] op_sel_hi:[0,1,1]
	ds_read_b128 v[182:185], v3 offset:1888
	ds_read_b128 v[186:189], v3 offset:1904
	s_waitcnt lgkmcnt(4)
	v_mov_b32_e32 v30, v91
	v_pk_fma_f32 v[8:9], v[30:31], v[22:23], v[8:9] op_sel_hi:[0,1,1]
	v_pk_fma_f32 v[10:11], v[30:31], v[24:25], v[10:11] op_sel_hi:[0,1,1]
	v_pk_fma_f32 v[12:13], v[30:31], v[26:27], v[12:13] op_sel_hi:[0,1,1]
	v_pk_fma_f32 v[6:7], v[30:31], v[28:29], v[6:7] op_sel_hi:[0,1,1]
	ds_read_b128 v[14:17], v3 offset:1920
	ds_read_b128 v[18:21], v3 offset:1936
	s_waitcnt lgkmcnt(4)
	v_pk_fma_f32 v[8:9], v[92:93], v[174:175], v[8:9] op_sel_hi:[0,1,1]
	v_pk_fma_f32 v[10:11], v[92:93], v[176:177], v[10:11] op_sel_hi:[0,1,1]
	v_pk_fma_f32 v[12:13], v[92:93], v[178:179], v[12:13] op_sel_hi:[0,1,1]
	v_pk_fma_f32 v[6:7], v[92:93], v[180:181], v[6:7] op_sel_hi:[0,1,1]
	ds_read_b128 v[22:25], v3 offset:1952
	ds_read_b128 v[26:29], v3 offset:1968
	s_waitcnt lgkmcnt(4)
	v_mov_b32_e32 v32, v93
	v_pk_fma_f32 v[8:9], v[32:33], v[182:183], v[8:9] op_sel_hi:[0,1,1]
	v_pk_fma_f32 v[10:11], v[32:33], v[184:185], v[10:11] op_sel_hi:[0,1,1]
	v_pk_fma_f32 v[12:13], v[32:33], v[186:187], v[12:13] op_sel_hi:[0,1,1]
	v_pk_fma_f32 v[6:7], v[32:33], v[188:189], v[6:7] op_sel_hi:[0,1,1]
	ds_read_b128 v[174:177], v3 offset:1984
	ds_read_b128 v[178:181], v3 offset:2000
	s_waitcnt lgkmcnt(4)
	v_pk_fma_f32 v[8:9], v[94:95], v[14:15], v[8:9] op_sel_hi:[0,1,1]
	v_pk_fma_f32 v[10:11], v[94:95], v[16:17], v[10:11] op_sel_hi:[0,1,1]
	v_pk_fma_f32 v[12:13], v[94:95], v[18:19], v[12:13] op_sel_hi:[0,1,1]
	v_pk_fma_f32 v[6:7], v[94:95], v[20:21], v[6:7] op_sel_hi:[0,1,1]
	ds_read_b128 v[182:185], v3 offset:2016
	ds_read_b128 v[186:189], v3 offset:2032
	s_waitcnt lgkmcnt(4)
	v_mov_b32_e32 v30, v95
	v_pk_fma_f32 v[8:9], v[30:31], v[22:23], v[8:9] op_sel_hi:[0,1,1]
	v_pk_fma_f32 v[10:11], v[30:31], v[24:25], v[10:11] op_sel_hi:[0,1,1]
	v_pk_fma_f32 v[12:13], v[30:31], v[26:27], v[12:13] op_sel_hi:[0,1,1]
	v_pk_fma_f32 v[6:7], v[30:31], v[28:29], v[6:7] op_sel_hi:[0,1,1]
	ds_read_b128 v[14:17], v3 offset:2048
	ds_read_b128 v[18:21], v3 offset:2064
	s_waitcnt lgkmcnt(4)
	v_pk_fma_f32 v[8:9], v[96:97], v[174:175], v[8:9] op_sel_hi:[0,1,1]
	v_pk_fma_f32 v[10:11], v[96:97], v[176:177], v[10:11] op_sel_hi:[0,1,1]
	v_pk_fma_f32 v[12:13], v[96:97], v[178:179], v[12:13] op_sel_hi:[0,1,1]
	v_pk_fma_f32 v[6:7], v[96:97], v[180:181], v[6:7] op_sel_hi:[0,1,1]
	ds_read_b128 v[22:25], v3 offset:2080
	ds_read_b128 v[26:29], v3 offset:2096
	s_waitcnt lgkmcnt(4)
	v_mov_b32_e32 v32, v97
	v_pk_fma_f32 v[8:9], v[32:33], v[182:183], v[8:9] op_sel_hi:[0,1,1]
	v_pk_fma_f32 v[10:11], v[32:33], v[184:185], v[10:11] op_sel_hi:[0,1,1]
	v_pk_fma_f32 v[12:13], v[32:33], v[186:187], v[12:13] op_sel_hi:[0,1,1]
	v_pk_fma_f32 v[6:7], v[32:33], v[188:189], v[6:7] op_sel_hi:[0,1,1]
	ds_read_b128 v[174:177], v3 offset:2112
	ds_read_b128 v[178:181], v3 offset:2128
	s_waitcnt lgkmcnt(4)
	v_pk_fma_f32 v[8:9], v[98:99], v[14:15], v[8:9] op_sel_hi:[0,1,1]
	v_pk_fma_f32 v[10:11], v[98:99], v[16:17], v[10:11] op_sel_hi:[0,1,1]
	v_pk_fma_f32 v[12:13], v[98:99], v[18:19], v[12:13] op_sel_hi:[0,1,1]
	v_pk_fma_f32 v[6:7], v[98:99], v[20:21], v[6:7] op_sel_hi:[0,1,1]
	ds_read_b128 v[182:185], v3 offset:2144
	ds_read_b128 v[186:189], v3 offset:2160
	s_waitcnt lgkmcnt(4)
	v_mov_b32_e32 v30, v99
	v_pk_fma_f32 v[8:9], v[30:31], v[22:23], v[8:9] op_sel_hi:[0,1,1]
	v_pk_fma_f32 v[10:11], v[30:31], v[24:25], v[10:11] op_sel_hi:[0,1,1]
	v_pk_fma_f32 v[12:13], v[30:31], v[26:27], v[12:13] op_sel_hi:[0,1,1]
	v_pk_fma_f32 v[6:7], v[30:31], v[28:29], v[6:7] op_sel_hi:[0,1,1]
	ds_read_b128 v[14:17], v3 offset:2176
	ds_read_b128 v[18:21], v3 offset:2192
	s_waitcnt lgkmcnt(4)
	v_pk_fma_f32 v[8:9], v[100:101], v[174:175], v[8:9] op_sel_hi:[0,1,1]
	v_pk_fma_f32 v[10:11], v[100:101], v[176:177], v[10:11] op_sel_hi:[0,1,1]
	v_pk_fma_f32 v[12:13], v[100:101], v[178:179], v[12:13] op_sel_hi:[0,1,1]
	v_pk_fma_f32 v[6:7], v[100:101], v[180:181], v[6:7] op_sel_hi:[0,1,1]
	ds_read_b128 v[22:25], v3 offset:2208
	ds_read_b128 v[26:29], v3 offset:2224
	s_waitcnt lgkmcnt(4)
	v_mov_b32_e32 v32, v101
	v_pk_fma_f32 v[8:9], v[32:33], v[182:183], v[8:9] op_sel_hi:[0,1,1]
	v_pk_fma_f32 v[10:11], v[32:33], v[184:185], v[10:11] op_sel_hi:[0,1,1]
	v_pk_fma_f32 v[12:13], v[32:33], v[186:187], v[12:13] op_sel_hi:[0,1,1]
	v_pk_fma_f32 v[6:7], v[32:33], v[188:189], v[6:7] op_sel_hi:[0,1,1]
	ds_read_b128 v[174:177], v3 offset:2240
	ds_read_b128 v[178:181], v3 offset:2256
	s_waitcnt lgkmcnt(4)
	v_pk_fma_f32 v[8:9], v[102:103], v[14:15], v[8:9] op_sel_hi:[0,1,1]
	v_pk_fma_f32 v[10:11], v[102:103], v[16:17], v[10:11] op_sel_hi:[0,1,1]
	v_pk_fma_f32 v[12:13], v[102:103], v[18:19], v[12:13] op_sel_hi:[0,1,1]
	v_pk_fma_f32 v[6:7], v[102:103], v[20:21], v[6:7] op_sel_hi:[0,1,1]
	ds_read_b128 v[182:185], v3 offset:2272
	ds_read_b128 v[186:189], v3 offset:2288
	s_waitcnt lgkmcnt(4)
	v_mov_b32_e32 v30, v103
	v_pk_fma_f32 v[8:9], v[30:31], v[22:23], v[8:9] op_sel_hi:[0,1,1]
	v_pk_fma_f32 v[10:11], v[30:31], v[24:25], v[10:11] op_sel_hi:[0,1,1]
	v_pk_fma_f32 v[12:13], v[30:31], v[26:27], v[12:13] op_sel_hi:[0,1,1]
	v_pk_fma_f32 v[6:7], v[30:31], v[28:29], v[6:7] op_sel_hi:[0,1,1]
	ds_read_b128 v[14:17], v3 offset:2304
	ds_read_b128 v[18:21], v3 offset:2320
	s_waitcnt lgkmcnt(4)
	v_pk_fma_f32 v[8:9], v[104:105], v[174:175], v[8:9] op_sel_hi:[0,1,1]
	v_pk_fma_f32 v[10:11], v[104:105], v[176:177], v[10:11] op_sel_hi:[0,1,1]
	v_pk_fma_f32 v[12:13], v[104:105], v[178:179], v[12:13] op_sel_hi:[0,1,1]
	v_pk_fma_f32 v[6:7], v[104:105], v[180:181], v[6:7] op_sel_hi:[0,1,1]
	ds_read_b128 v[22:25], v3 offset:2336
	ds_read_b128 v[26:29], v3 offset:2352
	s_waitcnt lgkmcnt(4)
	v_mov_b32_e32 v32, v105
	v_pk_fma_f32 v[8:9], v[32:33], v[182:183], v[8:9] op_sel_hi:[0,1,1]
	v_pk_fma_f32 v[10:11], v[32:33], v[184:185], v[10:11] op_sel_hi:[0,1,1]
	v_pk_fma_f32 v[12:13], v[32:33], v[186:187], v[12:13] op_sel_hi:[0,1,1]
	v_pk_fma_f32 v[6:7], v[32:33], v[188:189], v[6:7] op_sel_hi:[0,1,1]
	ds_read_b128 v[174:177], v3 offset:2368
	ds_read_b128 v[178:181], v3 offset:2384
	s_waitcnt lgkmcnt(4)
	v_pk_fma_f32 v[8:9], v[106:107], v[14:15], v[8:9] op_sel_hi:[0,1,1]
	v_pk_fma_f32 v[10:11], v[106:107], v[16:17], v[10:11] op_sel_hi:[0,1,1]
	v_pk_fma_f32 v[12:13], v[106:107], v[18:19], v[12:13] op_sel_hi:[0,1,1]
	v_pk_fma_f32 v[6:7], v[106:107], v[20:21], v[6:7] op_sel_hi:[0,1,1]
	ds_read_b128 v[182:185], v3 offset:2400
	ds_read_b128 v[186:189], v3 offset:2416
	s_waitcnt lgkmcnt(4)
	v_mov_b32_e32 v30, v107
	v_pk_fma_f32 v[8:9], v[30:31], v[22:23], v[8:9] op_sel_hi:[0,1,1]
	v_pk_fma_f32 v[10:11], v[30:31], v[24:25], v[10:11] op_sel_hi:[0,1,1]
	v_pk_fma_f32 v[12:13], v[30:31], v[26:27], v[12:13] op_sel_hi:[0,1,1]
	v_pk_fma_f32 v[6:7], v[30:31], v[28:29], v[6:7] op_sel_hi:[0,1,1]
	ds_read_b128 v[14:17], v3 offset:2432
	ds_read_b128 v[18:21], v3 offset:2448
	s_waitcnt lgkmcnt(4)
	v_pk_fma_f32 v[8:9], v[108:109], v[174:175], v[8:9] op_sel_hi:[0,1,1]
	v_pk_fma_f32 v[10:11], v[108:109], v[176:177], v[10:11] op_sel_hi:[0,1,1]
	v_pk_fma_f32 v[12:13], v[108:109], v[178:179], v[12:13] op_sel_hi:[0,1,1]
	v_pk_fma_f32 v[6:7], v[108:109], v[180:181], v[6:7] op_sel_hi:[0,1,1]
	ds_read_b128 v[22:25], v3 offset:2464
	ds_read_b128 v[26:29], v3 offset:2480
	s_waitcnt lgkmcnt(4)
	v_mov_b32_e32 v32, v109
	v_pk_fma_f32 v[8:9], v[32:33], v[182:183], v[8:9] op_sel_hi:[0,1,1]
	v_pk_fma_f32 v[10:11], v[32:33], v[184:185], v[10:11] op_sel_hi:[0,1,1]
	v_pk_fma_f32 v[12:13], v[32:33], v[186:187], v[12:13] op_sel_hi:[0,1,1]
	v_pk_fma_f32 v[6:7], v[32:33], v[188:189], v[6:7] op_sel_hi:[0,1,1]
	ds_read_b128 v[174:177], v3 offset:2496
	ds_read_b128 v[178:181], v3 offset:2512
	s_waitcnt lgkmcnt(4)
	v_pk_fma_f32 v[8:9], v[110:111], v[14:15], v[8:9] op_sel_hi:[0,1,1]
	v_pk_fma_f32 v[10:11], v[110:111], v[16:17], v[10:11] op_sel_hi:[0,1,1]
	v_pk_fma_f32 v[12:13], v[110:111], v[18:19], v[12:13] op_sel_hi:[0,1,1]
	v_pk_fma_f32 v[6:7], v[110:111], v[20:21], v[6:7] op_sel_hi:[0,1,1]
	ds_read_b128 v[182:185], v3 offset:2528
	ds_read_b128 v[186:189], v3 offset:2544
	s_waitcnt lgkmcnt(4)
	v_mov_b32_e32 v30, v111
	v_pk_fma_f32 v[8:9], v[30:31], v[22:23], v[8:9] op_sel_hi:[0,1,1]
	v_pk_fma_f32 v[10:11], v[30:31], v[24:25], v[10:11] op_sel_hi:[0,1,1]
	v_pk_fma_f32 v[12:13], v[30:31], v[26:27], v[12:13] op_sel_hi:[0,1,1]
	v_pk_fma_f32 v[6:7], v[30:31], v[28:29], v[6:7] op_sel_hi:[0,1,1]
	ds_read_b128 v[14:17], v3 offset:2560
	ds_read_b128 v[18:21], v3 offset:2576
	s_waitcnt lgkmcnt(4)
	v_pk_fma_f32 v[8:9], v[112:113], v[174:175], v[8:9] op_sel_hi:[0,1,1]
	v_pk_fma_f32 v[10:11], v[112:113], v[176:177], v[10:11] op_sel_hi:[0,1,1]
	v_pk_fma_f32 v[12:13], v[112:113], v[178:179], v[12:13] op_sel_hi:[0,1,1]
	v_pk_fma_f32 v[6:7], v[112:113], v[180:181], v[6:7] op_sel_hi:[0,1,1]
	ds_read_b128 v[22:25], v3 offset:2592
	ds_read_b128 v[26:29], v3 offset:2608
	s_waitcnt lgkmcnt(4)
	v_mov_b32_e32 v32, v113
	v_pk_fma_f32 v[8:9], v[32:33], v[182:183], v[8:9] op_sel_hi:[0,1,1]
	v_pk_fma_f32 v[10:11], v[32:33], v[184:185], v[10:11] op_sel_hi:[0,1,1]
	v_pk_fma_f32 v[12:13], v[32:33], v[186:187], v[12:13] op_sel_hi:[0,1,1]
	v_pk_fma_f32 v[6:7], v[32:33], v[188:189], v[6:7] op_sel_hi:[0,1,1]
	ds_read_b128 v[174:177], v3 offset:2624
	ds_read_b128 v[178:181], v3 offset:2640
	s_waitcnt lgkmcnt(4)
	v_pk_fma_f32 v[8:9], v[114:115], v[14:15], v[8:9] op_sel_hi:[0,1,1]
	v_pk_fma_f32 v[10:11], v[114:115], v[16:17], v[10:11] op_sel_hi:[0,1,1]
	v_pk_fma_f32 v[12:13], v[114:115], v[18:19], v[12:13] op_sel_hi:[0,1,1]
	v_pk_fma_f32 v[6:7], v[114:115], v[20:21], v[6:7] op_sel_hi:[0,1,1]
	ds_read_b128 v[182:185], v3 offset:2656
	ds_read_b128 v[186:189], v3 offset:2672
	s_waitcnt lgkmcnt(4)
	v_mov_b32_e32 v30, v115
	v_pk_fma_f32 v[8:9], v[30:31], v[22:23], v[8:9] op_sel_hi:[0,1,1]
	v_pk_fma_f32 v[10:11], v[30:31], v[24:25], v[10:11] op_sel_hi:[0,1,1]
	v_pk_fma_f32 v[12:13], v[30:31], v[26:27], v[12:13] op_sel_hi:[0,1,1]
	v_pk_fma_f32 v[6:7], v[30:31], v[28:29], v[6:7] op_sel_hi:[0,1,1]
	ds_read_b128 v[14:17], v3 offset:2688
	ds_read_b128 v[18:21], v3 offset:2704
	s_waitcnt lgkmcnt(4)
	v_pk_fma_f32 v[8:9], v[116:117], v[174:175], v[8:9] op_sel_hi:[0,1,1]
	v_pk_fma_f32 v[10:11], v[116:117], v[176:177], v[10:11] op_sel_hi:[0,1,1]
	v_pk_fma_f32 v[12:13], v[116:117], v[178:179], v[12:13] op_sel_hi:[0,1,1]
	v_pk_fma_f32 v[6:7], v[116:117], v[180:181], v[6:7] op_sel_hi:[0,1,1]
	ds_read_b128 v[22:25], v3 offset:2720
	ds_read_b128 v[26:29], v3 offset:2736
	s_waitcnt lgkmcnt(4)
	v_mov_b32_e32 v32, v117
	v_pk_fma_f32 v[8:9], v[32:33], v[182:183], v[8:9] op_sel_hi:[0,1,1]
	v_pk_fma_f32 v[10:11], v[32:33], v[184:185], v[10:11] op_sel_hi:[0,1,1]
	v_pk_fma_f32 v[12:13], v[32:33], v[186:187], v[12:13] op_sel_hi:[0,1,1]
	v_pk_fma_f32 v[6:7], v[32:33], v[188:189], v[6:7] op_sel_hi:[0,1,1]
	ds_read_b128 v[174:177], v3 offset:2752
	ds_read_b128 v[178:181], v3 offset:2768
	s_waitcnt lgkmcnt(4)
	v_pk_fma_f32 v[8:9], v[118:119], v[14:15], v[8:9] op_sel_hi:[0,1,1]
	v_pk_fma_f32 v[10:11], v[118:119], v[16:17], v[10:11] op_sel_hi:[0,1,1]
	v_pk_fma_f32 v[12:13], v[118:119], v[18:19], v[12:13] op_sel_hi:[0,1,1]
	v_pk_fma_f32 v[6:7], v[118:119], v[20:21], v[6:7] op_sel_hi:[0,1,1]
	ds_read_b128 v[182:185], v3 offset:2784
	ds_read_b128 v[186:189], v3 offset:2800
	s_waitcnt lgkmcnt(4)
	v_mov_b32_e32 v30, v119
	v_pk_fma_f32 v[8:9], v[30:31], v[22:23], v[8:9] op_sel_hi:[0,1,1]
	v_pk_fma_f32 v[10:11], v[30:31], v[24:25], v[10:11] op_sel_hi:[0,1,1]
	v_pk_fma_f32 v[12:13], v[30:31], v[26:27], v[12:13] op_sel_hi:[0,1,1]
	v_pk_fma_f32 v[6:7], v[30:31], v[28:29], v[6:7] op_sel_hi:[0,1,1]
	ds_read_b128 v[14:17], v3 offset:2816
	ds_read_b128 v[18:21], v3 offset:2832
	s_waitcnt lgkmcnt(4)
	v_pk_fma_f32 v[8:9], v[120:121], v[174:175], v[8:9] op_sel_hi:[0,1,1]
	v_pk_fma_f32 v[10:11], v[120:121], v[176:177], v[10:11] op_sel_hi:[0,1,1]
	v_pk_fma_f32 v[12:13], v[120:121], v[178:179], v[12:13] op_sel_hi:[0,1,1]
	v_pk_fma_f32 v[6:7], v[120:121], v[180:181], v[6:7] op_sel_hi:[0,1,1]
	ds_read_b128 v[22:25], v3 offset:2848
	ds_read_b128 v[26:29], v3 offset:2864
	s_waitcnt lgkmcnt(4)
	v_mov_b32_e32 v32, v121
	v_pk_fma_f32 v[8:9], v[32:33], v[182:183], v[8:9] op_sel_hi:[0,1,1]
	v_pk_fma_f32 v[10:11], v[32:33], v[184:185], v[10:11] op_sel_hi:[0,1,1]
	v_pk_fma_f32 v[12:13], v[32:33], v[186:187], v[12:13] op_sel_hi:[0,1,1]
	v_pk_fma_f32 v[6:7], v[32:33], v[188:189], v[6:7] op_sel_hi:[0,1,1]
	ds_read_b128 v[174:177], v3 offset:2880
	ds_read_b128 v[178:181], v3 offset:2896
	s_waitcnt lgkmcnt(4)
	v_pk_fma_f32 v[8:9], v[122:123], v[14:15], v[8:9] op_sel_hi:[0,1,1]
	v_pk_fma_f32 v[10:11], v[122:123], v[16:17], v[10:11] op_sel_hi:[0,1,1]
	v_pk_fma_f32 v[12:13], v[122:123], v[18:19], v[12:13] op_sel_hi:[0,1,1]
	v_pk_fma_f32 v[6:7], v[122:123], v[20:21], v[6:7] op_sel_hi:[0,1,1]
	ds_read_b128 v[182:185], v3 offset:2912
	ds_read_b128 v[186:189], v3 offset:2928
	s_waitcnt lgkmcnt(4)
	v_mov_b32_e32 v30, v123
	v_pk_fma_f32 v[8:9], v[30:31], v[22:23], v[8:9] op_sel_hi:[0,1,1]
	v_pk_fma_f32 v[10:11], v[30:31], v[24:25], v[10:11] op_sel_hi:[0,1,1]
	v_pk_fma_f32 v[12:13], v[30:31], v[26:27], v[12:13] op_sel_hi:[0,1,1]
	v_pk_fma_f32 v[6:7], v[30:31], v[28:29], v[6:7] op_sel_hi:[0,1,1]
	ds_read_b128 v[14:17], v3 offset:2944
	ds_read_b128 v[18:21], v3 offset:2960
	s_waitcnt lgkmcnt(4)
	v_pk_fma_f32 v[8:9], v[124:125], v[174:175], v[8:9] op_sel_hi:[0,1,1]
	v_pk_fma_f32 v[10:11], v[124:125], v[176:177], v[10:11] op_sel_hi:[0,1,1]
	v_pk_fma_f32 v[12:13], v[124:125], v[178:179], v[12:13] op_sel_hi:[0,1,1]
	v_pk_fma_f32 v[6:7], v[124:125], v[180:181], v[6:7] op_sel_hi:[0,1,1]
	ds_read_b128 v[22:25], v3 offset:2976
	ds_read_b128 v[26:29], v3 offset:2992
	s_waitcnt lgkmcnt(4)
	v_mov_b32_e32 v32, v125
	v_pk_fma_f32 v[8:9], v[32:33], v[182:183], v[8:9] op_sel_hi:[0,1,1]
	v_pk_fma_f32 v[10:11], v[32:33], v[184:185], v[10:11] op_sel_hi:[0,1,1]
	v_pk_fma_f32 v[12:13], v[32:33], v[186:187], v[12:13] op_sel_hi:[0,1,1]
	v_pk_fma_f32 v[6:7], v[32:33], v[188:189], v[6:7] op_sel_hi:[0,1,1]
	ds_read_b128 v[174:177], v3 offset:3008
	ds_read_b128 v[178:181], v3 offset:3024
	s_waitcnt lgkmcnt(4)
	v_pk_fma_f32 v[8:9], v[126:127], v[14:15], v[8:9] op_sel_hi:[0,1,1]
	v_pk_fma_f32 v[10:11], v[126:127], v[16:17], v[10:11] op_sel_hi:[0,1,1]
	v_pk_fma_f32 v[12:13], v[126:127], v[18:19], v[12:13] op_sel_hi:[0,1,1]
	v_pk_fma_f32 v[6:7], v[126:127], v[20:21], v[6:7] op_sel_hi:[0,1,1]
	ds_read_b128 v[182:185], v3 offset:3040
	ds_read_b128 v[186:189], v3 offset:3056
	s_waitcnt lgkmcnt(4)
	v_mov_b32_e32 v30, v127
	v_pk_fma_f32 v[8:9], v[30:31], v[22:23], v[8:9] op_sel_hi:[0,1,1]
	v_pk_fma_f32 v[10:11], v[30:31], v[24:25], v[10:11] op_sel_hi:[0,1,1]
	v_pk_fma_f32 v[12:13], v[30:31], v[26:27], v[12:13] op_sel_hi:[0,1,1]
	v_pk_fma_f32 v[6:7], v[30:31], v[28:29], v[6:7] op_sel_hi:[0,1,1]
	ds_read_b128 v[14:17], v3 offset:3072
	ds_read_b128 v[18:21], v3 offset:3088
	s_waitcnt lgkmcnt(4)
	v_pk_fma_f32 v[8:9], v[128:129], v[174:175], v[8:9] op_sel_hi:[0,1,1]
	v_pk_fma_f32 v[10:11], v[128:129], v[176:177], v[10:11] op_sel_hi:[0,1,1]
	v_pk_fma_f32 v[12:13], v[128:129], v[178:179], v[12:13] op_sel_hi:[0,1,1]
	v_pk_fma_f32 v[6:7], v[128:129], v[180:181], v[6:7] op_sel_hi:[0,1,1]
	ds_read_b128 v[22:25], v3 offset:3104
	ds_read_b128 v[26:29], v3 offset:3120
	s_waitcnt lgkmcnt(4)
	v_mov_b32_e32 v32, v129
	v_pk_fma_f32 v[8:9], v[32:33], v[182:183], v[8:9] op_sel_hi:[0,1,1]
	v_pk_fma_f32 v[10:11], v[32:33], v[184:185], v[10:11] op_sel_hi:[0,1,1]
	v_pk_fma_f32 v[12:13], v[32:33], v[186:187], v[12:13] op_sel_hi:[0,1,1]
	v_pk_fma_f32 v[6:7], v[32:33], v[188:189], v[6:7] op_sel_hi:[0,1,1]
	ds_read_b128 v[174:177], v3 offset:3136
	ds_read_b128 v[178:181], v3 offset:3152
	s_waitcnt lgkmcnt(4)
	v_pk_fma_f32 v[8:9], v[130:131], v[14:15], v[8:9] op_sel_hi:[0,1,1]
	v_pk_fma_f32 v[10:11], v[130:131], v[16:17], v[10:11] op_sel_hi:[0,1,1]
	v_pk_fma_f32 v[12:13], v[130:131], v[18:19], v[12:13] op_sel_hi:[0,1,1]
	v_pk_fma_f32 v[6:7], v[130:131], v[20:21], v[6:7] op_sel_hi:[0,1,1]
	ds_read_b128 v[182:185], v3 offset:3168
	ds_read_b128 v[186:189], v3 offset:3184
	s_waitcnt lgkmcnt(4)
	v_mov_b32_e32 v30, v131
	v_pk_fma_f32 v[8:9], v[30:31], v[22:23], v[8:9] op_sel_hi:[0,1,1]
	v_pk_fma_f32 v[10:11], v[30:31], v[24:25], v[10:11] op_sel_hi:[0,1,1]
	v_pk_fma_f32 v[12:13], v[30:31], v[26:27], v[12:13] op_sel_hi:[0,1,1]
	v_pk_fma_f32 v[6:7], v[30:31], v[28:29], v[6:7] op_sel_hi:[0,1,1]
	ds_read_b128 v[14:17], v3 offset:3200
	ds_read_b128 v[18:21], v3 offset:3216
	s_waitcnt lgkmcnt(4)
	v_pk_fma_f32 v[8:9], v[132:133], v[174:175], v[8:9] op_sel_hi:[0,1,1]
	v_pk_fma_f32 v[10:11], v[132:133], v[176:177], v[10:11] op_sel_hi:[0,1,1]
	v_pk_fma_f32 v[12:13], v[132:133], v[178:179], v[12:13] op_sel_hi:[0,1,1]
	v_pk_fma_f32 v[6:7], v[132:133], v[180:181], v[6:7] op_sel_hi:[0,1,1]
	ds_read_b128 v[22:25], v3 offset:3232
	ds_read_b128 v[26:29], v3 offset:3248
	s_waitcnt lgkmcnt(4)
	v_mov_b32_e32 v32, v133
	v_pk_fma_f32 v[8:9], v[32:33], v[182:183], v[8:9] op_sel_hi:[0,1,1]
	v_pk_fma_f32 v[10:11], v[32:33], v[184:185], v[10:11] op_sel_hi:[0,1,1]
	v_pk_fma_f32 v[12:13], v[32:33], v[186:187], v[12:13] op_sel_hi:[0,1,1]
	v_pk_fma_f32 v[6:7], v[32:33], v[188:189], v[6:7] op_sel_hi:[0,1,1]
	ds_read_b128 v[174:177], v3 offset:3264
	ds_read_b128 v[178:181], v3 offset:3280
	s_waitcnt lgkmcnt(4)
	v_pk_fma_f32 v[8:9], v[134:135], v[14:15], v[8:9] op_sel_hi:[0,1,1]
	v_pk_fma_f32 v[10:11], v[134:135], v[16:17], v[10:11] op_sel_hi:[0,1,1]
	v_pk_fma_f32 v[12:13], v[134:135], v[18:19], v[12:13] op_sel_hi:[0,1,1]
	v_pk_fma_f32 v[6:7], v[134:135], v[20:21], v[6:7] op_sel_hi:[0,1,1]
	ds_read_b128 v[182:185], v3 offset:3296
	ds_read_b128 v[186:189], v3 offset:3312
	s_waitcnt lgkmcnt(4)
	v_mov_b32_e32 v30, v135
	v_pk_fma_f32 v[8:9], v[30:31], v[22:23], v[8:9] op_sel_hi:[0,1,1]
	v_pk_fma_f32 v[10:11], v[30:31], v[24:25], v[10:11] op_sel_hi:[0,1,1]
	v_pk_fma_f32 v[12:13], v[30:31], v[26:27], v[12:13] op_sel_hi:[0,1,1]
	v_pk_fma_f32 v[6:7], v[30:31], v[28:29], v[6:7] op_sel_hi:[0,1,1]
	ds_read_b128 v[14:17], v3 offset:3328
	ds_read_b128 v[18:21], v3 offset:3344
	s_waitcnt lgkmcnt(4)
	v_pk_fma_f32 v[8:9], v[136:137], v[174:175], v[8:9] op_sel_hi:[0,1,1]
	v_pk_fma_f32 v[10:11], v[136:137], v[176:177], v[10:11] op_sel_hi:[0,1,1]
	v_pk_fma_f32 v[12:13], v[136:137], v[178:179], v[12:13] op_sel_hi:[0,1,1]
	v_pk_fma_f32 v[6:7], v[136:137], v[180:181], v[6:7] op_sel_hi:[0,1,1]
	ds_read_b128 v[22:25], v3 offset:3360
	ds_read_b128 v[26:29], v3 offset:3376
	s_waitcnt lgkmcnt(4)
	v_mov_b32_e32 v32, v137
	v_pk_fma_f32 v[8:9], v[32:33], v[182:183], v[8:9] op_sel_hi:[0,1,1]
	v_pk_fma_f32 v[10:11], v[32:33], v[184:185], v[10:11] op_sel_hi:[0,1,1]
	v_pk_fma_f32 v[12:13], v[32:33], v[186:187], v[12:13] op_sel_hi:[0,1,1]
	v_pk_fma_f32 v[6:7], v[32:33], v[188:189], v[6:7] op_sel_hi:[0,1,1]
	ds_read_b128 v[174:177], v3 offset:3392
	ds_read_b128 v[178:181], v3 offset:3408
	s_waitcnt lgkmcnt(4)
	v_pk_fma_f32 v[8:9], v[138:139], v[14:15], v[8:9] op_sel_hi:[0,1,1]
	v_pk_fma_f32 v[10:11], v[138:139], v[16:17], v[10:11] op_sel_hi:[0,1,1]
	v_pk_fma_f32 v[12:13], v[138:139], v[18:19], v[12:13] op_sel_hi:[0,1,1]
	v_pk_fma_f32 v[6:7], v[138:139], v[20:21], v[6:7] op_sel_hi:[0,1,1]
	ds_read_b128 v[182:185], v3 offset:3424
	ds_read_b128 v[186:189], v3 offset:3440
	s_waitcnt lgkmcnt(4)
	v_mov_b32_e32 v30, v139
	v_pk_fma_f32 v[8:9], v[30:31], v[22:23], v[8:9] op_sel_hi:[0,1,1]
	v_pk_fma_f32 v[10:11], v[30:31], v[24:25], v[10:11] op_sel_hi:[0,1,1]
	v_pk_fma_f32 v[12:13], v[30:31], v[26:27], v[12:13] op_sel_hi:[0,1,1]
	v_pk_fma_f32 v[6:7], v[30:31], v[28:29], v[6:7] op_sel_hi:[0,1,1]
	ds_read_b128 v[14:17], v3 offset:3456
	ds_read_b128 v[18:21], v3 offset:3472
	s_waitcnt lgkmcnt(4)
	v_pk_fma_f32 v[8:9], v[140:141], v[174:175], v[8:9] op_sel_hi:[0,1,1]
	v_pk_fma_f32 v[10:11], v[140:141], v[176:177], v[10:11] op_sel_hi:[0,1,1]
	v_pk_fma_f32 v[12:13], v[140:141], v[178:179], v[12:13] op_sel_hi:[0,1,1]
	v_pk_fma_f32 v[6:7], v[140:141], v[180:181], v[6:7] op_sel_hi:[0,1,1]
	ds_read_b128 v[22:25], v3 offset:3488
	ds_read_b128 v[26:29], v3 offset:3504
	s_waitcnt lgkmcnt(4)
	v_mov_b32_e32 v32, v141
	v_pk_fma_f32 v[8:9], v[32:33], v[182:183], v[8:9] op_sel_hi:[0,1,1]
	v_pk_fma_f32 v[10:11], v[32:33], v[184:185], v[10:11] op_sel_hi:[0,1,1]
	v_pk_fma_f32 v[12:13], v[32:33], v[186:187], v[12:13] op_sel_hi:[0,1,1]
	v_pk_fma_f32 v[6:7], v[32:33], v[188:189], v[6:7] op_sel_hi:[0,1,1]
	ds_read_b128 v[174:177], v3 offset:3520
	ds_read_b128 v[178:181], v3 offset:3536
	s_waitcnt lgkmcnt(4)
	v_pk_fma_f32 v[8:9], v[142:143], v[14:15], v[8:9] op_sel_hi:[0,1,1]
	v_pk_fma_f32 v[10:11], v[142:143], v[16:17], v[10:11] op_sel_hi:[0,1,1]
	v_pk_fma_f32 v[12:13], v[142:143], v[18:19], v[12:13] op_sel_hi:[0,1,1]
	v_pk_fma_f32 v[6:7], v[142:143], v[20:21], v[6:7] op_sel_hi:[0,1,1]
	ds_read_b128 v[182:185], v3 offset:3552
	ds_read_b128 v[186:189], v3 offset:3568
	s_waitcnt lgkmcnt(4)
	v_mov_b32_e32 v30, v143
	v_pk_fma_f32 v[8:9], v[30:31], v[22:23], v[8:9] op_sel_hi:[0,1,1]
	v_pk_fma_f32 v[10:11], v[30:31], v[24:25], v[10:11] op_sel_hi:[0,1,1]
	v_pk_fma_f32 v[12:13], v[30:31], v[26:27], v[12:13] op_sel_hi:[0,1,1]
	v_pk_fma_f32 v[6:7], v[30:31], v[28:29], v[6:7] op_sel_hi:[0,1,1]
	ds_read_b128 v[14:17], v3 offset:3584
	ds_read_b128 v[18:21], v3 offset:3600
	s_waitcnt lgkmcnt(4)
	v_pk_fma_f32 v[8:9], v[144:145], v[174:175], v[8:9] op_sel_hi:[0,1,1]
	v_pk_fma_f32 v[10:11], v[144:145], v[176:177], v[10:11] op_sel_hi:[0,1,1]
	v_pk_fma_f32 v[12:13], v[144:145], v[178:179], v[12:13] op_sel_hi:[0,1,1]
	v_pk_fma_f32 v[6:7], v[144:145], v[180:181], v[6:7] op_sel_hi:[0,1,1]
	ds_read_b128 v[22:25], v3 offset:3616
	ds_read_b128 v[26:29], v3 offset:3632
	s_waitcnt lgkmcnt(4)
	v_mov_b32_e32 v32, v145
	v_pk_fma_f32 v[8:9], v[32:33], v[182:183], v[8:9] op_sel_hi:[0,1,1]
	v_pk_fma_f32 v[10:11], v[32:33], v[184:185], v[10:11] op_sel_hi:[0,1,1]
	v_pk_fma_f32 v[12:13], v[32:33], v[186:187], v[12:13] op_sel_hi:[0,1,1]
	v_pk_fma_f32 v[6:7], v[32:33], v[188:189], v[6:7] op_sel_hi:[0,1,1]
	ds_read_b128 v[174:177], v3 offset:3648
	ds_read_b128 v[178:181], v3 offset:3664
	s_waitcnt lgkmcnt(4)
	v_pk_fma_f32 v[8:9], v[146:147], v[14:15], v[8:9] op_sel_hi:[0,1,1]
	v_pk_fma_f32 v[10:11], v[146:147], v[16:17], v[10:11] op_sel_hi:[0,1,1]
	v_pk_fma_f32 v[12:13], v[146:147], v[18:19], v[12:13] op_sel_hi:[0,1,1]
	v_pk_fma_f32 v[6:7], v[146:147], v[20:21], v[6:7] op_sel_hi:[0,1,1]
	ds_read_b128 v[182:185], v3 offset:3680
	ds_read_b128 v[186:189], v3 offset:3696
	s_waitcnt lgkmcnt(4)
	v_mov_b32_e32 v30, v147
	v_pk_fma_f32 v[8:9], v[30:31], v[22:23], v[8:9] op_sel_hi:[0,1,1]
	v_pk_fma_f32 v[10:11], v[30:31], v[24:25], v[10:11] op_sel_hi:[0,1,1]
	v_pk_fma_f32 v[12:13], v[30:31], v[26:27], v[12:13] op_sel_hi:[0,1,1]
	v_pk_fma_f32 v[6:7], v[30:31], v[28:29], v[6:7] op_sel_hi:[0,1,1]
	ds_read_b128 v[14:17], v3 offset:3712
	ds_read_b128 v[18:21], v3 offset:3728
	s_waitcnt lgkmcnt(4)
	v_pk_fma_f32 v[8:9], v[148:149], v[174:175], v[8:9] op_sel_hi:[0,1,1]
	v_pk_fma_f32 v[10:11], v[148:149], v[176:177], v[10:11] op_sel_hi:[0,1,1]
	v_pk_fma_f32 v[12:13], v[148:149], v[178:179], v[12:13] op_sel_hi:[0,1,1]
	v_pk_fma_f32 v[6:7], v[148:149], v[180:181], v[6:7] op_sel_hi:[0,1,1]
	ds_read_b128 v[22:25], v3 offset:3744
	ds_read_b128 v[26:29], v3 offset:3760
	s_waitcnt lgkmcnt(4)
	v_mov_b32_e32 v32, v149
	v_pk_fma_f32 v[8:9], v[32:33], v[182:183], v[8:9] op_sel_hi:[0,1,1]
	v_pk_fma_f32 v[10:11], v[32:33], v[184:185], v[10:11] op_sel_hi:[0,1,1]
	v_pk_fma_f32 v[12:13], v[32:33], v[186:187], v[12:13] op_sel_hi:[0,1,1]
	v_pk_fma_f32 v[6:7], v[32:33], v[188:189], v[6:7] op_sel_hi:[0,1,1]
	ds_read_b128 v[174:177], v3 offset:3776
	ds_read_b128 v[178:181], v3 offset:3792
	s_waitcnt lgkmcnt(4)
	v_pk_fma_f32 v[8:9], v[150:151], v[14:15], v[8:9] op_sel_hi:[0,1,1]
	v_pk_fma_f32 v[10:11], v[150:151], v[16:17], v[10:11] op_sel_hi:[0,1,1]
	v_pk_fma_f32 v[12:13], v[150:151], v[18:19], v[12:13] op_sel_hi:[0,1,1]
	v_pk_fma_f32 v[6:7], v[150:151], v[20:21], v[6:7] op_sel_hi:[0,1,1]
	ds_read_b128 v[182:185], v3 offset:3808
	ds_read_b128 v[186:189], v3 offset:3824
	s_waitcnt lgkmcnt(4)
	v_mov_b32_e32 v30, v151
	v_pk_fma_f32 v[8:9], v[30:31], v[22:23], v[8:9] op_sel_hi:[0,1,1]
	v_pk_fma_f32 v[10:11], v[30:31], v[24:25], v[10:11] op_sel_hi:[0,1,1]
	v_pk_fma_f32 v[12:13], v[30:31], v[26:27], v[12:13] op_sel_hi:[0,1,1]
	v_pk_fma_f32 v[6:7], v[30:31], v[28:29], v[6:7] op_sel_hi:[0,1,1]
	ds_read_b128 v[14:17], v3 offset:3840
	ds_read_b128 v[18:21], v3 offset:3856
	s_waitcnt lgkmcnt(4)
	v_pk_fma_f32 v[8:9], v[152:153], v[174:175], v[8:9] op_sel_hi:[0,1,1]
	v_pk_fma_f32 v[10:11], v[152:153], v[176:177], v[10:11] op_sel_hi:[0,1,1]
	v_pk_fma_f32 v[12:13], v[152:153], v[178:179], v[12:13] op_sel_hi:[0,1,1]
	v_pk_fma_f32 v[6:7], v[152:153], v[180:181], v[6:7] op_sel_hi:[0,1,1]
	ds_read_b128 v[22:25], v3 offset:3872
	ds_read_b128 v[26:29], v3 offset:3888
	s_waitcnt lgkmcnt(4)
	v_mov_b32_e32 v32, v153
	v_pk_fma_f32 v[8:9], v[32:33], v[182:183], v[8:9] op_sel_hi:[0,1,1]
	v_pk_fma_f32 v[10:11], v[32:33], v[184:185], v[10:11] op_sel_hi:[0,1,1]
	v_pk_fma_f32 v[12:13], v[32:33], v[186:187], v[12:13] op_sel_hi:[0,1,1]
	v_pk_fma_f32 v[6:7], v[32:33], v[188:189], v[6:7] op_sel_hi:[0,1,1]
	ds_read_b128 v[174:177], v3 offset:3904
	ds_read_b128 v[178:181], v3 offset:3920
	s_waitcnt lgkmcnt(4)
	v_pk_fma_f32 v[8:9], v[154:155], v[14:15], v[8:9] op_sel_hi:[0,1,1]
	v_pk_fma_f32 v[10:11], v[154:155], v[16:17], v[10:11] op_sel_hi:[0,1,1]
	v_pk_fma_f32 v[12:13], v[154:155], v[18:19], v[12:13] op_sel_hi:[0,1,1]
	v_pk_fma_f32 v[6:7], v[154:155], v[20:21], v[6:7] op_sel_hi:[0,1,1]
	ds_read_b128 v[182:185], v3 offset:3936
	ds_read_b128 v[186:189], v3 offset:3952
	s_waitcnt lgkmcnt(4)
	v_mov_b32_e32 v30, v155
	v_pk_fma_f32 v[8:9], v[30:31], v[22:23], v[8:9] op_sel_hi:[0,1,1]
	v_pk_fma_f32 v[10:11], v[30:31], v[24:25], v[10:11] op_sel_hi:[0,1,1]
	v_pk_fma_f32 v[12:13], v[30:31], v[26:27], v[12:13] op_sel_hi:[0,1,1]
	v_pk_fma_f32 v[6:7], v[30:31], v[28:29], v[6:7] op_sel_hi:[0,1,1]
	ds_read_b128 v[14:17], v3 offset:3968
	ds_read_b128 v[18:21], v3 offset:3984
	s_waitcnt lgkmcnt(4)
	v_pk_fma_f32 v[8:9], v[156:157], v[174:175], v[8:9] op_sel_hi:[0,1,1]
	v_pk_fma_f32 v[10:11], v[156:157], v[176:177], v[10:11] op_sel_hi:[0,1,1]
	v_pk_fma_f32 v[12:13], v[156:157], v[178:179], v[12:13] op_sel_hi:[0,1,1]
	v_pk_fma_f32 v[6:7], v[156:157], v[180:181], v[6:7] op_sel_hi:[0,1,1]
	ds_read_b128 v[22:25], v3 offset:4000
	ds_read_b128 v[26:29], v3 offset:4016
	s_waitcnt lgkmcnt(4)
	v_mov_b32_e32 v32, v157
	v_pk_fma_f32 v[8:9], v[32:33], v[182:183], v[8:9] op_sel_hi:[0,1,1]
	v_pk_fma_f32 v[10:11], v[32:33], v[184:185], v[10:11] op_sel_hi:[0,1,1]
	v_pk_fma_f32 v[12:13], v[32:33], v[186:187], v[12:13] op_sel_hi:[0,1,1]
	v_pk_fma_f32 v[6:7], v[32:33], v[188:189], v[6:7] op_sel_hi:[0,1,1]
	ds_read_b128 v[174:177], v3 offset:4032
	ds_read_b128 v[178:181], v3 offset:4048
	s_waitcnt lgkmcnt(4)
	v_pk_fma_f32 v[8:9], v[158:159], v[14:15], v[8:9] op_sel_hi:[0,1,1]
	v_pk_fma_f32 v[10:11], v[158:159], v[16:17], v[10:11] op_sel_hi:[0,1,1]
	v_pk_fma_f32 v[12:13], v[158:159], v[18:19], v[12:13] op_sel_hi:[0,1,1]
	v_pk_fma_f32 v[6:7], v[158:159], v[20:21], v[6:7] op_sel_hi:[0,1,1]
	ds_read_b128 v[182:185], v3 offset:4064
	ds_read_b128 v[186:189], v3 offset:4080
	s_waitcnt lgkmcnt(4)
	v_mov_b32_e32 v30, v159
	v_pk_fma_f32 v[8:9], v[30:31], v[22:23], v[8:9] op_sel_hi:[0,1,1]
	v_pk_fma_f32 v[10:11], v[30:31], v[24:25], v[10:11] op_sel_hi:[0,1,1]
	v_pk_fma_f32 v[12:13], v[30:31], v[26:27], v[12:13] op_sel_hi:[0,1,1]
	v_pk_fma_f32 v[6:7], v[30:31], v[28:29], v[6:7] op_sel_hi:[0,1,1]
	s_waitcnt lgkmcnt(2)
	v_pk_fma_f32 v[8:9], v[160:161], v[174:175], v[8:9] op_sel_hi:[0,1,1]
	v_pk_fma_f32 v[10:11], v[160:161], v[176:177], v[10:11] op_sel_hi:[0,1,1]
	v_pk_fma_f32 v[12:13], v[160:161], v[178:179], v[12:13] op_sel_hi:[0,1,1]
	v_pk_fma_f32 v[6:7], v[160:161], v[180:181], v[6:7] op_sel_hi:[0,1,1]
	s_waitcnt lgkmcnt(0)
	v_mov_b32_e32 v32, v161
	v_pk_fma_f32 v[8:9], v[32:33], v[182:183], v[8:9] op_sel_hi:[0,1,1]
	v_pk_fma_f32 v[10:11], v[32:33], v[184:185], v[10:11] op_sel_hi:[0,1,1]
	v_pk_fma_f32 v[12:13], v[32:33], v[186:187], v[12:13] op_sel_hi:[0,1,1]
	v_pk_fma_f32 v[6:7], v[32:33], v[188:189], v[6:7] op_sel_hi:[0,1,1]
	v_mov_b64_e32 v[4:5], s[90:91]
	v_mad_i64_i32 v[2:3], s[12:13], v2, s22, v[4:5]
	v_lshl_add_u64 v[2:3], s[2:3], 1, v[2:3]
	s_lshl_b32 s48, s48, 4
	v_cvt_pk_bf16_f32 v8, v8, v9
	v_cvt_pk_bf16_f32 v9, v10, v11
	v_cvt_pk_bf16_f32 v10, v12, v13
	v_cvt_pk_bf16_f32 v11, v6, v7
	v_lshl_add_u64 v[2:3], v[2:3], 0, s[48:49]
	global_store_dwordx4 v[2:3], v[8:11], off offset:2048
	s_barrier
	s_branch .LBB0_571
